# dsa_sparse: gathered-logit fast path (2 iterations of K-row gathers in flight) + P.V gathers issued before the softmax section
# speedup vs baseline: 1.0385x; 1.0022x over previous
.LBB0_1522:
	s_or_b64 exec, exec, s[0:1]
	s_add_i32 s80, s80, s65
	s_add_i32 s20, s78, -1
	v_lshl_add_u64 v[52:53], v[16:17], 1, s[44:45]
	v_cmp_gt_u32_e64 s[6:7], 16, v86
	v_lshl_add_u32 v87, v56, 4, s73
	v_mov_b32_e32 v88, v56
	s_cmpk_eq_i32 s78, 0x100
	s_cbranch_scc1 .Lqk_fast
	s_branch .LBB0_1524

.Lqk_fast:
	v_lshlrev_b32_e32 v24, 4, v55
	v_lshl_add_u32 v25, v56, 2, s66
	ds_read_b32 v16, v25 offset:6400
	ds_read_b32 v17, v25 offset:6464
	ds_read_b32 v18, v25 offset:6528
	ds_read_b32 v19, v25 offset:6592
	s_waitcnt lgkmcnt(3)
	v_add_u32_e32 v26, s42, v16
	v_lshl_add_u32 v26, v26, 9, v24
	global_load_dwordx4 v[130:133], v26, s[44:45]
	global_load_dwordx4 v[134:137], v26, s[44:45] offset:64
	global_load_dwordx4 v[138:141], v26, s[44:45] offset:128
	global_load_dwordx4 v[142:145], v26, s[44:45] offset:192
	s_waitcnt lgkmcnt(2)
	v_add_u32_e32 v27, s42, v17
	v_lshl_add_u32 v27, v27, 9, v24
	global_load_dwordx4 v[146:149], v27, s[44:45]
	global_load_dwordx4 v[150:153], v27, s[44:45] offset:64
	global_load_dwordx4 v[154:157], v27, s[44:45] offset:128
	global_load_dwordx4 v[158:161], v27, s[44:45] offset:192
	s_waitcnt lgkmcnt(1)
	v_add_u32_e32 v28, s42, v18
	v_lshl_add_u32 v28, v28, 9, v24
	global_load_dwordx4 v[162:165], v28, s[44:45]
	global_load_dwordx4 v[166:169], v28, s[44:45] offset:64
	global_load_dwordx4 v[170:173], v28, s[44:45] offset:128
	global_load_dwordx4 v[174:177], v28, s[44:45] offset:192
	s_waitcnt lgkmcnt(0)
	v_add_u32_e32 v29, s42, v19
	v_lshl_add_u32 v29, v29, 9, v24
	global_load_dwordx4 v[178:181], v29, s[44:45]
	global_load_dwordx4 v[182:185], v29, s[44:45] offset:64
	global_load_dwordx4 v[186:189], v29, s[44:45] offset:128
	global_load_dwordx4 v[190:193], v29, s[44:45] offset:192
	ds_read_b32 v20, v25 offset:6656
	ds_read_b32 v21, v25 offset:6720
	ds_read_b32 v22, v25 offset:6784
	ds_read_b32 v23, v25 offset:6848
	s_waitcnt lgkmcnt(3)
	v_add_u32_e32 v26, s42, v20
	v_lshl_add_u32 v26, v26, 9, v24
	global_load_dwordx4 v[210:213], v26, s[44:45]
	global_load_dwordx4 v[214:217], v26, s[44:45] offset:64
	global_load_dwordx4 v[218:221], v26, s[44:45] offset:128
	global_load_dwordx4 v[222:225], v26, s[44:45] offset:192
	s_waitcnt lgkmcnt(2)
	v_add_u32_e32 v27, s42, v21
	v_lshl_add_u32 v27, v27, 9, v24
	global_load_dwordx4 v[226:229], v27, s[44:45]
	global_load_dwordx4 v[230:233], v27, s[44:45] offset:64
	global_load_dwordx4 v[234:237], v27, s[44:45] offset:128
	global_load_dwordx4 v[238:241], v27, s[44:45] offset:192
	s_waitcnt lgkmcnt(1)
	v_add_u32_e32 v28, s42, v22
	v_lshl_add_u32 v28, v28, 9, v24
	global_load_dwordx4 v[70:73], v28, s[44:45]
	global_load_dwordx4 v[74:77], v28, s[44:45] offset:64
	global_load_dwordx4 v[78:81], v28, s[44:45] offset:128
	global_load_dwordx4 v[82:85], v28, s[44:45] offset:192
	s_waitcnt lgkmcnt(0)
	v_add_u32_e32 v29, s42, v23
	v_lshl_add_u32 v29, v29, 9, v24
	global_load_dwordx4 v[196:199], v29, s[44:45]
	global_load_dwordx4 v[200:203], v29, s[44:45] offset:64
	global_load_dwordx4 v[244:247], v29, s[44:45] offset:128
	global_load_dwordx4 v[248:251], v29, s[44:45] offset:192
	v_subrev_u32_e32 v30, s80, v16
	v_max_i32_e32 v30, 0xffffff80, v30
	v_lshl_add_u32 v30, v30, 2, s72
	ds_read2st64_b32 v[40:41], v30 offset0:2 offset1:5
	ds_read2st64_b32 v[42:43], v30 offset0:8 offset1:11
	s_waitcnt vmcnt(31)
	v_mfma_f32_16x16x32_bf16 v[32:35], v[4:7], v[130:133], 0
	s_waitcnt vmcnt(30)
	v_mfma_f32_16x16x32_bf16 v[32:35], v[0:3], v[134:137], v[32:35]
	s_waitcnt vmcnt(29)
	v_mfma_f32_16x16x32_bf16 v[32:35], v[12:15], v[138:141], v[32:35]
	s_waitcnt vmcnt(28)
	v_mfma_f32_16x16x32_bf16 v[32:35], v[8:11], v[142:145], v[32:35]
	v_add_u32_e32 v30, 0, v87
	s_waitcnt lgkmcnt(0)
	s_nop 6
	v_fmamk_f32 v32, v32, 0x3db504f3, v40
	v_fmac_f32_e32 v41, 0x3db504f3, v33
	v_fmamk_f32 v34, v34, 0x3db504f3, v42
	v_fmac_f32_e32 v43, 0x3db504f3, v35
	v_mov_b32_e32 v33, v41
	v_mov_b32_e32 v35, v43
	s_mov_b64 exec, s[6:7]
	ds_write_b128 v30, v[32:35]
	s_mov_b64 exec, -1
	v_subrev_u32_e32 v30, s80, v17
	v_max_i32_e32 v30, 0xffffff80, v30
	v_lshl_add_u32 v30, v30, 2, s72
	ds_read2st64_b32 v[44:45], v30 offset0:2 offset1:5
	ds_read2st64_b32 v[46:47], v30 offset0:8 offset1:11
	s_waitcnt vmcnt(27)
	v_mfma_f32_16x16x32_bf16 v[36:39], v[4:7], v[146:149], 0
	s_waitcnt vmcnt(26)
	v_mfma_f32_16x16x32_bf16 v[36:39], v[0:3], v[150:153], v[36:39]
	s_waitcnt vmcnt(25)
	v_mfma_f32_16x16x32_bf16 v[36:39], v[12:15], v[154:157], v[36:39]
	s_waitcnt vmcnt(24)
	v_mfma_f32_16x16x32_bf16 v[36:39], v[8:11], v[158:161], v[36:39]
	v_add_u32_e32 v30, 256, v87
	s_waitcnt lgkmcnt(0)
	s_nop 6
	v_fmamk_f32 v36, v36, 0x3db504f3, v44
	v_fmac_f32_e32 v45, 0x3db504f3, v37
	v_fmamk_f32 v38, v38, 0x3db504f3, v46
	v_fmac_f32_e32 v47, 0x3db504f3, v39
	v_mov_b32_e32 v37, v45
	v_mov_b32_e32 v39, v47
	s_mov_b64 exec, s[6:7]
	ds_write_b128 v30, v[36:39]
	s_mov_b64 exec, -1
	v_subrev_u32_e32 v30, s80, v18
	v_max_i32_e32 v30, 0xffffff80, v30
	v_lshl_add_u32 v30, v30, 2, s72
	ds_read2st64_b32 v[40:41], v30 offset0:2 offset1:5
	ds_read2st64_b32 v[42:43], v30 offset0:8 offset1:11
	s_waitcnt vmcnt(23)
	v_mfma_f32_16x16x32_bf16 v[32:35], v[4:7], v[162:165], 0
	s_waitcnt vmcnt(22)
	v_mfma_f32_16x16x32_bf16 v[32:35], v[0:3], v[166:169], v[32:35]
	s_waitcnt vmcnt(21)
	v_mfma_f32_16x16x32_bf16 v[32:35], v[12:15], v[170:173], v[32:35]
	s_waitcnt vmcnt(20)
	v_mfma_f32_16x16x32_bf16 v[32:35], v[8:11], v[174:177], v[32:35]
	v_add_u32_e32 v30, 512, v87
	s_waitcnt lgkmcnt(0)
	s_nop 6
	v_fmamk_f32 v32, v32, 0x3db504f3, v40
	v_fmac_f32_e32 v41, 0x3db504f3, v33
	v_fmamk_f32 v34, v34, 0x3db504f3, v42
	v_fmac_f32_e32 v43, 0x3db504f3, v35
	v_mov_b32_e32 v33, v41
	v_mov_b32_e32 v35, v43
	s_mov_b64 exec, s[6:7]
	ds_write_b128 v30, v[32:35]
	s_mov_b64 exec, -1
	v_subrev_u32_e32 v30, s80, v19
	v_max_i32_e32 v30, 0xffffff80, v30
	v_lshl_add_u32 v30, v30, 2, s72
	ds_read2st64_b32 v[44:45], v30 offset0:2 offset1:5
	ds_read2st64_b32 v[46:47], v30 offset0:8 offset1:11
	s_waitcnt vmcnt(19)
	v_mfma_f32_16x16x32_bf16 v[36:39], v[4:7], v[178:181], 0
	s_waitcnt vmcnt(18)
	v_mfma_f32_16x16x32_bf16 v[36:39], v[0:3], v[182:185], v[36:39]
	s_waitcnt vmcnt(17)
	v_mfma_f32_16x16x32_bf16 v[36:39], v[12:15], v[186:189], v[36:39]
	s_waitcnt vmcnt(16)
	v_mfma_f32_16x16x32_bf16 v[36:39], v[8:11], v[190:193], v[36:39]
	v_add_u32_e32 v30, 768, v87
	s_waitcnt lgkmcnt(0)
	s_nop 6
	v_fmamk_f32 v36, v36, 0x3db504f3, v44
	v_fmac_f32_e32 v45, 0x3db504f3, v37
	v_fmamk_f32 v38, v38, 0x3db504f3, v46
	v_fmac_f32_e32 v47, 0x3db504f3, v39
	v_mov_b32_e32 v37, v45
	v_mov_b32_e32 v39, v47
	s_mov_b64 exec, s[6:7]
	ds_write_b128 v30, v[36:39]
	s_mov_b64 exec, -1
	ds_read_b32 v16, v25 offset:6912
	ds_read_b32 v17, v25 offset:6976
	ds_read_b32 v18, v25 offset:7040
	ds_read_b32 v19, v25 offset:7104
	s_waitcnt lgkmcnt(3)
	v_add_u32_e32 v26, s42, v16
	v_lshl_add_u32 v26, v26, 9, v24
	global_load_dwordx4 v[130:133], v26, s[44:45]
	global_load_dwordx4 v[134:137], v26, s[44:45] offset:64
	global_load_dwordx4 v[138:141], v26, s[44:45] offset:128
	global_load_dwordx4 v[142:145], v26, s[44:45] offset:192
	s_waitcnt lgkmcnt(2)
	v_add_u32_e32 v27, s42, v17
	v_lshl_add_u32 v27, v27, 9, v24
	global_load_dwordx4 v[146:149], v27, s[44:45]
	global_load_dwordx4 v[150:153], v27, s[44:45] offset:64
	global_load_dwordx4 v[154:157], v27, s[44:45] offset:128
	global_load_dwordx4 v[158:161], v27, s[44:45] offset:192
	s_waitcnt lgkmcnt(1)
	v_add_u32_e32 v28, s42, v18
	v_lshl_add_u32 v28, v28, 9, v24
	global_load_dwordx4 v[162:165], v28, s[44:45]
	global_load_dwordx4 v[166:169], v28, s[44:45] offset:64
	global_load_dwordx4 v[170:173], v28, s[44:45] offset:128
	global_load_dwordx4 v[174:177], v28, s[44:45] offset:192
	s_waitcnt lgkmcnt(0)
	v_add_u32_e32 v29, s42, v19
	v_lshl_add_u32 v29, v29, 9, v24
	global_load_dwordx4 v[178:181], v29, s[44:45]
	global_load_dwordx4 v[182:185], v29, s[44:45] offset:64
	global_load_dwordx4 v[186:189], v29, s[44:45] offset:128
	global_load_dwordx4 v[190:193], v29, s[44:45] offset:192
	v_subrev_u32_e32 v30, s80, v20
	v_max_i32_e32 v30, 0xffffff80, v30
	v_lshl_add_u32 v30, v30, 2, s72
	ds_read2st64_b32 v[40:41], v30 offset0:2 offset1:5
	ds_read2st64_b32 v[42:43], v30 offset0:8 offset1:11
	s_waitcnt vmcnt(31)
	v_mfma_f32_16x16x32_bf16 v[32:35], v[4:7], v[210:213], 0
	s_waitcnt vmcnt(30)
	v_mfma_f32_16x16x32_bf16 v[32:35], v[0:3], v[214:217], v[32:35]
	s_waitcnt vmcnt(29)
	v_mfma_f32_16x16x32_bf16 v[32:35], v[12:15], v[218:221], v[32:35]
	s_waitcnt vmcnt(28)
	v_mfma_f32_16x16x32_bf16 v[32:35], v[8:11], v[222:225], v[32:35]
	v_add_u32_e32 v30, 1024, v87
	s_waitcnt lgkmcnt(0)
	s_nop 6
	v_fmamk_f32 v32, v32, 0x3db504f3, v40
	v_fmac_f32_e32 v41, 0x3db504f3, v33
	v_fmamk_f32 v34, v34, 0x3db504f3, v42
	v_fmac_f32_e32 v43, 0x3db504f3, v35
	v_mov_b32_e32 v33, v41
	v_mov_b32_e32 v35, v43
	s_mov_b64 exec, s[6:7]
	ds_write_b128 v30, v[32:35]
	s_mov_b64 exec, -1
	v_subrev_u32_e32 v30, s80, v21
	v_max_i32_e32 v30, 0xffffff80, v30
	v_lshl_add_u32 v30, v30, 2, s72
	ds_read2st64_b32 v[44:45], v30 offset0:2 offset1:5
	ds_read2st64_b32 v[46:47], v30 offset0:8 offset1:11
	s_waitcnt vmcnt(27)
	v_mfma_f32_16x16x32_bf16 v[36:39], v[4:7], v[226:229], 0
	s_waitcnt vmcnt(26)
	v_mfma_f32_16x16x32_bf16 v[36:39], v[0:3], v[230:233], v[36:39]
	s_waitcnt vmcnt(25)
	v_mfma_f32_16x16x32_bf16 v[36:39], v[12:15], v[234:237], v[36:39]
	s_waitcnt vmcnt(24)
	v_mfma_f32_16x16x32_bf16 v[36:39], v[8:11], v[238:241], v[36:39]
	v_add_u32_e32 v30, 1280, v87
	s_waitcnt lgkmcnt(0)
	s_nop 6
	v_fmamk_f32 v36, v36, 0x3db504f3, v44
	v_fmac_f32_e32 v45, 0x3db504f3, v37
	v_fmamk_f32 v38, v38, 0x3db504f3, v46
	v_fmac_f32_e32 v47, 0x3db504f3, v39
	v_mov_b32_e32 v37, v45
	v_mov_b32_e32 v39, v47
	s_mov_b64 exec, s[6:7]
	ds_write_b128 v30, v[36:39]
	s_mov_b64 exec, -1
	v_subrev_u32_e32 v30, s80, v22
	v_max_i32_e32 v30, 0xffffff80, v30
	v_lshl_add_u32 v30, v30, 2, s72
	ds_read2st64_b32 v[40:41], v30 offset0:2 offset1:5
	ds_read2st64_b32 v[42:43], v30 offset0:8 offset1:11
	s_waitcnt vmcnt(23)
	v_mfma_f32_16x16x32_bf16 v[32:35], v[4:7], v[70:73], 0
	s_waitcnt vmcnt(22)
	v_mfma_f32_16x16x32_bf16 v[32:35], v[0:3], v[74:77], v[32:35]
	s_waitcnt vmcnt(21)
	v_mfma_f32_16x16x32_bf16 v[32:35], v[12:15], v[78:81], v[32:35]
	s_waitcnt vmcnt(20)
	v_mfma_f32_16x16x32_bf16 v[32:35], v[8:11], v[82:85], v[32:35]
	v_add_u32_e32 v30, 1536, v87
	s_waitcnt lgkmcnt(0)
	s_nop 6
	v_fmamk_f32 v32, v32, 0x3db504f3, v40
	v_fmac_f32_e32 v41, 0x3db504f3, v33
	v_fmamk_f32 v34, v34, 0x3db504f3, v42
	v_fmac_f32_e32 v43, 0x3db504f3, v35
	v_mov_b32_e32 v33, v41
	v_mov_b32_e32 v35, v43
	s_mov_b64 exec, s[6:7]
	ds_write_b128 v30, v[32:35]
	s_mov_b64 exec, -1
	v_subrev_u32_e32 v30, s80, v23
	v_max_i32_e32 v30, 0xffffff80, v30
	v_lshl_add_u32 v30, v30, 2, s72
	ds_read2st64_b32 v[44:45], v30 offset0:2 offset1:5
	ds_read2st64_b32 v[46:47], v30 offset0:8 offset1:11
	s_waitcnt vmcnt(19)
	v_mfma_f32_16x16x32_bf16 v[36:39], v[4:7], v[196:199], 0
	s_waitcnt vmcnt(18)
	v_mfma_f32_16x16x32_bf16 v[36:39], v[0:3], v[200:203], v[36:39]
	s_waitcnt vmcnt(17)
	v_mfma_f32_16x16x32_bf16 v[36:39], v[12:15], v[244:247], v[36:39]
	s_waitcnt vmcnt(16)
	v_mfma_f32_16x16x32_bf16 v[36:39], v[8:11], v[248:251], v[36:39]
	v_add_u32_e32 v30, 1792, v87
	s_waitcnt lgkmcnt(0)
	s_nop 6
	v_fmamk_f32 v36, v36, 0x3db504f3, v44
	v_fmac_f32_e32 v45, 0x3db504f3, v37
	v_fmamk_f32 v38, v38, 0x3db504f3, v46
	v_fmac_f32_e32 v47, 0x3db504f3, v39
	v_mov_b32_e32 v37, v45
	v_mov_b32_e32 v39, v47
	s_mov_b64 exec, s[6:7]
	ds_write_b128 v30, v[36:39]
	s_mov_b64 exec, -1
	ds_read_b32 v20, v25 offset:7168
	ds_read_b32 v21, v25 offset:7232
	ds_read_b32 v22, v25 offset:7296
	ds_read_b32 v23, v25 offset:7360
	s_waitcnt lgkmcnt(3)
	v_add_u32_e32 v26, s42, v20
	v_lshl_add_u32 v26, v26, 9, v24
	global_load_dwordx4 v[210:213], v26, s[44:45]
	global_load_dwordx4 v[214:217], v26, s[44:45] offset:64
	global_load_dwordx4 v[218:221], v26, s[44:45] offset:128
	global_load_dwordx4 v[222:225], v26, s[44:45] offset:192
	s_waitcnt lgkmcnt(2)
	v_add_u32_e32 v27, s42, v21
	v_lshl_add_u32 v27, v27, 9, v24
	global_load_dwordx4 v[226:229], v27, s[44:45]
	global_load_dwordx4 v[230:233], v27, s[44:45] offset:64
	global_load_dwordx4 v[234:237], v27, s[44:45] offset:128
	global_load_dwordx4 v[238:241], v27, s[44:45] offset:192
	s_waitcnt lgkmcnt(1)
	v_add_u32_e32 v28, s42, v22
	v_lshl_add_u32 v28, v28, 9, v24
	global_load_dwordx4 v[70:73], v28, s[44:45]
	global_load_dwordx4 v[74:77], v28, s[44:45] offset:64
	global_load_dwordx4 v[78:81], v28, s[44:45] offset:128
	global_load_dwordx4 v[82:85], v28, s[44:45] offset:192
	s_waitcnt lgkmcnt(0)
	v_add_u32_e32 v29, s42, v23
	v_lshl_add_u32 v29, v29, 9, v24
	global_load_dwordx4 v[196:199], v29, s[44:45]
	global_load_dwordx4 v[200:203], v29, s[44:45] offset:64
	global_load_dwordx4 v[244:247], v29, s[44:45] offset:128
	global_load_dwordx4 v[248:251], v29, s[44:45] offset:192
	v_subrev_u32_e32 v30, s80, v16
	v_max_i32_e32 v30, 0xffffff80, v30
	v_lshl_add_u32 v30, v30, 2, s72
	ds_read2st64_b32 v[40:41], v30 offset0:2 offset1:5
	ds_read2st64_b32 v[42:43], v30 offset0:8 offset1:11
	s_waitcnt vmcnt(31)
	v_mfma_f32_16x16x32_bf16 v[32:35], v[4:7], v[130:133], 0
	s_waitcnt vmcnt(30)
	v_mfma_f32_16x16x32_bf16 v[32:35], v[0:3], v[134:137], v[32:35]
	s_waitcnt vmcnt(29)
	v_mfma_f32_16x16x32_bf16 v[32:35], v[12:15], v[138:141], v[32:35]
	s_waitcnt vmcnt(28)
	v_mfma_f32_16x16x32_bf16 v[32:35], v[8:11], v[142:145], v[32:35]
	v_add_u32_e32 v30, 2048, v87
	s_waitcnt lgkmcnt(0)
	s_nop 6
	v_fmamk_f32 v32, v32, 0x3db504f3, v40
	v_fmac_f32_e32 v41, 0x3db504f3, v33
	v_fmamk_f32 v34, v34, 0x3db504f3, v42
	v_fmac_f32_e32 v43, 0x3db504f3, v35
	v_mov_b32_e32 v33, v41
	v_mov_b32_e32 v35, v43
	s_mov_b64 exec, s[6:7]
	ds_write_b128 v30, v[32:35]
	s_mov_b64 exec, -1
	v_subrev_u32_e32 v30, s80, v17
	v_max_i32_e32 v30, 0xffffff80, v30
	v_lshl_add_u32 v30, v30, 2, s72
	ds_read2st64_b32 v[44:45], v30 offset0:2 offset1:5
	ds_read2st64_b32 v[46:47], v30 offset0:8 offset1:11
	s_waitcnt vmcnt(27)
	v_mfma_f32_16x16x32_bf16 v[36:39], v[4:7], v[146:149], 0
	s_waitcnt vmcnt(26)
	v_mfma_f32_16x16x32_bf16 v[36:39], v[0:3], v[150:153], v[36:39]
	s_waitcnt vmcnt(25)
	v_mfma_f32_16x16x32_bf16 v[36:39], v[12:15], v[154:157], v[36:39]
	s_waitcnt vmcnt(24)
	v_mfma_f32_16x16x32_bf16 v[36:39], v[8:11], v[158:161], v[36:39]
	v_add_u32_e32 v30, 2304, v87
	s_waitcnt lgkmcnt(0)
	s_nop 6
	v_fmamk_f32 v36, v36, 0x3db504f3, v44
	v_fmac_f32_e32 v45, 0x3db504f3, v37
	v_fmamk_f32 v38, v38, 0x3db504f3, v46
	v_fmac_f32_e32 v47, 0x3db504f3, v39
	v_mov_b32_e32 v37, v45
	v_mov_b32_e32 v39, v47
	s_mov_b64 exec, s[6:7]
	ds_write_b128 v30, v[36:39]
	s_mov_b64 exec, -1
	v_subrev_u32_e32 v30, s80, v18
	v_max_i32_e32 v30, 0xffffff80, v30
	v_lshl_add_u32 v30, v30, 2, s72
	ds_read2st64_b32 v[40:41], v30 offset0:2 offset1:5
	ds_read2st64_b32 v[42:43], v30 offset0:8 offset1:11
	s_waitcnt vmcnt(23)
	v_mfma_f32_16x16x32_bf16 v[32:35], v[4:7], v[162:165], 0
	s_waitcnt vmcnt(22)
	v_mfma_f32_16x16x32_bf16 v[32:35], v[0:3], v[166:169], v[32:35]
	s_waitcnt vmcnt(21)
	v_mfma_f32_16x16x32_bf16 v[32:35], v[12:15], v[170:173], v[32:35]
	s_waitcnt vmcnt(20)
	v_mfma_f32_16x16x32_bf16 v[32:35], v[8:11], v[174:177], v[32:35]
	v_add_u32_e32 v30, 2560, v87
	s_waitcnt lgkmcnt(0)
	s_nop 6
	v_fmamk_f32 v32, v32, 0x3db504f3, v40
	v_fmac_f32_e32 v41, 0x3db504f3, v33
	v_fmamk_f32 v34, v34, 0x3db504f3, v42
	v_fmac_f32_e32 v43, 0x3db504f3, v35
	v_mov_b32_e32 v33, v41
	v_mov_b32_e32 v35, v43
	s_mov_b64 exec, s[6:7]
	ds_write_b128 v30, v[32:35]
	s_mov_b64 exec, -1
	v_subrev_u32_e32 v30, s80, v19
	v_max_i32_e32 v30, 0xffffff80, v30
	v_lshl_add_u32 v30, v30, 2, s72
	ds_read2st64_b32 v[44:45], v30 offset0:2 offset1:5
	ds_read2st64_b32 v[46:47], v30 offset0:8 offset1:11
	s_waitcnt vmcnt(19)
	v_mfma_f32_16x16x32_bf16 v[36:39], v[4:7], v[178:181], 0
	s_waitcnt vmcnt(18)
	v_mfma_f32_16x16x32_bf16 v[36:39], v[0:3], v[182:185], v[36:39]
	s_waitcnt vmcnt(17)
	v_mfma_f32_16x16x32_bf16 v[36:39], v[12:15], v[186:189], v[36:39]
	s_waitcnt vmcnt(16)
	v_mfma_f32_16x16x32_bf16 v[36:39], v[8:11], v[190:193], v[36:39]
	v_add_u32_e32 v30, 2816, v87
	s_waitcnt lgkmcnt(0)
	s_nop 6
	v_fmamk_f32 v36, v36, 0x3db504f3, v44
	v_fmac_f32_e32 v45, 0x3db504f3, v37
	v_fmamk_f32 v38, v38, 0x3db504f3, v46
	v_fmac_f32_e32 v47, 0x3db504f3, v39
	v_mov_b32_e32 v37, v45
	v_mov_b32_e32 v39, v47
	s_mov_b64 exec, s[6:7]
	ds_write_b128 v30, v[36:39]
	s_mov_b64 exec, -1
	v_subrev_u32_e32 v30, s80, v20
	v_max_i32_e32 v30, 0xffffff80, v30
	v_lshl_add_u32 v30, v30, 2, s72
	ds_read2st64_b32 v[40:41], v30 offset0:2 offset1:5
	ds_read2st64_b32 v[42:43], v30 offset0:8 offset1:11
	s_waitcnt vmcnt(15)
	v_mfma_f32_16x16x32_bf16 v[32:35], v[4:7], v[210:213], 0
	s_waitcnt vmcnt(14)
	v_mfma_f32_16x16x32_bf16 v[32:35], v[0:3], v[214:217], v[32:35]
	s_waitcnt vmcnt(13)
	v_mfma_f32_16x16x32_bf16 v[32:35], v[12:15], v[218:221], v[32:35]
	s_waitcnt vmcnt(12)
	v_mfma_f32_16x16x32_bf16 v[32:35], v[8:11], v[222:225], v[32:35]
	v_add_u32_e32 v30, 3072, v87
	s_waitcnt lgkmcnt(0)
	s_nop 6
	v_fmamk_f32 v32, v32, 0x3db504f3, v40
	v_fmac_f32_e32 v41, 0x3db504f3, v33
	v_fmamk_f32 v34, v34, 0x3db504f3, v42
	v_fmac_f32_e32 v43, 0x3db504f3, v35
	v_mov_b32_e32 v33, v41
	v_mov_b32_e32 v35, v43
	s_mov_b64 exec, s[6:7]
	ds_write_b128 v30, v[32:35]
	s_mov_b64 exec, -1
	v_subrev_u32_e32 v30, s80, v21
	v_max_i32_e32 v30, 0xffffff80, v30
	v_lshl_add_u32 v30, v30, 2, s72
	ds_read2st64_b32 v[44:45], v30 offset0:2 offset1:5
	ds_read2st64_b32 v[46:47], v30 offset0:8 offset1:11
	s_waitcnt vmcnt(11)
	v_mfma_f32_16x16x32_bf16 v[36:39], v[4:7], v[226:229], 0
	s_waitcnt vmcnt(10)
	v_mfma_f32_16x16x32_bf16 v[36:39], v[0:3], v[230:233], v[36:39]
	s_waitcnt vmcnt(9)
	v_mfma_f32_16x16x32_bf16 v[36:39], v[12:15], v[234:237], v[36:39]
	s_waitcnt vmcnt(8)
	v_mfma_f32_16x16x32_bf16 v[36:39], v[8:11], v[238:241], v[36:39]
	v_add_u32_e32 v30, 3328, v87
	s_waitcnt lgkmcnt(0)
	s_nop 6
	v_fmamk_f32 v36, v36, 0x3db504f3, v44
	v_fmac_f32_e32 v45, 0x3db504f3, v37
	v_fmamk_f32 v38, v38, 0x3db504f3, v46
	v_fmac_f32_e32 v47, 0x3db504f3, v39
	v_mov_b32_e32 v37, v45
	v_mov_b32_e32 v39, v47
	s_mov_b64 exec, s[6:7]
	ds_write_b128 v30, v[36:39]
	s_mov_b64 exec, -1
	v_subrev_u32_e32 v30, s80, v22
	v_max_i32_e32 v30, 0xffffff80, v30
	v_lshl_add_u32 v30, v30, 2, s72
	ds_read2st64_b32 v[40:41], v30 offset0:2 offset1:5
	ds_read2st64_b32 v[42:43], v30 offset0:8 offset1:11
	s_waitcnt vmcnt(7)
	v_mfma_f32_16x16x32_bf16 v[32:35], v[4:7], v[70:73], 0
	s_waitcnt vmcnt(6)
	v_mfma_f32_16x16x32_bf16 v[32:35], v[0:3], v[74:77], v[32:35]
	s_waitcnt vmcnt(5)
	v_mfma_f32_16x16x32_bf16 v[32:35], v[12:15], v[78:81], v[32:35]
	s_waitcnt vmcnt(4)
	v_mfma_f32_16x16x32_bf16 v[32:35], v[8:11], v[82:85], v[32:35]
	v_add_u32_e32 v30, 3584, v87
	s_waitcnt lgkmcnt(0)
	s_nop 6
	v_fmamk_f32 v32, v32, 0x3db504f3, v40
	v_fmac_f32_e32 v41, 0x3db504f3, v33
	v_fmamk_f32 v34, v34, 0x3db504f3, v42
	v_fmac_f32_e32 v43, 0x3db504f3, v35
	v_mov_b32_e32 v33, v41
	v_mov_b32_e32 v35, v43
	s_mov_b64 exec, s[6:7]
	ds_write_b128 v30, v[32:35]
	s_mov_b64 exec, -1
	v_subrev_u32_e32 v30, s80, v23
	v_max_i32_e32 v30, 0xffffff80, v30
	v_lshl_add_u32 v30, v30, 2, s72
	ds_read2st64_b32 v[44:45], v30 offset0:2 offset1:5
	ds_read2st64_b32 v[46:47], v30 offset0:8 offset1:11
	s_waitcnt vmcnt(3)
	v_mfma_f32_16x16x32_bf16 v[36:39], v[4:7], v[196:199], 0
	s_waitcnt vmcnt(2)
	v_mfma_f32_16x16x32_bf16 v[36:39], v[0:3], v[200:203], v[36:39]
	s_waitcnt vmcnt(1)
	v_mfma_f32_16x16x32_bf16 v[36:39], v[12:15], v[244:247], v[36:39]
	s_waitcnt vmcnt(0)
	v_mfma_f32_16x16x32_bf16 v[36:39], v[8:11], v[248:251], v[36:39]
	v_add_u32_e32 v30, 3840, v87
	s_waitcnt lgkmcnt(0)
	s_nop 6
	v_fmamk_f32 v36, v36, 0x3db504f3, v44
	v_fmac_f32_e32 v45, 0x3db504f3, v37
	v_fmamk_f32 v38, v38, 0x3db504f3, v46
	v_fmac_f32_e32 v47, 0x3db504f3, v39
	v_mov_b32_e32 v37, v45
	v_mov_b32_e32 v39, v47
	s_mov_b64 exec, s[6:7]
	ds_write_b128 v30, v[36:39]
	s_mov_b64 exec, -1
	s_branch .LBB0_1532
.LBB0_1532:
	s_cmpk_eq_i32 s78, 0x100
	s_cbranch_scc0 .Lpv_nopre
	s_lshl_b64 s[8:9], s[42:43], 9
	s_add_u32 s8, s69, s8
	s_addc_u32 s9, s70, s9
	v_lshlrev_b32_e32 v110, 4, v56
	v_lshl_add_u32 v129, v55, 2, s66
	v_lshl_add_u32 v112, v55, 4, s67
	ds_read_b32 v34, v129 offset:6400
	ds_read_b32 v35, v129 offset:6416
	ds_read_b32 v36, v129 offset:6432
	ds_read_b32 v37, v129 offset:6448
	ds_read_b32 v38, v129 offset:6464
	ds_read_b32 v39, v129 offset:6480
	ds_read_b32 v40, v129 offset:6496
	ds_read_b32 v41, v129 offset:6512
	ds_read_b32 v42, v129 offset:6528
	ds_read_b32 v43, v129 offset:6544
	ds_read_b32 v44, v129 offset:6560
	ds_read_b32 v45, v129 offset:6576
	ds_read_b32 v46, v129 offset:6592
	ds_read_b32 v47, v129 offset:6608
	ds_read_b32 v48, v129 offset:6624
	ds_read_b32 v49, v129 offset:6640
	s_waitcnt lgkmcnt(15)
	v_lshl_add_u32 v34, v34, 9, v110
	global_load_dwordx4 v[130:133], v34, s[8:9]
	s_waitcnt lgkmcnt(14)
	v_lshl_add_u32 v35, v35, 9, v110
	global_load_dwordx4 v[134:137], v35, s[8:9]
	s_waitcnt lgkmcnt(13)
	v_lshl_add_u32 v36, v36, 9, v110
	global_load_dwordx4 v[138:141], v36, s[8:9]
	s_waitcnt lgkmcnt(12)
	v_lshl_add_u32 v37, v37, 9, v110
	global_load_dwordx4 v[142:145], v37, s[8:9]
	s_waitcnt lgkmcnt(11)
	v_lshl_add_u32 v38, v38, 9, v110
	global_load_dwordx4 v[146:149], v38, s[8:9]
	s_waitcnt lgkmcnt(10)
	v_lshl_add_u32 v39, v39, 9, v110
	global_load_dwordx4 v[150:153], v39, s[8:9]
	s_waitcnt lgkmcnt(9)
	v_lshl_add_u32 v40, v40, 9, v110
	global_load_dwordx4 v[154:157], v40, s[8:9]
	s_waitcnt lgkmcnt(8)
	v_lshl_add_u32 v41, v41, 9, v110
	global_load_dwordx4 v[158:161], v41, s[8:9]
	s_waitcnt lgkmcnt(7)
	v_lshl_add_u32 v42, v42, 9, v110
	global_load_dwordx4 v[162:165], v42, s[8:9]
	s_waitcnt lgkmcnt(6)
	v_lshl_add_u32 v43, v43, 9, v110
	global_load_dwordx4 v[166:169], v43, s[8:9]
	s_waitcnt lgkmcnt(5)
	v_lshl_add_u32 v44, v44, 9, v110
	global_load_dwordx4 v[170:173], v44, s[8:9]
	s_waitcnt lgkmcnt(4)
	v_lshl_add_u32 v45, v45, 9, v110
	global_load_dwordx4 v[174:177], v45, s[8:9]
	s_waitcnt lgkmcnt(3)
	v_lshl_add_u32 v46, v46, 9, v110
	global_load_dwordx4 v[178:181], v46, s[8:9]
	s_waitcnt lgkmcnt(2)
	v_lshl_add_u32 v47, v47, 9, v110
	global_load_dwordx4 v[182:185], v47, s[8:9]
	s_waitcnt lgkmcnt(1)
	v_lshl_add_u32 v48, v48, 9, v110
	global_load_dwordx4 v[186:189], v48, s[8:9]
	s_waitcnt lgkmcnt(0)
	v_lshl_add_u32 v49, v49, 9, v110
	global_load_dwordx4 v[190:193], v49, s[8:9]
	ds_read_b32 v34, v129 offset:6656
	ds_read_b32 v35, v129 offset:6672
	ds_read_b32 v36, v129 offset:6688
	ds_read_b32 v37, v129 offset:6704
	ds_read_b32 v38, v129 offset:6720
	ds_read_b32 v39, v129 offset:6736
	ds_read_b32 v40, v129 offset:6752
	ds_read_b32 v41, v129 offset:6768
	ds_read_b32 v42, v129 offset:6784
	ds_read_b32 v43, v129 offset:6800
	ds_read_b32 v44, v129 offset:6816
	ds_read_b32 v45, v129 offset:6832
	ds_read_b32 v46, v129 offset:6848
	ds_read_b32 v47, v129 offset:6864
	ds_read_b32 v48, v129 offset:6880
	ds_read_b32 v49, v129 offset:6896
	s_waitcnt lgkmcnt(15)
	v_lshl_add_u32 v34, v34, 9, v110
	global_load_dwordx4 v[210:213], v34, s[8:9]
	s_waitcnt lgkmcnt(14)
	v_lshl_add_u32 v35, v35, 9, v110
	global_load_dwordx4 v[214:217], v35, s[8:9]
	s_waitcnt lgkmcnt(13)
	v_lshl_add_u32 v36, v36, 9, v110
	global_load_dwordx4 v[218:221], v36, s[8:9]
	s_waitcnt lgkmcnt(12)
	v_lshl_add_u32 v37, v37, 9, v110
	global_load_dwordx4 v[222:225], v37, s[8:9]
	s_waitcnt lgkmcnt(11)
	v_lshl_add_u32 v38, v38, 9, v110
	global_load_dwordx4 v[226:229], v38, s[8:9]
	s_waitcnt lgkmcnt(10)
	v_lshl_add_u32 v39, v39, 9, v110
	global_load_dwordx4 v[230:233], v39, s[8:9]
	s_waitcnt lgkmcnt(9)
	v_lshl_add_u32 v40, v40, 9, v110
	global_load_dwordx4 v[234:237], v40, s[8:9]
	s_waitcnt lgkmcnt(8)
	v_lshl_add_u32 v41, v41, 9, v110
	global_load_dwordx4 v[238:241], v41, s[8:9]
	s_waitcnt lgkmcnt(7)
	v_lshl_add_u32 v42, v42, 9, v110
	global_load_dwordx4 v[70:73], v42, s[8:9]
	s_waitcnt lgkmcnt(6)
	v_lshl_add_u32 v43, v43, 9, v110
	global_load_dwordx4 v[74:77], v43, s[8:9]
	s_waitcnt lgkmcnt(5)
	v_lshl_add_u32 v44, v44, 9, v110
	global_load_dwordx4 v[78:81], v44, s[8:9]
	s_waitcnt lgkmcnt(4)
	v_lshl_add_u32 v45, v45, 9, v110
	global_load_dwordx4 v[82:85], v45, s[8:9]
	s_waitcnt lgkmcnt(3)
	v_lshl_add_u32 v46, v46, 9, v110
	global_load_dwordx4 v[90:93], v46, s[8:9]
	s_waitcnt lgkmcnt(2)
	v_lshl_add_u32 v47, v47, 9, v110
	global_load_dwordx4 v[94:97], v47, s[8:9]
	s_waitcnt lgkmcnt(1)
	v_lshl_add_u32 v48, v48, 9, v110
	global_load_dwordx4 v[196:199], v48, s[8:9]
	s_waitcnt lgkmcnt(0)
	v_lshl_add_u32 v49, v49, 9, v110
	global_load_dwordx4 v[200:203], v49, s[8:9]

.Lpv_fast:
	ds_read_b128 v[248:251], v112 offset:43264
	ds_read_b128 v[252:255], v112 offset:43328
	s_waitcnt vmcnt(31)
	v_lshlrev_b32_e32 v108, 16, v130
	v_and_b32_e32 v109, 0xffff0000, v130
	v_lshlrev_b32_e32 v246, 16, v131
	v_and_b32_e32 v247, 0xffff0000, v131
	v_lshlrev_b32_e32 v130, 16, v132
	v_and_b32_e32 v131, 0xffff0000, v132
	v_lshlrev_b32_e32 v132, 16, v133
	v_and_b32_e32 v133, 0xffff0000, v133
	s_waitcnt lgkmcnt(1)
	v_pk_fma_f32 v[8:9], v[250:251], v[108:109], v[8:9] op_sel:[1,0,0] op_sel_hi:[1,1,1]
	v_pk_fma_f32 v[32:33], v[248:249], v[108:109], v[32:33] op_sel_hi:[0,1,1]
	v_pk_fma_f32 v[22:23], v[248:249], v[108:109], v[22:23] op_sel:[1,0,0] op_sel_hi:[1,1,1]
	v_pk_fma_f32 v[16:17], v[250:251], v[108:109], v[16:17] op_sel_hi:[0,1,1]
	v_pk_fma_f32 v[4:5], v[250:251], v[246:247], v[4:5] op_sel:[1,0,0] op_sel_hi:[1,1,1]
	v_pk_fma_f32 v[30:31], v[248:249], v[246:247], v[30:31] op_sel_hi:[0,1,1]
	v_pk_fma_f32 v[20:21], v[248:249], v[246:247], v[20:21] op_sel:[1,0,0] op_sel_hi:[1,1,1]
	v_pk_fma_f32 v[12:13], v[250:251], v[246:247], v[12:13] op_sel_hi:[0,1,1]
	v_pk_fma_f32 v[2:3], v[250:251], v[130:131], v[2:3] op_sel:[1,0,0] op_sel_hi:[1,1,1]
	v_pk_fma_f32 v[26:27], v[248:249], v[130:131], v[26:27] op_sel_hi:[0,1,1]
	v_pk_fma_f32 v[18:19], v[248:249], v[130:131], v[18:19] op_sel:[1,0,0] op_sel_hi:[1,1,1]
	v_pk_fma_f32 v[10:11], v[250:251], v[130:131], v[10:11] op_sel_hi:[0,1,1]
	v_pk_fma_f32 v[0:1], v[250:251], v[132:133], v[0:1] op_sel:[1,0,0] op_sel_hi:[1,1,1]
	v_pk_fma_f32 v[24:25], v[248:249], v[132:133], v[24:25] op_sel_hi:[0,1,1]
	v_pk_fma_f32 v[14:15], v[248:249], v[132:133], v[14:15] op_sel:[1,0,0] op_sel_hi:[1,1,1]
	v_pk_fma_f32 v[6:7], v[250:251], v[132:133], v[6:7] op_sel_hi:[0,1,1]
	ds_read_b128 v[248:251], v112 offset:43392
	s_waitcnt vmcnt(30)
	v_lshlrev_b32_e32 v108, 16, v134
	v_and_b32_e32 v109, 0xffff0000, v134
	v_lshlrev_b32_e32 v246, 16, v135
	v_and_b32_e32 v247, 0xffff0000, v135
	v_lshlrev_b32_e32 v134, 16, v136
	v_and_b32_e32 v135, 0xffff0000, v136
	v_lshlrev_b32_e32 v136, 16, v137
	v_and_b32_e32 v137, 0xffff0000, v137
	s_waitcnt lgkmcnt(1)
	v_pk_fma_f32 v[8:9], v[254:255], v[108:109], v[8:9] op_sel:[1,0,0] op_sel_hi:[1,1,1]
	v_pk_fma_f32 v[32:33], v[252:253], v[108:109], v[32:33] op_sel_hi:[0,1,1]
	v_pk_fma_f32 v[22:23], v[252:253], v[108:109], v[22:23] op_sel:[1,0,0] op_sel_hi:[1,1,1]
	v_pk_fma_f32 v[16:17], v[254:255], v[108:109], v[16:17] op_sel_hi:[0,1,1]
	v_pk_fma_f32 v[4:5], v[254:255], v[246:247], v[4:5] op_sel:[1,0,0] op_sel_hi:[1,1,1]
	v_pk_fma_f32 v[30:31], v[252:253], v[246:247], v[30:31] op_sel_hi:[0,1,1]
	v_pk_fma_f32 v[20:21], v[252:253], v[246:247], v[20:21] op_sel:[1,0,0] op_sel_hi:[1,1,1]
	v_pk_fma_f32 v[12:13], v[254:255], v[246:247], v[12:13] op_sel_hi:[0,1,1]
	v_pk_fma_f32 v[2:3], v[254:255], v[134:135], v[2:3] op_sel:[1,0,0] op_sel_hi:[1,1,1]
	v_pk_fma_f32 v[26:27], v[252:253], v[134:135], v[26:27] op_sel_hi:[0,1,1]
	v_pk_fma_f32 v[18:19], v[252:253], v[134:135], v[18:19] op_sel:[1,0,0] op_sel_hi:[1,1,1]
	v_pk_fma_f32 v[10:11], v[254:255], v[134:135], v[10:11] op_sel_hi:[0,1,1]
	v_pk_fma_f32 v[0:1], v[254:255], v[136:137], v[0:1] op_sel:[1,0,0] op_sel_hi:[1,1,1]
	v_pk_fma_f32 v[24:25], v[252:253], v[136:137], v[24:25] op_sel_hi:[0,1,1]
	v_pk_fma_f32 v[14:15], v[252:253], v[136:137], v[14:15] op_sel:[1,0,0] op_sel_hi:[1,1,1]
	v_pk_fma_f32 v[6:7], v[254:255], v[136:137], v[6:7] op_sel_hi:[0,1,1]
	ds_read_b128 v[252:255], v112 offset:43456
	s_waitcnt vmcnt(29)
	v_lshlrev_b32_e32 v108, 16, v138
	v_and_b32_e32 v109, 0xffff0000, v138
	v_lshlrev_b32_e32 v246, 16, v139
	v_and_b32_e32 v247, 0xffff0000, v139
	v_lshlrev_b32_e32 v138, 16, v140
	v_and_b32_e32 v139, 0xffff0000, v140
	v_lshlrev_b32_e32 v140, 16, v141
	v_and_b32_e32 v141, 0xffff0000, v141
	s_waitcnt lgkmcnt(1)
	v_pk_fma_f32 v[8:9], v[250:251], v[108:109], v[8:9] op_sel:[1,0,0] op_sel_hi:[1,1,1]
	v_pk_fma_f32 v[32:33], v[248:249], v[108:109], v[32:33] op_sel_hi:[0,1,1]
	v_pk_fma_f32 v[22:23], v[248:249], v[108:109], v[22:23] op_sel:[1,0,0] op_sel_hi:[1,1,1]
	v_pk_fma_f32 v[16:17], v[250:251], v[108:109], v[16:17] op_sel_hi:[0,1,1]
	v_pk_fma_f32 v[4:5], v[250:251], v[246:247], v[4:5] op_sel:[1,0,0] op_sel_hi:[1,1,1]
	v_pk_fma_f32 v[30:31], v[248:249], v[246:247], v[30:31] op_sel_hi:[0,1,1]
	v_pk_fma_f32 v[20:21], v[248:249], v[246:247], v[20:21] op_sel:[1,0,0] op_sel_hi:[1,1,1]
	v_pk_fma_f32 v[12:13], v[250:251], v[246:247], v[12:13] op_sel_hi:[0,1,1]
	v_pk_fma_f32 v[2:3], v[250:251], v[138:139], v[2:3] op_sel:[1,0,0] op_sel_hi:[1,1,1]
	v_pk_fma_f32 v[26:27], v[248:249], v[138:139], v[26:27] op_sel_hi:[0,1,1]
	v_pk_fma_f32 v[18:19], v[248:249], v[138:139], v[18:19] op_sel:[1,0,0] op_sel_hi:[1,1,1]
	v_pk_fma_f32 v[10:11], v[250:251], v[138:139], v[10:11] op_sel_hi:[0,1,1]
	v_pk_fma_f32 v[0:1], v[250:251], v[140:141], v[0:1] op_sel:[1,0,0] op_sel_hi:[1,1,1]
	v_pk_fma_f32 v[24:25], v[248:249], v[140:141], v[24:25] op_sel_hi:[0,1,1]
	v_pk_fma_f32 v[14:15], v[248:249], v[140:141], v[14:15] op_sel:[1,0,0] op_sel_hi:[1,1,1]
	v_pk_fma_f32 v[6:7], v[250:251], v[140:141], v[6:7] op_sel_hi:[0,1,1]
	ds_read_b128 v[248:251], v112 offset:43520
	s_waitcnt vmcnt(28)
	v_lshlrev_b32_e32 v108, 16, v142
	v_and_b32_e32 v109, 0xffff0000, v142
	v_lshlrev_b32_e32 v246, 16, v143
	v_and_b32_e32 v247, 0xffff0000, v143
	v_lshlrev_b32_e32 v142, 16, v144
	v_and_b32_e32 v143, 0xffff0000, v144
	v_lshlrev_b32_e32 v144, 16, v145
	v_and_b32_e32 v145, 0xffff0000, v145
	s_waitcnt lgkmcnt(1)
	v_pk_fma_f32 v[8:9], v[254:255], v[108:109], v[8:9] op_sel:[1,0,0] op_sel_hi:[1,1,1]
	v_pk_fma_f32 v[32:33], v[252:253], v[108:109], v[32:33] op_sel_hi:[0,1,1]
	v_pk_fma_f32 v[22:23], v[252:253], v[108:109], v[22:23] op_sel:[1,0,0] op_sel_hi:[1,1,1]
	v_pk_fma_f32 v[16:17], v[254:255], v[108:109], v[16:17] op_sel_hi:[0,1,1]
	v_pk_fma_f32 v[4:5], v[254:255], v[246:247], v[4:5] op_sel:[1,0,0] op_sel_hi:[1,1,1]
	v_pk_fma_f32 v[30:31], v[252:253], v[246:247], v[30:31] op_sel_hi:[0,1,1]
	v_pk_fma_f32 v[20:21], v[252:253], v[246:247], v[20:21] op_sel:[1,0,0] op_sel_hi:[1,1,1]
	v_pk_fma_f32 v[12:13], v[254:255], v[246:247], v[12:13] op_sel_hi:[0,1,1]
	v_pk_fma_f32 v[2:3], v[254:255], v[142:143], v[2:3] op_sel:[1,0,0] op_sel_hi:[1,1,1]
	v_pk_fma_f32 v[26:27], v[252:253], v[142:143], v[26:27] op_sel_hi:[0,1,1]
	v_pk_fma_f32 v[18:19], v[252:253], v[142:143], v[18:19] op_sel:[1,0,0] op_sel_hi:[1,1,1]
	v_pk_fma_f32 v[10:11], v[254:255], v[142:143], v[10:11] op_sel_hi:[0,1,1]
	v_pk_fma_f32 v[0:1], v[254:255], v[144:145], v[0:1] op_sel:[1,0,0] op_sel_hi:[1,1,1]
	v_pk_fma_f32 v[24:25], v[252:253], v[144:145], v[24:25] op_sel_hi:[0,1,1]
	v_pk_fma_f32 v[14:15], v[252:253], v[144:145], v[14:15] op_sel:[1,0,0] op_sel_hi:[1,1,1]
	v_pk_fma_f32 v[6:7], v[254:255], v[144:145], v[6:7] op_sel_hi:[0,1,1]
	ds_read_b128 v[252:255], v112 offset:43584
	s_waitcnt vmcnt(27)
	v_lshlrev_b32_e32 v108, 16, v146
	v_and_b32_e32 v109, 0xffff0000, v146
	v_lshlrev_b32_e32 v246, 16, v147
	v_and_b32_e32 v247, 0xffff0000, v147
	v_lshlrev_b32_e32 v146, 16, v148
	v_and_b32_e32 v147, 0xffff0000, v148
	v_lshlrev_b32_e32 v148, 16, v149
	v_and_b32_e32 v149, 0xffff0000, v149
	s_waitcnt lgkmcnt(1)
	v_pk_fma_f32 v[8:9], v[250:251], v[108:109], v[8:9] op_sel:[1,0,0] op_sel_hi:[1,1,1]
	v_pk_fma_f32 v[32:33], v[248:249], v[108:109], v[32:33] op_sel_hi:[0,1,1]
	v_pk_fma_f32 v[22:23], v[248:249], v[108:109], v[22:23] op_sel:[1,0,0] op_sel_hi:[1,1,1]
	v_pk_fma_f32 v[16:17], v[250:251], v[108:109], v[16:17] op_sel_hi:[0,1,1]
	v_pk_fma_f32 v[4:5], v[250:251], v[246:247], v[4:5] op_sel:[1,0,0] op_sel_hi:[1,1,1]
	v_pk_fma_f32 v[30:31], v[248:249], v[246:247], v[30:31] op_sel_hi:[0,1,1]
	v_pk_fma_f32 v[20:21], v[248:249], v[246:247], v[20:21] op_sel:[1,0,0] op_sel_hi:[1,1,1]
	v_pk_fma_f32 v[12:13], v[250:251], v[246:247], v[12:13] op_sel_hi:[0,1,1]
	v_pk_fma_f32 v[2:3], v[250:251], v[146:147], v[2:3] op_sel:[1,0,0] op_sel_hi:[1,1,1]
	v_pk_fma_f32 v[26:27], v[248:249], v[146:147], v[26:27] op_sel_hi:[0,1,1]
	v_pk_fma_f32 v[18:19], v[248:249], v[146:147], v[18:19] op_sel:[1,0,0] op_sel_hi:[1,1,1]
	v_pk_fma_f32 v[10:11], v[250:251], v[146:147], v[10:11] op_sel_hi:[0,1,1]
	v_pk_fma_f32 v[0:1], v[250:251], v[148:149], v[0:1] op_sel:[1,0,0] op_sel_hi:[1,1,1]
	v_pk_fma_f32 v[24:25], v[248:249], v[148:149], v[24:25] op_sel_hi:[0,1,1]
	v_pk_fma_f32 v[14:15], v[248:249], v[148:149], v[14:15] op_sel:[1,0,0] op_sel_hi:[1,1,1]
	v_pk_fma_f32 v[6:7], v[250:251], v[148:149], v[6:7] op_sel_hi:[0,1,1]
	ds_read_b128 v[248:251], v112 offset:43648
	s_waitcnt vmcnt(26)
	v_lshlrev_b32_e32 v108, 16, v150
	v_and_b32_e32 v109, 0xffff0000, v150
	v_lshlrev_b32_e32 v246, 16, v151
	v_and_b32_e32 v247, 0xffff0000, v151
	v_lshlrev_b32_e32 v150, 16, v152
	v_and_b32_e32 v151, 0xffff0000, v152
	v_lshlrev_b32_e32 v152, 16, v153
	v_and_b32_e32 v153, 0xffff0000, v153
	s_waitcnt lgkmcnt(1)
	v_pk_fma_f32 v[8:9], v[254:255], v[108:109], v[8:9] op_sel:[1,0,0] op_sel_hi:[1,1,1]
	v_pk_fma_f32 v[32:33], v[252:253], v[108:109], v[32:33] op_sel_hi:[0,1,1]
	v_pk_fma_f32 v[22:23], v[252:253], v[108:109], v[22:23] op_sel:[1,0,0] op_sel_hi:[1,1,1]
	v_pk_fma_f32 v[16:17], v[254:255], v[108:109], v[16:17] op_sel_hi:[0,1,1]
	v_pk_fma_f32 v[4:5], v[254:255], v[246:247], v[4:5] op_sel:[1,0,0] op_sel_hi:[1,1,1]
	v_pk_fma_f32 v[30:31], v[252:253], v[246:247], v[30:31] op_sel_hi:[0,1,1]
	v_pk_fma_f32 v[20:21], v[252:253], v[246:247], v[20:21] op_sel:[1,0,0] op_sel_hi:[1,1,1]
	v_pk_fma_f32 v[12:13], v[254:255], v[246:247], v[12:13] op_sel_hi:[0,1,1]
	v_pk_fma_f32 v[2:3], v[254:255], v[150:151], v[2:3] op_sel:[1,0,0] op_sel_hi:[1,1,1]
	v_pk_fma_f32 v[26:27], v[252:253], v[150:151], v[26:27] op_sel_hi:[0,1,1]
	v_pk_fma_f32 v[18:19], v[252:253], v[150:151], v[18:19] op_sel:[1,0,0] op_sel_hi:[1,1,1]
	v_pk_fma_f32 v[10:11], v[254:255], v[150:151], v[10:11] op_sel_hi:[0,1,1]
	v_pk_fma_f32 v[0:1], v[254:255], v[152:153], v[0:1] op_sel:[1,0,0] op_sel_hi:[1,1,1]
	v_pk_fma_f32 v[24:25], v[252:253], v[152:153], v[24:25] op_sel_hi:[0,1,1]
	v_pk_fma_f32 v[14:15], v[252:253], v[152:153], v[14:15] op_sel:[1,0,0] op_sel_hi:[1,1,1]
	v_pk_fma_f32 v[6:7], v[254:255], v[152:153], v[6:7] op_sel_hi:[0,1,1]
	ds_read_b128 v[252:255], v112 offset:43712
	s_waitcnt vmcnt(25)
	v_lshlrev_b32_e32 v108, 16, v154
	v_and_b32_e32 v109, 0xffff0000, v154
	v_lshlrev_b32_e32 v246, 16, v155
	v_and_b32_e32 v247, 0xffff0000, v155
	v_lshlrev_b32_e32 v154, 16, v156
	v_and_b32_e32 v155, 0xffff0000, v156
	v_lshlrev_b32_e32 v156, 16, v157
	v_and_b32_e32 v157, 0xffff0000, v157
	s_waitcnt lgkmcnt(1)
	v_pk_fma_f32 v[8:9], v[250:251], v[108:109], v[8:9] op_sel:[1,0,0] op_sel_hi:[1,1,1]
	v_pk_fma_f32 v[32:33], v[248:249], v[108:109], v[32:33] op_sel_hi:[0,1,1]
	v_pk_fma_f32 v[22:23], v[248:249], v[108:109], v[22:23] op_sel:[1,0,0] op_sel_hi:[1,1,1]
	v_pk_fma_f32 v[16:17], v[250:251], v[108:109], v[16:17] op_sel_hi:[0,1,1]
	v_pk_fma_f32 v[4:5], v[250:251], v[246:247], v[4:5] op_sel:[1,0,0] op_sel_hi:[1,1,1]
	v_pk_fma_f32 v[30:31], v[248:249], v[246:247], v[30:31] op_sel_hi:[0,1,1]
	v_pk_fma_f32 v[20:21], v[248:249], v[246:247], v[20:21] op_sel:[1,0,0] op_sel_hi:[1,1,1]
	v_pk_fma_f32 v[12:13], v[250:251], v[246:247], v[12:13] op_sel_hi:[0,1,1]
	v_pk_fma_f32 v[2:3], v[250:251], v[154:155], v[2:3] op_sel:[1,0,0] op_sel_hi:[1,1,1]
	v_pk_fma_f32 v[26:27], v[248:249], v[154:155], v[26:27] op_sel_hi:[0,1,1]
	v_pk_fma_f32 v[18:19], v[248:249], v[154:155], v[18:19] op_sel:[1,0,0] op_sel_hi:[1,1,1]
	v_pk_fma_f32 v[10:11], v[250:251], v[154:155], v[10:11] op_sel_hi:[0,1,1]
	v_pk_fma_f32 v[0:1], v[250:251], v[156:157], v[0:1] op_sel:[1,0,0] op_sel_hi:[1,1,1]
	v_pk_fma_f32 v[24:25], v[248:249], v[156:157], v[24:25] op_sel_hi:[0,1,1]
	v_pk_fma_f32 v[14:15], v[248:249], v[156:157], v[14:15] op_sel:[1,0,0] op_sel_hi:[1,1,1]
	v_pk_fma_f32 v[6:7], v[250:251], v[156:157], v[6:7] op_sel_hi:[0,1,1]
	ds_read_b128 v[248:251], v112 offset:43776
	s_waitcnt vmcnt(24)
	v_lshlrev_b32_e32 v108, 16, v158
	v_and_b32_e32 v109, 0xffff0000, v158
	v_lshlrev_b32_e32 v246, 16, v159
	v_and_b32_e32 v247, 0xffff0000, v159
	v_lshlrev_b32_e32 v158, 16, v160
	v_and_b32_e32 v159, 0xffff0000, v160
	v_lshlrev_b32_e32 v160, 16, v161
	v_and_b32_e32 v161, 0xffff0000, v161
	s_waitcnt lgkmcnt(1)
	v_pk_fma_f32 v[8:9], v[254:255], v[108:109], v[8:9] op_sel:[1,0,0] op_sel_hi:[1,1,1]
	v_pk_fma_f32 v[32:33], v[252:253], v[108:109], v[32:33] op_sel_hi:[0,1,1]
	v_pk_fma_f32 v[22:23], v[252:253], v[108:109], v[22:23] op_sel:[1,0,0] op_sel_hi:[1,1,1]
	v_pk_fma_f32 v[16:17], v[254:255], v[108:109], v[16:17] op_sel_hi:[0,1,1]
	v_pk_fma_f32 v[4:5], v[254:255], v[246:247], v[4:5] op_sel:[1,0,0] op_sel_hi:[1,1,1]
	v_pk_fma_f32 v[30:31], v[252:253], v[246:247], v[30:31] op_sel_hi:[0,1,1]
	v_pk_fma_f32 v[20:21], v[252:253], v[246:247], v[20:21] op_sel:[1,0,0] op_sel_hi:[1,1,1]
	v_pk_fma_f32 v[12:13], v[254:255], v[246:247], v[12:13] op_sel_hi:[0,1,1]
	v_pk_fma_f32 v[2:3], v[254:255], v[158:159], v[2:3] op_sel:[1,0,0] op_sel_hi:[1,1,1]
	v_pk_fma_f32 v[26:27], v[252:253], v[158:159], v[26:27] op_sel_hi:[0,1,1]
	v_pk_fma_f32 v[18:19], v[252:253], v[158:159], v[18:19] op_sel:[1,0,0] op_sel_hi:[1,1,1]
	v_pk_fma_f32 v[10:11], v[254:255], v[158:159], v[10:11] op_sel_hi:[0,1,1]
	v_pk_fma_f32 v[0:1], v[254:255], v[160:161], v[0:1] op_sel:[1,0,0] op_sel_hi:[1,1,1]
	v_pk_fma_f32 v[24:25], v[252:253], v[160:161], v[24:25] op_sel_hi:[0,1,1]
	v_pk_fma_f32 v[14:15], v[252:253], v[160:161], v[14:15] op_sel:[1,0,0] op_sel_hi:[1,1,1]
	v_pk_fma_f32 v[6:7], v[254:255], v[160:161], v[6:7] op_sel_hi:[0,1,1]
	ds_read_b128 v[252:255], v112 offset:43840
	s_waitcnt vmcnt(23)
	v_lshlrev_b32_e32 v108, 16, v162
	v_and_b32_e32 v109, 0xffff0000, v162
	v_lshlrev_b32_e32 v246, 16, v163
	v_and_b32_e32 v247, 0xffff0000, v163
	v_lshlrev_b32_e32 v162, 16, v164
	v_and_b32_e32 v163, 0xffff0000, v164
	v_lshlrev_b32_e32 v164, 16, v165
	v_and_b32_e32 v165, 0xffff0000, v165
	s_waitcnt lgkmcnt(1)
	v_pk_fma_f32 v[8:9], v[250:251], v[108:109], v[8:9] op_sel:[1,0,0] op_sel_hi:[1,1,1]
	v_pk_fma_f32 v[32:33], v[248:249], v[108:109], v[32:33] op_sel_hi:[0,1,1]
	v_pk_fma_f32 v[22:23], v[248:249], v[108:109], v[22:23] op_sel:[1,0,0] op_sel_hi:[1,1,1]
	v_pk_fma_f32 v[16:17], v[250:251], v[108:109], v[16:17] op_sel_hi:[0,1,1]
	v_pk_fma_f32 v[4:5], v[250:251], v[246:247], v[4:5] op_sel:[1,0,0] op_sel_hi:[1,1,1]
	v_pk_fma_f32 v[30:31], v[248:249], v[246:247], v[30:31] op_sel_hi:[0,1,1]
	v_pk_fma_f32 v[20:21], v[248:249], v[246:247], v[20:21] op_sel:[1,0,0] op_sel_hi:[1,1,1]
	v_pk_fma_f32 v[12:13], v[250:251], v[246:247], v[12:13] op_sel_hi:[0,1,1]
	v_pk_fma_f32 v[2:3], v[250:251], v[162:163], v[2:3] op_sel:[1,0,0] op_sel_hi:[1,1,1]
	v_pk_fma_f32 v[26:27], v[248:249], v[162:163], v[26:27] op_sel_hi:[0,1,1]
	v_pk_fma_f32 v[18:19], v[248:249], v[162:163], v[18:19] op_sel:[1,0,0] op_sel_hi:[1,1,1]
	v_pk_fma_f32 v[10:11], v[250:251], v[162:163], v[10:11] op_sel_hi:[0,1,1]
	v_pk_fma_f32 v[0:1], v[250:251], v[164:165], v[0:1] op_sel:[1,0,0] op_sel_hi:[1,1,1]
	v_pk_fma_f32 v[24:25], v[248:249], v[164:165], v[24:25] op_sel_hi:[0,1,1]
	v_pk_fma_f32 v[14:15], v[248:249], v[164:165], v[14:15] op_sel:[1,0,0] op_sel_hi:[1,1,1]
	v_pk_fma_f32 v[6:7], v[250:251], v[164:165], v[6:7] op_sel_hi:[0,1,1]
	ds_read_b128 v[248:251], v112 offset:43904
	s_waitcnt vmcnt(22)
	v_lshlrev_b32_e32 v108, 16, v166
	v_and_b32_e32 v109, 0xffff0000, v166
	v_lshlrev_b32_e32 v246, 16, v167
	v_and_b32_e32 v247, 0xffff0000, v167
	v_lshlrev_b32_e32 v166, 16, v168
	v_and_b32_e32 v167, 0xffff0000, v168
	v_lshlrev_b32_e32 v168, 16, v169
	v_and_b32_e32 v169, 0xffff0000, v169
	s_waitcnt lgkmcnt(1)
	v_pk_fma_f32 v[8:9], v[254:255], v[108:109], v[8:9] op_sel:[1,0,0] op_sel_hi:[1,1,1]
	v_pk_fma_f32 v[32:33], v[252:253], v[108:109], v[32:33] op_sel_hi:[0,1,1]
	v_pk_fma_f32 v[22:23], v[252:253], v[108:109], v[22:23] op_sel:[1,0,0] op_sel_hi:[1,1,1]
	v_pk_fma_f32 v[16:17], v[254:255], v[108:109], v[16:17] op_sel_hi:[0,1,1]
	v_pk_fma_f32 v[4:5], v[254:255], v[246:247], v[4:5] op_sel:[1,0,0] op_sel_hi:[1,1,1]
	v_pk_fma_f32 v[30:31], v[252:253], v[246:247], v[30:31] op_sel_hi:[0,1,1]
	v_pk_fma_f32 v[20:21], v[252:253], v[246:247], v[20:21] op_sel:[1,0,0] op_sel_hi:[1,1,1]
	v_pk_fma_f32 v[12:13], v[254:255], v[246:247], v[12:13] op_sel_hi:[0,1,1]
	v_pk_fma_f32 v[2:3], v[254:255], v[166:167], v[2:3] op_sel:[1,0,0] op_sel_hi:[1,1,1]
	v_pk_fma_f32 v[26:27], v[252:253], v[166:167], v[26:27] op_sel_hi:[0,1,1]
	v_pk_fma_f32 v[18:19], v[252:253], v[166:167], v[18:19] op_sel:[1,0,0] op_sel_hi:[1,1,1]
	v_pk_fma_f32 v[10:11], v[254:255], v[166:167], v[10:11] op_sel_hi:[0,1,1]
	v_pk_fma_f32 v[0:1], v[254:255], v[168:169], v[0:1] op_sel:[1,0,0] op_sel_hi:[1,1,1]
	v_pk_fma_f32 v[24:25], v[252:253], v[168:169], v[24:25] op_sel_hi:[0,1,1]
	v_pk_fma_f32 v[14:15], v[252:253], v[168:169], v[14:15] op_sel:[1,0,0] op_sel_hi:[1,1,1]
	v_pk_fma_f32 v[6:7], v[254:255], v[168:169], v[6:7] op_sel_hi:[0,1,1]
	ds_read_b128 v[252:255], v112 offset:43968
	s_waitcnt vmcnt(21)
	v_lshlrev_b32_e32 v108, 16, v170
	v_and_b32_e32 v109, 0xffff0000, v170
	v_lshlrev_b32_e32 v246, 16, v171
	v_and_b32_e32 v247, 0xffff0000, v171
	v_lshlrev_b32_e32 v170, 16, v172
	v_and_b32_e32 v171, 0xffff0000, v172
	v_lshlrev_b32_e32 v172, 16, v173
	v_and_b32_e32 v173, 0xffff0000, v173
	s_waitcnt lgkmcnt(1)
	v_pk_fma_f32 v[8:9], v[250:251], v[108:109], v[8:9] op_sel:[1,0,0] op_sel_hi:[1,1,1]
	v_pk_fma_f32 v[32:33], v[248:249], v[108:109], v[32:33] op_sel_hi:[0,1,1]
	v_pk_fma_f32 v[22:23], v[248:249], v[108:109], v[22:23] op_sel:[1,0,0] op_sel_hi:[1,1,1]
	v_pk_fma_f32 v[16:17], v[250:251], v[108:109], v[16:17] op_sel_hi:[0,1,1]
	v_pk_fma_f32 v[4:5], v[250:251], v[246:247], v[4:5] op_sel:[1,0,0] op_sel_hi:[1,1,1]
	v_pk_fma_f32 v[30:31], v[248:249], v[246:247], v[30:31] op_sel_hi:[0,1,1]
	v_pk_fma_f32 v[20:21], v[248:249], v[246:247], v[20:21] op_sel:[1,0,0] op_sel_hi:[1,1,1]
	v_pk_fma_f32 v[12:13], v[250:251], v[246:247], v[12:13] op_sel_hi:[0,1,1]
	v_pk_fma_f32 v[2:3], v[250:251], v[170:171], v[2:3] op_sel:[1,0,0] op_sel_hi:[1,1,1]
	v_pk_fma_f32 v[26:27], v[248:249], v[170:171], v[26:27] op_sel_hi:[0,1,1]
	v_pk_fma_f32 v[18:19], v[248:249], v[170:171], v[18:19] op_sel:[1,0,0] op_sel_hi:[1,1,1]
	v_pk_fma_f32 v[10:11], v[250:251], v[170:171], v[10:11] op_sel_hi:[0,1,1]
	v_pk_fma_f32 v[0:1], v[250:251], v[172:173], v[0:1] op_sel:[1,0,0] op_sel_hi:[1,1,1]
	v_pk_fma_f32 v[24:25], v[248:249], v[172:173], v[24:25] op_sel_hi:[0,1,1]
	v_pk_fma_f32 v[14:15], v[248:249], v[172:173], v[14:15] op_sel:[1,0,0] op_sel_hi:[1,1,1]
	v_pk_fma_f32 v[6:7], v[250:251], v[172:173], v[6:7] op_sel_hi:[0,1,1]
	ds_read_b128 v[248:251], v112 offset:44032
	s_waitcnt vmcnt(20)
	v_lshlrev_b32_e32 v108, 16, v174
	v_and_b32_e32 v109, 0xffff0000, v174
	v_lshlrev_b32_e32 v246, 16, v175
	v_and_b32_e32 v247, 0xffff0000, v175
	v_lshlrev_b32_e32 v174, 16, v176
	v_and_b32_e32 v175, 0xffff0000, v176
	v_lshlrev_b32_e32 v176, 16, v177
	v_and_b32_e32 v177, 0xffff0000, v177
	s_waitcnt lgkmcnt(1)
	v_pk_fma_f32 v[8:9], v[254:255], v[108:109], v[8:9] op_sel:[1,0,0] op_sel_hi:[1,1,1]
	v_pk_fma_f32 v[32:33], v[252:253], v[108:109], v[32:33] op_sel_hi:[0,1,1]
	v_pk_fma_f32 v[22:23], v[252:253], v[108:109], v[22:23] op_sel:[1,0,0] op_sel_hi:[1,1,1]
	v_pk_fma_f32 v[16:17], v[254:255], v[108:109], v[16:17] op_sel_hi:[0,1,1]
	v_pk_fma_f32 v[4:5], v[254:255], v[246:247], v[4:5] op_sel:[1,0,0] op_sel_hi:[1,1,1]
	v_pk_fma_f32 v[30:31], v[252:253], v[246:247], v[30:31] op_sel_hi:[0,1,1]
	v_pk_fma_f32 v[20:21], v[252:253], v[246:247], v[20:21] op_sel:[1,0,0] op_sel_hi:[1,1,1]
	v_pk_fma_f32 v[12:13], v[254:255], v[246:247], v[12:13] op_sel_hi:[0,1,1]
	v_pk_fma_f32 v[2:3], v[254:255], v[174:175], v[2:3] op_sel:[1,0,0] op_sel_hi:[1,1,1]
	v_pk_fma_f32 v[26:27], v[252:253], v[174:175], v[26:27] op_sel_hi:[0,1,1]
	v_pk_fma_f32 v[18:19], v[252:253], v[174:175], v[18:19] op_sel:[1,0,0] op_sel_hi:[1,1,1]
	v_pk_fma_f32 v[10:11], v[254:255], v[174:175], v[10:11] op_sel_hi:[0,1,1]
	v_pk_fma_f32 v[0:1], v[254:255], v[176:177], v[0:1] op_sel:[1,0,0] op_sel_hi:[1,1,1]
	v_pk_fma_f32 v[24:25], v[252:253], v[176:177], v[24:25] op_sel_hi:[0,1,1]
	v_pk_fma_f32 v[14:15], v[252:253], v[176:177], v[14:15] op_sel:[1,0,0] op_sel_hi:[1,1,1]
	v_pk_fma_f32 v[6:7], v[254:255], v[176:177], v[6:7] op_sel_hi:[0,1,1]
	ds_read_b128 v[252:255], v112 offset:44096
	s_waitcnt vmcnt(19)
	v_lshlrev_b32_e32 v108, 16, v178
	v_and_b32_e32 v109, 0xffff0000, v178
	v_lshlrev_b32_e32 v246, 16, v179
	v_and_b32_e32 v247, 0xffff0000, v179
	v_lshlrev_b32_e32 v178, 16, v180
	v_and_b32_e32 v179, 0xffff0000, v180
	v_lshlrev_b32_e32 v180, 16, v181
	v_and_b32_e32 v181, 0xffff0000, v181
	s_waitcnt lgkmcnt(1)
	v_pk_fma_f32 v[8:9], v[250:251], v[108:109], v[8:9] op_sel:[1,0,0] op_sel_hi:[1,1,1]
	v_pk_fma_f32 v[32:33], v[248:249], v[108:109], v[32:33] op_sel_hi:[0,1,1]
	v_pk_fma_f32 v[22:23], v[248:249], v[108:109], v[22:23] op_sel:[1,0,0] op_sel_hi:[1,1,1]
	v_pk_fma_f32 v[16:17], v[250:251], v[108:109], v[16:17] op_sel_hi:[0,1,1]
	v_pk_fma_f32 v[4:5], v[250:251], v[246:247], v[4:5] op_sel:[1,0,0] op_sel_hi:[1,1,1]
	v_pk_fma_f32 v[30:31], v[248:249], v[246:247], v[30:31] op_sel_hi:[0,1,1]
	v_pk_fma_f32 v[20:21], v[248:249], v[246:247], v[20:21] op_sel:[1,0,0] op_sel_hi:[1,1,1]
	v_pk_fma_f32 v[12:13], v[250:251], v[246:247], v[12:13] op_sel_hi:[0,1,1]
	v_pk_fma_f32 v[2:3], v[250:251], v[178:179], v[2:3] op_sel:[1,0,0] op_sel_hi:[1,1,1]
	v_pk_fma_f32 v[26:27], v[248:249], v[178:179], v[26:27] op_sel_hi:[0,1,1]
	v_pk_fma_f32 v[18:19], v[248:249], v[178:179], v[18:19] op_sel:[1,0,0] op_sel_hi:[1,1,1]
	v_pk_fma_f32 v[10:11], v[250:251], v[178:179], v[10:11] op_sel_hi:[0,1,1]
	v_pk_fma_f32 v[0:1], v[250:251], v[180:181], v[0:1] op_sel:[1,0,0] op_sel_hi:[1,1,1]
	v_pk_fma_f32 v[24:25], v[248:249], v[180:181], v[24:25] op_sel_hi:[0,1,1]
	v_pk_fma_f32 v[14:15], v[248:249], v[180:181], v[14:15] op_sel:[1,0,0] op_sel_hi:[1,1,1]
	v_pk_fma_f32 v[6:7], v[250:251], v[180:181], v[6:7] op_sel_hi:[0,1,1]
	ds_read_b128 v[248:251], v112 offset:44160
	s_waitcnt vmcnt(18)
	v_lshlrev_b32_e32 v108, 16, v182
	v_and_b32_e32 v109, 0xffff0000, v182
	v_lshlrev_b32_e32 v246, 16, v183
	v_and_b32_e32 v247, 0xffff0000, v183
	v_lshlrev_b32_e32 v182, 16, v184
	v_and_b32_e32 v183, 0xffff0000, v184
	v_lshlrev_b32_e32 v184, 16, v185
	v_and_b32_e32 v185, 0xffff0000, v185
	s_waitcnt lgkmcnt(1)
	v_pk_fma_f32 v[8:9], v[254:255], v[108:109], v[8:9] op_sel:[1,0,0] op_sel_hi:[1,1,1]
	v_pk_fma_f32 v[32:33], v[252:253], v[108:109], v[32:33] op_sel_hi:[0,1,1]
	v_pk_fma_f32 v[22:23], v[252:253], v[108:109], v[22:23] op_sel:[1,0,0] op_sel_hi:[1,1,1]
	v_pk_fma_f32 v[16:17], v[254:255], v[108:109], v[16:17] op_sel_hi:[0,1,1]
	v_pk_fma_f32 v[4:5], v[254:255], v[246:247], v[4:5] op_sel:[1,0,0] op_sel_hi:[1,1,1]
	v_pk_fma_f32 v[30:31], v[252:253], v[246:247], v[30:31] op_sel_hi:[0,1,1]
	v_pk_fma_f32 v[20:21], v[252:253], v[246:247], v[20:21] op_sel:[1,0,0] op_sel_hi:[1,1,1]
	v_pk_fma_f32 v[12:13], v[254:255], v[246:247], v[12:13] op_sel_hi:[0,1,1]
	v_pk_fma_f32 v[2:3], v[254:255], v[182:183], v[2:3] op_sel:[1,0,0] op_sel_hi:[1,1,1]
	v_pk_fma_f32 v[26:27], v[252:253], v[182:183], v[26:27] op_sel_hi:[0,1,1]
	v_pk_fma_f32 v[18:19], v[252:253], v[182:183], v[18:19] op_sel:[1,0,0] op_sel_hi:[1,1,1]
	v_pk_fma_f32 v[10:11], v[254:255], v[182:183], v[10:11] op_sel_hi:[0,1,1]
	v_pk_fma_f32 v[0:1], v[254:255], v[184:185], v[0:1] op_sel:[1,0,0] op_sel_hi:[1,1,1]
	v_pk_fma_f32 v[24:25], v[252:253], v[184:185], v[24:25] op_sel_hi:[0,1,1]
	v_pk_fma_f32 v[14:15], v[252:253], v[184:185], v[14:15] op_sel:[1,0,0] op_sel_hi:[1,1,1]
	v_pk_fma_f32 v[6:7], v[254:255], v[184:185], v[6:7] op_sel_hi:[0,1,1]
	ds_read_b128 v[252:255], v112 offset:44224
	s_waitcnt vmcnt(17)
	v_lshlrev_b32_e32 v108, 16, v186
	v_and_b32_e32 v109, 0xffff0000, v186
	v_lshlrev_b32_e32 v246, 16, v187
	v_and_b32_e32 v247, 0xffff0000, v187
	v_lshlrev_b32_e32 v186, 16, v188
	v_and_b32_e32 v187, 0xffff0000, v188
	v_lshlrev_b32_e32 v188, 16, v189
	v_and_b32_e32 v189, 0xffff0000, v189
	s_waitcnt lgkmcnt(1)
	v_pk_fma_f32 v[8:9], v[250:251], v[108:109], v[8:9] op_sel:[1,0,0] op_sel_hi:[1,1,1]
	v_pk_fma_f32 v[32:33], v[248:249], v[108:109], v[32:33] op_sel_hi:[0,1,1]
	v_pk_fma_f32 v[22:23], v[248:249], v[108:109], v[22:23] op_sel:[1,0,0] op_sel_hi:[1,1,1]
	v_pk_fma_f32 v[16:17], v[250:251], v[108:109], v[16:17] op_sel_hi:[0,1,1]
	v_pk_fma_f32 v[4:5], v[250:251], v[246:247], v[4:5] op_sel:[1,0,0] op_sel_hi:[1,1,1]
	v_pk_fma_f32 v[30:31], v[248:249], v[246:247], v[30:31] op_sel_hi:[0,1,1]
	v_pk_fma_f32 v[20:21], v[248:249], v[246:247], v[20:21] op_sel:[1,0,0] op_sel_hi:[1,1,1]
	v_pk_fma_f32 v[12:13], v[250:251], v[246:247], v[12:13] op_sel_hi:[0,1,1]
	v_pk_fma_f32 v[2:3], v[250:251], v[186:187], v[2:3] op_sel:[1,0,0] op_sel_hi:[1,1,1]
	v_pk_fma_f32 v[26:27], v[248:249], v[186:187], v[26:27] op_sel_hi:[0,1,1]
	v_pk_fma_f32 v[18:19], v[248:249], v[186:187], v[18:19] op_sel:[1,0,0] op_sel_hi:[1,1,1]
	v_pk_fma_f32 v[10:11], v[250:251], v[186:187], v[10:11] op_sel_hi:[0,1,1]
	v_pk_fma_f32 v[0:1], v[250:251], v[188:189], v[0:1] op_sel:[1,0,0] op_sel_hi:[1,1,1]
	v_pk_fma_f32 v[24:25], v[248:249], v[188:189], v[24:25] op_sel_hi:[0,1,1]
	v_pk_fma_f32 v[14:15], v[248:249], v[188:189], v[14:15] op_sel:[1,0,0] op_sel_hi:[1,1,1]
	v_pk_fma_f32 v[6:7], v[250:251], v[188:189], v[6:7] op_sel_hi:[0,1,1]
	s_waitcnt vmcnt(16)
	v_lshlrev_b32_e32 v108, 16, v190
	v_and_b32_e32 v109, 0xffff0000, v190
	v_lshlrev_b32_e32 v246, 16, v191
	v_and_b32_e32 v247, 0xffff0000, v191
	v_lshlrev_b32_e32 v190, 16, v192
	v_and_b32_e32 v191, 0xffff0000, v192
	v_lshlrev_b32_e32 v192, 16, v193
	v_and_b32_e32 v193, 0xffff0000, v193
	s_waitcnt lgkmcnt(0)
	v_pk_fma_f32 v[8:9], v[254:255], v[108:109], v[8:9] op_sel:[1,0,0] op_sel_hi:[1,1,1]
	v_pk_fma_f32 v[32:33], v[252:253], v[108:109], v[32:33] op_sel_hi:[0,1,1]
	v_pk_fma_f32 v[22:23], v[252:253], v[108:109], v[22:23] op_sel:[1,0,0] op_sel_hi:[1,1,1]
	v_pk_fma_f32 v[16:17], v[254:255], v[108:109], v[16:17] op_sel_hi:[0,1,1]
	v_pk_fma_f32 v[4:5], v[254:255], v[246:247], v[4:5] op_sel:[1,0,0] op_sel_hi:[1,1,1]
	v_pk_fma_f32 v[30:31], v[252:253], v[246:247], v[30:31] op_sel_hi:[0,1,1]
	v_pk_fma_f32 v[20:21], v[252:253], v[246:247], v[20:21] op_sel:[1,0,0] op_sel_hi:[1,1,1]
	v_pk_fma_f32 v[12:13], v[254:255], v[246:247], v[12:13] op_sel_hi:[0,1,1]
	v_pk_fma_f32 v[2:3], v[254:255], v[190:191], v[2:3] op_sel:[1,0,0] op_sel_hi:[1,1,1]
	v_pk_fma_f32 v[26:27], v[252:253], v[190:191], v[26:27] op_sel_hi:[0,1,1]
	v_pk_fma_f32 v[18:19], v[252:253], v[190:191], v[18:19] op_sel:[1,0,0] op_sel_hi:[1,1,1]
	v_pk_fma_f32 v[10:11], v[254:255], v[190:191], v[10:11] op_sel_hi:[0,1,1]
	v_pk_fma_f32 v[0:1], v[254:255], v[192:193], v[0:1] op_sel:[1,0,0] op_sel_hi:[1,1,1]
	v_pk_fma_f32 v[24:25], v[252:253], v[192:193], v[24:25] op_sel_hi:[0,1,1]
	v_pk_fma_f32 v[14:15], v[252:253], v[192:193], v[14:15] op_sel:[1,0,0] op_sel_hi:[1,1,1]
	v_pk_fma_f32 v[6:7], v[254:255], v[192:193], v[6:7] op_sel_hi:[0,1,1]
	ds_read_b32 v34, v129 offset:6912
	ds_read_b32 v35, v129 offset:6928
	ds_read_b32 v36, v129 offset:6944
	ds_read_b32 v37, v129 offset:6960
	ds_read_b32 v38, v129 offset:6976
	ds_read_b32 v39, v129 offset:6992
	ds_read_b32 v40, v129 offset:7008
	ds_read_b32 v41, v129 offset:7024
	ds_read_b32 v42, v129 offset:7040
	ds_read_b32 v43, v129 offset:7056
	ds_read_b32 v44, v129 offset:7072
	ds_read_b32 v45, v129 offset:7088
	ds_read_b32 v46, v129 offset:7104
	ds_read_b32 v47, v129 offset:7120
	ds_read_b32 v48, v129 offset:7136
	ds_read_b32 v49, v129 offset:7152
	s_waitcnt lgkmcnt(15)
	v_lshl_add_u32 v34, v34, 9, v110
	global_load_dwordx4 v[130:133], v34, s[8:9]
	s_waitcnt lgkmcnt(14)
	v_lshl_add_u32 v35, v35, 9, v110
	global_load_dwordx4 v[134:137], v35, s[8:9]
	s_waitcnt lgkmcnt(13)
	v_lshl_add_u32 v36, v36, 9, v110
	global_load_dwordx4 v[138:141], v36, s[8:9]
	s_waitcnt lgkmcnt(12)
	v_lshl_add_u32 v37, v37, 9, v110
	global_load_dwordx4 v[142:145], v37, s[8:9]
	s_waitcnt lgkmcnt(11)
	v_lshl_add_u32 v38, v38, 9, v110
	global_load_dwordx4 v[146:149], v38, s[8:9]
	s_waitcnt lgkmcnt(10)
	v_lshl_add_u32 v39, v39, 9, v110
	global_load_dwordx4 v[150:153], v39, s[8:9]
	s_waitcnt lgkmcnt(9)
	v_lshl_add_u32 v40, v40, 9, v110
	global_load_dwordx4 v[154:157], v40, s[8:9]
	s_waitcnt lgkmcnt(8)
	v_lshl_add_u32 v41, v41, 9, v110
	global_load_dwordx4 v[158:161], v41, s[8:9]
	s_waitcnt lgkmcnt(7)
	v_lshl_add_u32 v42, v42, 9, v110
	global_load_dwordx4 v[162:165], v42, s[8:9]
	s_waitcnt lgkmcnt(6)
	v_lshl_add_u32 v43, v43, 9, v110
	global_load_dwordx4 v[166:169], v43, s[8:9]
	s_waitcnt lgkmcnt(5)
	v_lshl_add_u32 v44, v44, 9, v110
	global_load_dwordx4 v[170:173], v44, s[8:9]
	s_waitcnt lgkmcnt(4)
	v_lshl_add_u32 v45, v45, 9, v110
	global_load_dwordx4 v[174:177], v45, s[8:9]
	s_waitcnt lgkmcnt(3)
	v_lshl_add_u32 v46, v46, 9, v110
	global_load_dwordx4 v[178:181], v46, s[8:9]
	s_waitcnt lgkmcnt(2)
	v_lshl_add_u32 v47, v47, 9, v110
	global_load_dwordx4 v[182:185], v47, s[8:9]
	s_waitcnt lgkmcnt(1)
	v_lshl_add_u32 v48, v48, 9, v110
	global_load_dwordx4 v[186:189], v48, s[8:9]
	s_waitcnt lgkmcnt(0)
	v_lshl_add_u32 v49, v49, 9, v110
	global_load_dwordx4 v[190:193], v49, s[8:9]
	ds_read_b128 v[248:251], v112 offset:44288
	ds_read_b128 v[252:255], v112 offset:44352
	s_waitcnt vmcnt(31)
	v_lshlrev_b32_e32 v108, 16, v210
	v_and_b32_e32 v109, 0xffff0000, v210
	v_lshlrev_b32_e32 v246, 16, v211
	v_and_b32_e32 v247, 0xffff0000, v211
	v_lshlrev_b32_e32 v210, 16, v212
	v_and_b32_e32 v211, 0xffff0000, v212
	v_lshlrev_b32_e32 v212, 16, v213
	v_and_b32_e32 v213, 0xffff0000, v213
	s_waitcnt lgkmcnt(1)
	v_pk_fma_f32 v[8:9], v[250:251], v[108:109], v[8:9] op_sel:[1,0,0] op_sel_hi:[1,1,1]
	v_pk_fma_f32 v[32:33], v[248:249], v[108:109], v[32:33] op_sel_hi:[0,1,1]
	v_pk_fma_f32 v[22:23], v[248:249], v[108:109], v[22:23] op_sel:[1,0,0] op_sel_hi:[1,1,1]
	v_pk_fma_f32 v[16:17], v[250:251], v[108:109], v[16:17] op_sel_hi:[0,1,1]
	v_pk_fma_f32 v[4:5], v[250:251], v[246:247], v[4:5] op_sel:[1,0,0] op_sel_hi:[1,1,1]
	v_pk_fma_f32 v[30:31], v[248:249], v[246:247], v[30:31] op_sel_hi:[0,1,1]
	v_pk_fma_f32 v[20:21], v[248:249], v[246:247], v[20:21] op_sel:[1,0,0] op_sel_hi:[1,1,1]
	v_pk_fma_f32 v[12:13], v[250:251], v[246:247], v[12:13] op_sel_hi:[0,1,1]
	v_pk_fma_f32 v[2:3], v[250:251], v[210:211], v[2:3] op_sel:[1,0,0] op_sel_hi:[1,1,1]
	v_pk_fma_f32 v[26:27], v[248:249], v[210:211], v[26:27] op_sel_hi:[0,1,1]
	v_pk_fma_f32 v[18:19], v[248:249], v[210:211], v[18:19] op_sel:[1,0,0] op_sel_hi:[1,1,1]
	v_pk_fma_f32 v[10:11], v[250:251], v[210:211], v[10:11] op_sel_hi:[0,1,1]
	v_pk_fma_f32 v[0:1], v[250:251], v[212:213], v[0:1] op_sel:[1,0,0] op_sel_hi:[1,1,1]
	v_pk_fma_f32 v[24:25], v[248:249], v[212:213], v[24:25] op_sel_hi:[0,1,1]
	v_pk_fma_f32 v[14:15], v[248:249], v[212:213], v[14:15] op_sel:[1,0,0] op_sel_hi:[1,1,1]
	v_pk_fma_f32 v[6:7], v[250:251], v[212:213], v[6:7] op_sel_hi:[0,1,1]
	ds_read_b128 v[248:251], v112 offset:44416
	s_waitcnt vmcnt(30)
	v_lshlrev_b32_e32 v108, 16, v214
	v_and_b32_e32 v109, 0xffff0000, v214
	v_lshlrev_b32_e32 v246, 16, v215
	v_and_b32_e32 v247, 0xffff0000, v215
	v_lshlrev_b32_e32 v214, 16, v216
	v_and_b32_e32 v215, 0xffff0000, v216
	v_lshlrev_b32_e32 v216, 16, v217
	v_and_b32_e32 v217, 0xffff0000, v217
	s_waitcnt lgkmcnt(1)
	v_pk_fma_f32 v[8:9], v[254:255], v[108:109], v[8:9] op_sel:[1,0,0] op_sel_hi:[1,1,1]
	v_pk_fma_f32 v[32:33], v[252:253], v[108:109], v[32:33] op_sel_hi:[0,1,1]
	v_pk_fma_f32 v[22:23], v[252:253], v[108:109], v[22:23] op_sel:[1,0,0] op_sel_hi:[1,1,1]
	v_pk_fma_f32 v[16:17], v[254:255], v[108:109], v[16:17] op_sel_hi:[0,1,1]
	v_pk_fma_f32 v[4:5], v[254:255], v[246:247], v[4:5] op_sel:[1,0,0] op_sel_hi:[1,1,1]
	v_pk_fma_f32 v[30:31], v[252:253], v[246:247], v[30:31] op_sel_hi:[0,1,1]
	v_pk_fma_f32 v[20:21], v[252:253], v[246:247], v[20:21] op_sel:[1,0,0] op_sel_hi:[1,1,1]
	v_pk_fma_f32 v[12:13], v[254:255], v[246:247], v[12:13] op_sel_hi:[0,1,1]
	v_pk_fma_f32 v[2:3], v[254:255], v[214:215], v[2:3] op_sel:[1,0,0] op_sel_hi:[1,1,1]
	v_pk_fma_f32 v[26:27], v[252:253], v[214:215], v[26:27] op_sel_hi:[0,1,1]
	v_pk_fma_f32 v[18:19], v[252:253], v[214:215], v[18:19] op_sel:[1,0,0] op_sel_hi:[1,1,1]
	v_pk_fma_f32 v[10:11], v[254:255], v[214:215], v[10:11] op_sel_hi:[0,1,1]
	v_pk_fma_f32 v[0:1], v[254:255], v[216:217], v[0:1] op_sel:[1,0,0] op_sel_hi:[1,1,1]
	v_pk_fma_f32 v[24:25], v[252:253], v[216:217], v[24:25] op_sel_hi:[0,1,1]
	v_pk_fma_f32 v[14:15], v[252:253], v[216:217], v[14:15] op_sel:[1,0,0] op_sel_hi:[1,1,1]
	v_pk_fma_f32 v[6:7], v[254:255], v[216:217], v[6:7] op_sel_hi:[0,1,1]
	ds_read_b128 v[252:255], v112 offset:44480
	s_waitcnt vmcnt(29)
	v_lshlrev_b32_e32 v108, 16, v218
	v_and_b32_e32 v109, 0xffff0000, v218
	v_lshlrev_b32_e32 v246, 16, v219
	v_and_b32_e32 v247, 0xffff0000, v219
	v_lshlrev_b32_e32 v218, 16, v220
	v_and_b32_e32 v219, 0xffff0000, v220
	v_lshlrev_b32_e32 v220, 16, v221
	v_and_b32_e32 v221, 0xffff0000, v221
	s_waitcnt lgkmcnt(1)
	v_pk_fma_f32 v[8:9], v[250:251], v[108:109], v[8:9] op_sel:[1,0,0] op_sel_hi:[1,1,1]
	v_pk_fma_f32 v[32:33], v[248:249], v[108:109], v[32:33] op_sel_hi:[0,1,1]
	v_pk_fma_f32 v[22:23], v[248:249], v[108:109], v[22:23] op_sel:[1,0,0] op_sel_hi:[1,1,1]
	v_pk_fma_f32 v[16:17], v[250:251], v[108:109], v[16:17] op_sel_hi:[0,1,1]
	v_pk_fma_f32 v[4:5], v[250:251], v[246:247], v[4:5] op_sel:[1,0,0] op_sel_hi:[1,1,1]
	v_pk_fma_f32 v[30:31], v[248:249], v[246:247], v[30:31] op_sel_hi:[0,1,1]
	v_pk_fma_f32 v[20:21], v[248:249], v[246:247], v[20:21] op_sel:[1,0,0] op_sel_hi:[1,1,1]
	v_pk_fma_f32 v[12:13], v[250:251], v[246:247], v[12:13] op_sel_hi:[0,1,1]
	v_pk_fma_f32 v[2:3], v[250:251], v[218:219], v[2:3] op_sel:[1,0,0] op_sel_hi:[1,1,1]
	v_pk_fma_f32 v[26:27], v[248:249], v[218:219], v[26:27] op_sel_hi:[0,1,1]
	v_pk_fma_f32 v[18:19], v[248:249], v[218:219], v[18:19] op_sel:[1,0,0] op_sel_hi:[1,1,1]
	v_pk_fma_f32 v[10:11], v[250:251], v[218:219], v[10:11] op_sel_hi:[0,1,1]
	v_pk_fma_f32 v[0:1], v[250:251], v[220:221], v[0:1] op_sel:[1,0,0] op_sel_hi:[1,1,1]
	v_pk_fma_f32 v[24:25], v[248:249], v[220:221], v[24:25] op_sel_hi:[0,1,1]
	v_pk_fma_f32 v[14:15], v[248:249], v[220:221], v[14:15] op_sel:[1,0,0] op_sel_hi:[1,1,1]
	v_pk_fma_f32 v[6:7], v[250:251], v[220:221], v[6:7] op_sel_hi:[0,1,1]
	ds_read_b128 v[248:251], v112 offset:44544
	s_waitcnt vmcnt(28)
	v_lshlrev_b32_e32 v108, 16, v222
	v_and_b32_e32 v109, 0xffff0000, v222
	v_lshlrev_b32_e32 v246, 16, v223
	v_and_b32_e32 v247, 0xffff0000, v223
	v_lshlrev_b32_e32 v222, 16, v224
	v_and_b32_e32 v223, 0xffff0000, v224
	v_lshlrev_b32_e32 v224, 16, v225
	v_and_b32_e32 v225, 0xffff0000, v225
	s_waitcnt lgkmcnt(1)
	v_pk_fma_f32 v[8:9], v[254:255], v[108:109], v[8:9] op_sel:[1,0,0] op_sel_hi:[1,1,1]
	v_pk_fma_f32 v[32:33], v[252:253], v[108:109], v[32:33] op_sel_hi:[0,1,1]
	v_pk_fma_f32 v[22:23], v[252:253], v[108:109], v[22:23] op_sel:[1,0,0] op_sel_hi:[1,1,1]
	v_pk_fma_f32 v[16:17], v[254:255], v[108:109], v[16:17] op_sel_hi:[0,1,1]
	v_pk_fma_f32 v[4:5], v[254:255], v[246:247], v[4:5] op_sel:[1,0,0] op_sel_hi:[1,1,1]
	v_pk_fma_f32 v[30:31], v[252:253], v[246:247], v[30:31] op_sel_hi:[0,1,1]
	v_pk_fma_f32 v[20:21], v[252:253], v[246:247], v[20:21] op_sel:[1,0,0] op_sel_hi:[1,1,1]
	v_pk_fma_f32 v[12:13], v[254:255], v[246:247], v[12:13] op_sel_hi:[0,1,1]
	v_pk_fma_f32 v[2:3], v[254:255], v[222:223], v[2:3] op_sel:[1,0,0] op_sel_hi:[1,1,1]
	v_pk_fma_f32 v[26:27], v[252:253], v[222:223], v[26:27] op_sel_hi:[0,1,1]
	v_pk_fma_f32 v[18:19], v[252:253], v[222:223], v[18:19] op_sel:[1,0,0] op_sel_hi:[1,1,1]
	v_pk_fma_f32 v[10:11], v[254:255], v[222:223], v[10:11] op_sel_hi:[0,1,1]
	v_pk_fma_f32 v[0:1], v[254:255], v[224:225], v[0:1] op_sel:[1,0,0] op_sel_hi:[1,1,1]
	v_pk_fma_f32 v[24:25], v[252:253], v[224:225], v[24:25] op_sel_hi:[0,1,1]
	v_pk_fma_f32 v[14:15], v[252:253], v[224:225], v[14:15] op_sel:[1,0,0] op_sel_hi:[1,1,1]
	v_pk_fma_f32 v[6:7], v[254:255], v[224:225], v[6:7] op_sel_hi:[0,1,1]
	ds_read_b128 v[252:255], v112 offset:44608
	s_waitcnt vmcnt(27)
	v_lshlrev_b32_e32 v108, 16, v226
	v_and_b32_e32 v109, 0xffff0000, v226
	v_lshlrev_b32_e32 v246, 16, v227
	v_and_b32_e32 v247, 0xffff0000, v227
	v_lshlrev_b32_e32 v226, 16, v228
	v_and_b32_e32 v227, 0xffff0000, v228
	v_lshlrev_b32_e32 v228, 16, v229
	v_and_b32_e32 v229, 0xffff0000, v229
	s_waitcnt lgkmcnt(1)
	v_pk_fma_f32 v[8:9], v[250:251], v[108:109], v[8:9] op_sel:[1,0,0] op_sel_hi:[1,1,1]
	v_pk_fma_f32 v[32:33], v[248:249], v[108:109], v[32:33] op_sel_hi:[0,1,1]
	v_pk_fma_f32 v[22:23], v[248:249], v[108:109], v[22:23] op_sel:[1,0,0] op_sel_hi:[1,1,1]
	v_pk_fma_f32 v[16:17], v[250:251], v[108:109], v[16:17] op_sel_hi:[0,1,1]
	v_pk_fma_f32 v[4:5], v[250:251], v[246:247], v[4:5] op_sel:[1,0,0] op_sel_hi:[1,1,1]
	v_pk_fma_f32 v[30:31], v[248:249], v[246:247], v[30:31] op_sel_hi:[0,1,1]
	v_pk_fma_f32 v[20:21], v[248:249], v[246:247], v[20:21] op_sel:[1,0,0] op_sel_hi:[1,1,1]
	v_pk_fma_f32 v[12:13], v[250:251], v[246:247], v[12:13] op_sel_hi:[0,1,1]
	v_pk_fma_f32 v[2:3], v[250:251], v[226:227], v[2:3] op_sel:[1,0,0] op_sel_hi:[1,1,1]
	v_pk_fma_f32 v[26:27], v[248:249], v[226:227], v[26:27] op_sel_hi:[0,1,1]
	v_pk_fma_f32 v[18:19], v[248:249], v[226:227], v[18:19] op_sel:[1,0,0] op_sel_hi:[1,1,1]
	v_pk_fma_f32 v[10:11], v[250:251], v[226:227], v[10:11] op_sel_hi:[0,1,1]
	v_pk_fma_f32 v[0:1], v[250:251], v[228:229], v[0:1] op_sel:[1,0,0] op_sel_hi:[1,1,1]
	v_pk_fma_f32 v[24:25], v[248:249], v[228:229], v[24:25] op_sel_hi:[0,1,1]
	v_pk_fma_f32 v[14:15], v[248:249], v[228:229], v[14:15] op_sel:[1,0,0] op_sel_hi:[1,1,1]
	v_pk_fma_f32 v[6:7], v[250:251], v[228:229], v[6:7] op_sel_hi:[0,1,1]
	ds_read_b128 v[248:251], v112 offset:44672
	s_waitcnt vmcnt(26)
	v_lshlrev_b32_e32 v108, 16, v230
	v_and_b32_e32 v109, 0xffff0000, v230
	v_lshlrev_b32_e32 v246, 16, v231
	v_and_b32_e32 v247, 0xffff0000, v231
	v_lshlrev_b32_e32 v230, 16, v232
	v_and_b32_e32 v231, 0xffff0000, v232
	v_lshlrev_b32_e32 v232, 16, v233
	v_and_b32_e32 v233, 0xffff0000, v233
	s_waitcnt lgkmcnt(1)
	v_pk_fma_f32 v[8:9], v[254:255], v[108:109], v[8:9] op_sel:[1,0,0] op_sel_hi:[1,1,1]
	v_pk_fma_f32 v[32:33], v[252:253], v[108:109], v[32:33] op_sel_hi:[0,1,1]
	v_pk_fma_f32 v[22:23], v[252:253], v[108:109], v[22:23] op_sel:[1,0,0] op_sel_hi:[1,1,1]
	v_pk_fma_f32 v[16:17], v[254:255], v[108:109], v[16:17] op_sel_hi:[0,1,1]
	v_pk_fma_f32 v[4:5], v[254:255], v[246:247], v[4:5] op_sel:[1,0,0] op_sel_hi:[1,1,1]
	v_pk_fma_f32 v[30:31], v[252:253], v[246:247], v[30:31] op_sel_hi:[0,1,1]
	v_pk_fma_f32 v[20:21], v[252:253], v[246:247], v[20:21] op_sel:[1,0,0] op_sel_hi:[1,1,1]
	v_pk_fma_f32 v[12:13], v[254:255], v[246:247], v[12:13] op_sel_hi:[0,1,1]
	v_pk_fma_f32 v[2:3], v[254:255], v[230:231], v[2:3] op_sel:[1,0,0] op_sel_hi:[1,1,1]
	v_pk_fma_f32 v[26:27], v[252:253], v[230:231], v[26:27] op_sel_hi:[0,1,1]
	v_pk_fma_f32 v[18:19], v[252:253], v[230:231], v[18:19] op_sel:[1,0,0] op_sel_hi:[1,1,1]
	v_pk_fma_f32 v[10:11], v[254:255], v[230:231], v[10:11] op_sel_hi:[0,1,1]
	v_pk_fma_f32 v[0:1], v[254:255], v[232:233], v[0:1] op_sel:[1,0,0] op_sel_hi:[1,1,1]
	v_pk_fma_f32 v[24:25], v[252:253], v[232:233], v[24:25] op_sel_hi:[0,1,1]
	v_pk_fma_f32 v[14:15], v[252:253], v[232:233], v[14:15] op_sel:[1,0,0] op_sel_hi:[1,1,1]
	v_pk_fma_f32 v[6:7], v[254:255], v[232:233], v[6:7] op_sel_hi:[0,1,1]
	ds_read_b128 v[252:255], v112 offset:44736
	s_waitcnt vmcnt(25)
	v_lshlrev_b32_e32 v108, 16, v234
	v_and_b32_e32 v109, 0xffff0000, v234
	v_lshlrev_b32_e32 v246, 16, v235
	v_and_b32_e32 v247, 0xffff0000, v235
	v_lshlrev_b32_e32 v234, 16, v236
	v_and_b32_e32 v235, 0xffff0000, v236
	v_lshlrev_b32_e32 v236, 16, v237
	v_and_b32_e32 v237, 0xffff0000, v237
	s_waitcnt lgkmcnt(1)
	v_pk_fma_f32 v[8:9], v[250:251], v[108:109], v[8:9] op_sel:[1,0,0] op_sel_hi:[1,1,1]
	v_pk_fma_f32 v[32:33], v[248:249], v[108:109], v[32:33] op_sel_hi:[0,1,1]
	v_pk_fma_f32 v[22:23], v[248:249], v[108:109], v[22:23] op_sel:[1,0,0] op_sel_hi:[1,1,1]
	v_pk_fma_f32 v[16:17], v[250:251], v[108:109], v[16:17] op_sel_hi:[0,1,1]
	v_pk_fma_f32 v[4:5], v[250:251], v[246:247], v[4:5] op_sel:[1,0,0] op_sel_hi:[1,1,1]
	v_pk_fma_f32 v[30:31], v[248:249], v[246:247], v[30:31] op_sel_hi:[0,1,1]
	v_pk_fma_f32 v[20:21], v[248:249], v[246:247], v[20:21] op_sel:[1,0,0] op_sel_hi:[1,1,1]
	v_pk_fma_f32 v[12:13], v[250:251], v[246:247], v[12:13] op_sel_hi:[0,1,1]
	v_pk_fma_f32 v[2:3], v[250:251], v[234:235], v[2:3] op_sel:[1,0,0] op_sel_hi:[1,1,1]
	v_pk_fma_f32 v[26:27], v[248:249], v[234:235], v[26:27] op_sel_hi:[0,1,1]
	v_pk_fma_f32 v[18:19], v[248:249], v[234:235], v[18:19] op_sel:[1,0,0] op_sel_hi:[1,1,1]
	v_pk_fma_f32 v[10:11], v[250:251], v[234:235], v[10:11] op_sel_hi:[0,1,1]
	v_pk_fma_f32 v[0:1], v[250:251], v[236:237], v[0:1] op_sel:[1,0,0] op_sel_hi:[1,1,1]
	v_pk_fma_f32 v[24:25], v[248:249], v[236:237], v[24:25] op_sel_hi:[0,1,1]
	v_pk_fma_f32 v[14:15], v[248:249], v[236:237], v[14:15] op_sel:[1,0,0] op_sel_hi:[1,1,1]
	v_pk_fma_f32 v[6:7], v[250:251], v[236:237], v[6:7] op_sel_hi:[0,1,1]
	ds_read_b128 v[248:251], v112 offset:44800
	s_waitcnt vmcnt(24)
	v_lshlrev_b32_e32 v108, 16, v238
	v_and_b32_e32 v109, 0xffff0000, v238
	v_lshlrev_b32_e32 v246, 16, v239
	v_and_b32_e32 v247, 0xffff0000, v239
	v_lshlrev_b32_e32 v238, 16, v240
	v_and_b32_e32 v239, 0xffff0000, v240
	v_lshlrev_b32_e32 v240, 16, v241
	v_and_b32_e32 v241, 0xffff0000, v241
	s_waitcnt lgkmcnt(1)
	v_pk_fma_f32 v[8:9], v[254:255], v[108:109], v[8:9] op_sel:[1,0,0] op_sel_hi:[1,1,1]
	v_pk_fma_f32 v[32:33], v[252:253], v[108:109], v[32:33] op_sel_hi:[0,1,1]
	v_pk_fma_f32 v[22:23], v[252:253], v[108:109], v[22:23] op_sel:[1,0,0] op_sel_hi:[1,1,1]
	v_pk_fma_f32 v[16:17], v[254:255], v[108:109], v[16:17] op_sel_hi:[0,1,1]
	v_pk_fma_f32 v[4:5], v[254:255], v[246:247], v[4:5] op_sel:[1,0,0] op_sel_hi:[1,1,1]
	v_pk_fma_f32 v[30:31], v[252:253], v[246:247], v[30:31] op_sel_hi:[0,1,1]
	v_pk_fma_f32 v[20:21], v[252:253], v[246:247], v[20:21] op_sel:[1,0,0] op_sel_hi:[1,1,1]
	v_pk_fma_f32 v[12:13], v[254:255], v[246:247], v[12:13] op_sel_hi:[0,1,1]
	v_pk_fma_f32 v[2:3], v[254:255], v[238:239], v[2:3] op_sel:[1,0,0] op_sel_hi:[1,1,1]
	v_pk_fma_f32 v[26:27], v[252:253], v[238:239], v[26:27] op_sel_hi:[0,1,1]
	v_pk_fma_f32 v[18:19], v[252:253], v[238:239], v[18:19] op_sel:[1,0,0] op_sel_hi:[1,1,1]
	v_pk_fma_f32 v[10:11], v[254:255], v[238:239], v[10:11] op_sel_hi:[0,1,1]
	v_pk_fma_f32 v[0:1], v[254:255], v[240:241], v[0:1] op_sel:[1,0,0] op_sel_hi:[1,1,1]
	v_pk_fma_f32 v[24:25], v[252:253], v[240:241], v[24:25] op_sel_hi:[0,1,1]
	v_pk_fma_f32 v[14:15], v[252:253], v[240:241], v[14:15] op_sel:[1,0,0] op_sel_hi:[1,1,1]
	v_pk_fma_f32 v[6:7], v[254:255], v[240:241], v[6:7] op_sel_hi:[0,1,1]
	ds_read_b128 v[252:255], v112 offset:44864
	s_waitcnt vmcnt(23)
	v_lshlrev_b32_e32 v108, 16, v70
	v_and_b32_e32 v109, 0xffff0000, v70
	v_lshlrev_b32_e32 v246, 16, v71
	v_and_b32_e32 v247, 0xffff0000, v71
	v_lshlrev_b32_e32 v70, 16, v72
	v_and_b32_e32 v71, 0xffff0000, v72
	v_lshlrev_b32_e32 v72, 16, v73
	v_and_b32_e32 v73, 0xffff0000, v73
	s_waitcnt lgkmcnt(1)
	v_pk_fma_f32 v[8:9], v[250:251], v[108:109], v[8:9] op_sel:[1,0,0] op_sel_hi:[1,1,1]
	v_pk_fma_f32 v[32:33], v[248:249], v[108:109], v[32:33] op_sel_hi:[0,1,1]
	v_pk_fma_f32 v[22:23], v[248:249], v[108:109], v[22:23] op_sel:[1,0,0] op_sel_hi:[1,1,1]
	v_pk_fma_f32 v[16:17], v[250:251], v[108:109], v[16:17] op_sel_hi:[0,1,1]
	v_pk_fma_f32 v[4:5], v[250:251], v[246:247], v[4:5] op_sel:[1,0,0] op_sel_hi:[1,1,1]
	v_pk_fma_f32 v[30:31], v[248:249], v[246:247], v[30:31] op_sel_hi:[0,1,1]
	v_pk_fma_f32 v[20:21], v[248:249], v[246:247], v[20:21] op_sel:[1,0,0] op_sel_hi:[1,1,1]
	v_pk_fma_f32 v[12:13], v[250:251], v[246:247], v[12:13] op_sel_hi:[0,1,1]
	v_pk_fma_f32 v[2:3], v[250:251], v[70:71], v[2:3] op_sel:[1,0,0] op_sel_hi:[1,1,1]
	v_pk_fma_f32 v[26:27], v[248:249], v[70:71], v[26:27] op_sel_hi:[0,1,1]
	v_pk_fma_f32 v[18:19], v[248:249], v[70:71], v[18:19] op_sel:[1,0,0] op_sel_hi:[1,1,1]
	v_pk_fma_f32 v[10:11], v[250:251], v[70:71], v[10:11] op_sel_hi:[0,1,1]
	v_pk_fma_f32 v[0:1], v[250:251], v[72:73], v[0:1] op_sel:[1,0,0] op_sel_hi:[1,1,1]
	v_pk_fma_f32 v[24:25], v[248:249], v[72:73], v[24:25] op_sel_hi:[0,1,1]
	v_pk_fma_f32 v[14:15], v[248:249], v[72:73], v[14:15] op_sel:[1,0,0] op_sel_hi:[1,1,1]
	v_pk_fma_f32 v[6:7], v[250:251], v[72:73], v[6:7] op_sel_hi:[0,1,1]
	ds_read_b128 v[248:251], v112 offset:44928
	s_waitcnt vmcnt(22)
	v_lshlrev_b32_e32 v108, 16, v74
	v_and_b32_e32 v109, 0xffff0000, v74
	v_lshlrev_b32_e32 v246, 16, v75
	v_and_b32_e32 v247, 0xffff0000, v75
	v_lshlrev_b32_e32 v74, 16, v76
	v_and_b32_e32 v75, 0xffff0000, v76
	v_lshlrev_b32_e32 v76, 16, v77
	v_and_b32_e32 v77, 0xffff0000, v77
	s_waitcnt lgkmcnt(1)
	v_pk_fma_f32 v[8:9], v[254:255], v[108:109], v[8:9] op_sel:[1,0,0] op_sel_hi:[1,1,1]
	v_pk_fma_f32 v[32:33], v[252:253], v[108:109], v[32:33] op_sel_hi:[0,1,1]
	v_pk_fma_f32 v[22:23], v[252:253], v[108:109], v[22:23] op_sel:[1,0,0] op_sel_hi:[1,1,1]
	v_pk_fma_f32 v[16:17], v[254:255], v[108:109], v[16:17] op_sel_hi:[0,1,1]
	v_pk_fma_f32 v[4:5], v[254:255], v[246:247], v[4:5] op_sel:[1,0,0] op_sel_hi:[1,1,1]
	v_pk_fma_f32 v[30:31], v[252:253], v[246:247], v[30:31] op_sel_hi:[0,1,1]
	v_pk_fma_f32 v[20:21], v[252:253], v[246:247], v[20:21] op_sel:[1,0,0] op_sel_hi:[1,1,1]
	v_pk_fma_f32 v[12:13], v[254:255], v[246:247], v[12:13] op_sel_hi:[0,1,1]
	v_pk_fma_f32 v[2:3], v[254:255], v[74:75], v[2:3] op_sel:[1,0,0] op_sel_hi:[1,1,1]
	v_pk_fma_f32 v[26:27], v[252:253], v[74:75], v[26:27] op_sel_hi:[0,1,1]
	v_pk_fma_f32 v[18:19], v[252:253], v[74:75], v[18:19] op_sel:[1,0,0] op_sel_hi:[1,1,1]
	v_pk_fma_f32 v[10:11], v[254:255], v[74:75], v[10:11] op_sel_hi:[0,1,1]
	v_pk_fma_f32 v[0:1], v[254:255], v[76:77], v[0:1] op_sel:[1,0,0] op_sel_hi:[1,1,1]
	v_pk_fma_f32 v[24:25], v[252:253], v[76:77], v[24:25] op_sel_hi:[0,1,1]
	v_pk_fma_f32 v[14:15], v[252:253], v[76:77], v[14:15] op_sel:[1,0,0] op_sel_hi:[1,1,1]
	v_pk_fma_f32 v[6:7], v[254:255], v[76:77], v[6:7] op_sel_hi:[0,1,1]
	ds_read_b128 v[252:255], v112 offset:44992
	s_waitcnt vmcnt(21)
	v_lshlrev_b32_e32 v108, 16, v78
	v_and_b32_e32 v109, 0xffff0000, v78
	v_lshlrev_b32_e32 v246, 16, v79
	v_and_b32_e32 v247, 0xffff0000, v79
	v_lshlrev_b32_e32 v78, 16, v80
	v_and_b32_e32 v79, 0xffff0000, v80
	v_lshlrev_b32_e32 v80, 16, v81
	v_and_b32_e32 v81, 0xffff0000, v81
	s_waitcnt lgkmcnt(1)
	v_pk_fma_f32 v[8:9], v[250:251], v[108:109], v[8:9] op_sel:[1,0,0] op_sel_hi:[1,1,1]
	v_pk_fma_f32 v[32:33], v[248:249], v[108:109], v[32:33] op_sel_hi:[0,1,1]
	v_pk_fma_f32 v[22:23], v[248:249], v[108:109], v[22:23] op_sel:[1,0,0] op_sel_hi:[1,1,1]
	v_pk_fma_f32 v[16:17], v[250:251], v[108:109], v[16:17] op_sel_hi:[0,1,1]
	v_pk_fma_f32 v[4:5], v[250:251], v[246:247], v[4:5] op_sel:[1,0,0] op_sel_hi:[1,1,1]
	v_pk_fma_f32 v[30:31], v[248:249], v[246:247], v[30:31] op_sel_hi:[0,1,1]
	v_pk_fma_f32 v[20:21], v[248:249], v[246:247], v[20:21] op_sel:[1,0,0] op_sel_hi:[1,1,1]
	v_pk_fma_f32 v[12:13], v[250:251], v[246:247], v[12:13] op_sel_hi:[0,1,1]
	v_pk_fma_f32 v[2:3], v[250:251], v[78:79], v[2:3] op_sel:[1,0,0] op_sel_hi:[1,1,1]
	v_pk_fma_f32 v[26:27], v[248:249], v[78:79], v[26:27] op_sel_hi:[0,1,1]
	v_pk_fma_f32 v[18:19], v[248:249], v[78:79], v[18:19] op_sel:[1,0,0] op_sel_hi:[1,1,1]
	v_pk_fma_f32 v[10:11], v[250:251], v[78:79], v[10:11] op_sel_hi:[0,1,1]
	v_pk_fma_f32 v[0:1], v[250:251], v[80:81], v[0:1] op_sel:[1,0,0] op_sel_hi:[1,1,1]
	v_pk_fma_f32 v[24:25], v[248:249], v[80:81], v[24:25] op_sel_hi:[0,1,1]
	v_pk_fma_f32 v[14:15], v[248:249], v[80:81], v[14:15] op_sel:[1,0,0] op_sel_hi:[1,1,1]
	v_pk_fma_f32 v[6:7], v[250:251], v[80:81], v[6:7] op_sel_hi:[0,1,1]
	ds_read_b128 v[248:251], v112 offset:45056
	s_waitcnt vmcnt(20)
	v_lshlrev_b32_e32 v108, 16, v82
	v_and_b32_e32 v109, 0xffff0000, v82
	v_lshlrev_b32_e32 v246, 16, v83
	v_and_b32_e32 v247, 0xffff0000, v83
	v_lshlrev_b32_e32 v82, 16, v84
	v_and_b32_e32 v83, 0xffff0000, v84
	v_lshlrev_b32_e32 v84, 16, v85
	v_and_b32_e32 v85, 0xffff0000, v85
	s_waitcnt lgkmcnt(1)
	v_pk_fma_f32 v[8:9], v[254:255], v[108:109], v[8:9] op_sel:[1,0,0] op_sel_hi:[1,1,1]
	v_pk_fma_f32 v[32:33], v[252:253], v[108:109], v[32:33] op_sel_hi:[0,1,1]
	v_pk_fma_f32 v[22:23], v[252:253], v[108:109], v[22:23] op_sel:[1,0,0] op_sel_hi:[1,1,1]
	v_pk_fma_f32 v[16:17], v[254:255], v[108:109], v[16:17] op_sel_hi:[0,1,1]
	v_pk_fma_f32 v[4:5], v[254:255], v[246:247], v[4:5] op_sel:[1,0,0] op_sel_hi:[1,1,1]
	v_pk_fma_f32 v[30:31], v[252:253], v[246:247], v[30:31] op_sel_hi:[0,1,1]
	v_pk_fma_f32 v[20:21], v[252:253], v[246:247], v[20:21] op_sel:[1,0,0] op_sel_hi:[1,1,1]
	v_pk_fma_f32 v[12:13], v[254:255], v[246:247], v[12:13] op_sel_hi:[0,1,1]
	v_pk_fma_f32 v[2:3], v[254:255], v[82:83], v[2:3] op_sel:[1,0,0] op_sel_hi:[1,1,1]
	v_pk_fma_f32 v[26:27], v[252:253], v[82:83], v[26:27] op_sel_hi:[0,1,1]
	v_pk_fma_f32 v[18:19], v[252:253], v[82:83], v[18:19] op_sel:[1,0,0] op_sel_hi:[1,1,1]
	v_pk_fma_f32 v[10:11], v[254:255], v[82:83], v[10:11] op_sel_hi:[0,1,1]
	v_pk_fma_f32 v[0:1], v[254:255], v[84:85], v[0:1] op_sel:[1,0,0] op_sel_hi:[1,1,1]
	v_pk_fma_f32 v[24:25], v[252:253], v[84:85], v[24:25] op_sel_hi:[0,1,1]
	v_pk_fma_f32 v[14:15], v[252:253], v[84:85], v[14:15] op_sel:[1,0,0] op_sel_hi:[1,1,1]
	v_pk_fma_f32 v[6:7], v[254:255], v[84:85], v[6:7] op_sel_hi:[0,1,1]
	ds_read_b128 v[252:255], v112 offset:45120
	s_waitcnt vmcnt(19)
	v_lshlrev_b32_e32 v108, 16, v90
	v_and_b32_e32 v109, 0xffff0000, v90
	v_lshlrev_b32_e32 v246, 16, v91
	v_and_b32_e32 v247, 0xffff0000, v91
	v_lshlrev_b32_e32 v90, 16, v92
	v_and_b32_e32 v91, 0xffff0000, v92
	v_lshlrev_b32_e32 v92, 16, v93
	v_and_b32_e32 v93, 0xffff0000, v93
	s_waitcnt lgkmcnt(1)
	v_pk_fma_f32 v[8:9], v[250:251], v[108:109], v[8:9] op_sel:[1,0,0] op_sel_hi:[1,1,1]
	v_pk_fma_f32 v[32:33], v[248:249], v[108:109], v[32:33] op_sel_hi:[0,1,1]
	v_pk_fma_f32 v[22:23], v[248:249], v[108:109], v[22:23] op_sel:[1,0,0] op_sel_hi:[1,1,1]
	v_pk_fma_f32 v[16:17], v[250:251], v[108:109], v[16:17] op_sel_hi:[0,1,1]
	v_pk_fma_f32 v[4:5], v[250:251], v[246:247], v[4:5] op_sel:[1,0,0] op_sel_hi:[1,1,1]
	v_pk_fma_f32 v[30:31], v[248:249], v[246:247], v[30:31] op_sel_hi:[0,1,1]
	v_pk_fma_f32 v[20:21], v[248:249], v[246:247], v[20:21] op_sel:[1,0,0] op_sel_hi:[1,1,1]
	v_pk_fma_f32 v[12:13], v[250:251], v[246:247], v[12:13] op_sel_hi:[0,1,1]
	v_pk_fma_f32 v[2:3], v[250:251], v[90:91], v[2:3] op_sel:[1,0,0] op_sel_hi:[1,1,1]
	v_pk_fma_f32 v[26:27], v[248:249], v[90:91], v[26:27] op_sel_hi:[0,1,1]
	v_pk_fma_f32 v[18:19], v[248:249], v[90:91], v[18:19] op_sel:[1,0,0] op_sel_hi:[1,1,1]
	v_pk_fma_f32 v[10:11], v[250:251], v[90:91], v[10:11] op_sel_hi:[0,1,1]
	v_pk_fma_f32 v[0:1], v[250:251], v[92:93], v[0:1] op_sel:[1,0,0] op_sel_hi:[1,1,1]
	v_pk_fma_f32 v[24:25], v[248:249], v[92:93], v[24:25] op_sel_hi:[0,1,1]
	v_pk_fma_f32 v[14:15], v[248:249], v[92:93], v[14:15] op_sel:[1,0,0] op_sel_hi:[1,1,1]
	v_pk_fma_f32 v[6:7], v[250:251], v[92:93], v[6:7] op_sel_hi:[0,1,1]
	ds_read_b128 v[248:251], v112 offset:45184
	s_waitcnt vmcnt(18)
	v_lshlrev_b32_e32 v108, 16, v94
	v_and_b32_e32 v109, 0xffff0000, v94
	v_lshlrev_b32_e32 v246, 16, v95
	v_and_b32_e32 v247, 0xffff0000, v95
	v_lshlrev_b32_e32 v94, 16, v96
	v_and_b32_e32 v95, 0xffff0000, v96
	v_lshlrev_b32_e32 v96, 16, v97
	v_and_b32_e32 v97, 0xffff0000, v97
	s_waitcnt lgkmcnt(1)
	v_pk_fma_f32 v[8:9], v[254:255], v[108:109], v[8:9] op_sel:[1,0,0] op_sel_hi:[1,1,1]
	v_pk_fma_f32 v[32:33], v[252:253], v[108:109], v[32:33] op_sel_hi:[0,1,1]
	v_pk_fma_f32 v[22:23], v[252:253], v[108:109], v[22:23] op_sel:[1,0,0] op_sel_hi:[1,1,1]
	v_pk_fma_f32 v[16:17], v[254:255], v[108:109], v[16:17] op_sel_hi:[0,1,1]
	v_pk_fma_f32 v[4:5], v[254:255], v[246:247], v[4:5] op_sel:[1,0,0] op_sel_hi:[1,1,1]
	v_pk_fma_f32 v[30:31], v[252:253], v[246:247], v[30:31] op_sel_hi:[0,1,1]
	v_pk_fma_f32 v[20:21], v[252:253], v[246:247], v[20:21] op_sel:[1,0,0] op_sel_hi:[1,1,1]
	v_pk_fma_f32 v[12:13], v[254:255], v[246:247], v[12:13] op_sel_hi:[0,1,1]
	v_pk_fma_f32 v[2:3], v[254:255], v[94:95], v[2:3] op_sel:[1,0,0] op_sel_hi:[1,1,1]
	v_pk_fma_f32 v[26:27], v[252:253], v[94:95], v[26:27] op_sel_hi:[0,1,1]
	v_pk_fma_f32 v[18:19], v[252:253], v[94:95], v[18:19] op_sel:[1,0,0] op_sel_hi:[1,1,1]
	v_pk_fma_f32 v[10:11], v[254:255], v[94:95], v[10:11] op_sel_hi:[0,1,1]
	v_pk_fma_f32 v[0:1], v[254:255], v[96:97], v[0:1] op_sel:[1,0,0] op_sel_hi:[1,1,1]
	v_pk_fma_f32 v[24:25], v[252:253], v[96:97], v[24:25] op_sel_hi:[0,1,1]
	v_pk_fma_f32 v[14:15], v[252:253], v[96:97], v[14:15] op_sel:[1,0,0] op_sel_hi:[1,1,1]
	v_pk_fma_f32 v[6:7], v[254:255], v[96:97], v[6:7] op_sel_hi:[0,1,1]
	ds_read_b128 v[252:255], v112 offset:45248
	s_waitcnt vmcnt(17)
	v_lshlrev_b32_e32 v108, 16, v196
	v_and_b32_e32 v109, 0xffff0000, v196
	v_lshlrev_b32_e32 v246, 16, v197
	v_and_b32_e32 v247, 0xffff0000, v197
	v_lshlrev_b32_e32 v196, 16, v198
	v_and_b32_e32 v197, 0xffff0000, v198
	v_lshlrev_b32_e32 v198, 16, v199
	v_and_b32_e32 v199, 0xffff0000, v199
	s_waitcnt lgkmcnt(1)
	v_pk_fma_f32 v[8:9], v[250:251], v[108:109], v[8:9] op_sel:[1,0,0] op_sel_hi:[1,1,1]
	v_pk_fma_f32 v[32:33], v[248:249], v[108:109], v[32:33] op_sel_hi:[0,1,1]
	v_pk_fma_f32 v[22:23], v[248:249], v[108:109], v[22:23] op_sel:[1,0,0] op_sel_hi:[1,1,1]
	v_pk_fma_f32 v[16:17], v[250:251], v[108:109], v[16:17] op_sel_hi:[0,1,1]
	v_pk_fma_f32 v[4:5], v[250:251], v[246:247], v[4:5] op_sel:[1,0,0] op_sel_hi:[1,1,1]
	v_pk_fma_f32 v[30:31], v[248:249], v[246:247], v[30:31] op_sel_hi:[0,1,1]
	v_pk_fma_f32 v[20:21], v[248:249], v[246:247], v[20:21] op_sel:[1,0,0] op_sel_hi:[1,1,1]
	v_pk_fma_f32 v[12:13], v[250:251], v[246:247], v[12:13] op_sel_hi:[0,1,1]
	v_pk_fma_f32 v[2:3], v[250:251], v[196:197], v[2:3] op_sel:[1,0,0] op_sel_hi:[1,1,1]
	v_pk_fma_f32 v[26:27], v[248:249], v[196:197], v[26:27] op_sel_hi:[0,1,1]
	v_pk_fma_f32 v[18:19], v[248:249], v[196:197], v[18:19] op_sel:[1,0,0] op_sel_hi:[1,1,1]
	v_pk_fma_f32 v[10:11], v[250:251], v[196:197], v[10:11] op_sel_hi:[0,1,1]
	v_pk_fma_f32 v[0:1], v[250:251], v[198:199], v[0:1] op_sel:[1,0,0] op_sel_hi:[1,1,1]
	v_pk_fma_f32 v[24:25], v[248:249], v[198:199], v[24:25] op_sel_hi:[0,1,1]
	v_pk_fma_f32 v[14:15], v[248:249], v[198:199], v[14:15] op_sel:[1,0,0] op_sel_hi:[1,1,1]
	v_pk_fma_f32 v[6:7], v[250:251], v[198:199], v[6:7] op_sel_hi:[0,1,1]
	s_waitcnt vmcnt(16)
	v_lshlrev_b32_e32 v108, 16, v200
	v_and_b32_e32 v109, 0xffff0000, v200
	v_lshlrev_b32_e32 v246, 16, v201
	v_and_b32_e32 v247, 0xffff0000, v201
	v_lshlrev_b32_e32 v200, 16, v202
	v_and_b32_e32 v201, 0xffff0000, v202
	v_lshlrev_b32_e32 v202, 16, v203
	v_and_b32_e32 v203, 0xffff0000, v203
	s_waitcnt lgkmcnt(0)
	v_pk_fma_f32 v[8:9], v[254:255], v[108:109], v[8:9] op_sel:[1,0,0] op_sel_hi:[1,1,1]
	v_pk_fma_f32 v[32:33], v[252:253], v[108:109], v[32:33] op_sel_hi:[0,1,1]
	v_pk_fma_f32 v[22:23], v[252:253], v[108:109], v[22:23] op_sel:[1,0,0] op_sel_hi:[1,1,1]
	v_pk_fma_f32 v[16:17], v[254:255], v[108:109], v[16:17] op_sel_hi:[0,1,1]
	v_pk_fma_f32 v[4:5], v[254:255], v[246:247], v[4:5] op_sel:[1,0,0] op_sel_hi:[1,1,1]
	v_pk_fma_f32 v[30:31], v[252:253], v[246:247], v[30:31] op_sel_hi:[0,1,1]
	v_pk_fma_f32 v[20:21], v[252:253], v[246:247], v[20:21] op_sel:[1,0,0] op_sel_hi:[1,1,1]
	v_pk_fma_f32 v[12:13], v[254:255], v[246:247], v[12:13] op_sel_hi:[0,1,1]
	v_pk_fma_f32 v[2:3], v[254:255], v[200:201], v[2:3] op_sel:[1,0,0] op_sel_hi:[1,1,1]
	v_pk_fma_f32 v[26:27], v[252:253], v[200:201], v[26:27] op_sel_hi:[0,1,1]
	v_pk_fma_f32 v[18:19], v[252:253], v[200:201], v[18:19] op_sel:[1,0,0] op_sel_hi:[1,1,1]
	v_pk_fma_f32 v[10:11], v[254:255], v[200:201], v[10:11] op_sel_hi:[0,1,1]
	v_pk_fma_f32 v[0:1], v[254:255], v[202:203], v[0:1] op_sel:[1,0,0] op_sel_hi:[1,1,1]
	v_pk_fma_f32 v[24:25], v[252:253], v[202:203], v[24:25] op_sel_hi:[0,1,1]
	v_pk_fma_f32 v[14:15], v[252:253], v[202:203], v[14:15] op_sel:[1,0,0] op_sel_hi:[1,1,1]
	v_pk_fma_f32 v[6:7], v[254:255], v[202:203], v[6:7] op_sel_hi:[0,1,1]
	ds_read_b32 v34, v129 offset:7168
	ds_read_b32 v35, v129 offset:7184
	ds_read_b32 v36, v129 offset:7200
	ds_read_b32 v37, v129 offset:7216
	ds_read_b32 v38, v129 offset:7232
	ds_read_b32 v39, v129 offset:7248
	ds_read_b32 v40, v129 offset:7264
	ds_read_b32 v41, v129 offset:7280
	ds_read_b32 v42, v129 offset:7296
	ds_read_b32 v43, v129 offset:7312
	ds_read_b32 v44, v129 offset:7328
	ds_read_b32 v45, v129 offset:7344
	ds_read_b32 v46, v129 offset:7360
	ds_read_b32 v47, v129 offset:7376
	ds_read_b32 v48, v129 offset:7392
	ds_read_b32 v49, v129 offset:7408
	s_waitcnt lgkmcnt(15)
	v_lshl_add_u32 v34, v34, 9, v110
	global_load_dwordx4 v[210:213], v34, s[8:9]
	s_waitcnt lgkmcnt(14)
	v_lshl_add_u32 v35, v35, 9, v110
	global_load_dwordx4 v[214:217], v35, s[8:9]
	s_waitcnt lgkmcnt(13)
	v_lshl_add_u32 v36, v36, 9, v110
	global_load_dwordx4 v[218:221], v36, s[8:9]
	s_waitcnt lgkmcnt(12)
	v_lshl_add_u32 v37, v37, 9, v110
	global_load_dwordx4 v[222:225], v37, s[8:9]
	s_waitcnt lgkmcnt(11)
	v_lshl_add_u32 v38, v38, 9, v110
	global_load_dwordx4 v[226:229], v38, s[8:9]
	s_waitcnt lgkmcnt(10)
	v_lshl_add_u32 v39, v39, 9, v110
	global_load_dwordx4 v[230:233], v39, s[8:9]
	s_waitcnt lgkmcnt(9)
	v_lshl_add_u32 v40, v40, 9, v110
	global_load_dwordx4 v[234:237], v40, s[8:9]
	s_waitcnt lgkmcnt(8)
	v_lshl_add_u32 v41, v41, 9, v110
	global_load_dwordx4 v[238:241], v41, s[8:9]
	s_waitcnt lgkmcnt(7)
	v_lshl_add_u32 v42, v42, 9, v110
	global_load_dwordx4 v[70:73], v42, s[8:9]
	s_waitcnt lgkmcnt(6)
	v_lshl_add_u32 v43, v43, 9, v110
	global_load_dwordx4 v[74:77], v43, s[8:9]
	s_waitcnt lgkmcnt(5)
	v_lshl_add_u32 v44, v44, 9, v110
	global_load_dwordx4 v[78:81], v44, s[8:9]
	s_waitcnt lgkmcnt(4)
	v_lshl_add_u32 v45, v45, 9, v110
	global_load_dwordx4 v[82:85], v45, s[8:9]
	s_waitcnt lgkmcnt(3)
	v_lshl_add_u32 v46, v46, 9, v110
	global_load_dwordx4 v[90:93], v46, s[8:9]
	s_waitcnt lgkmcnt(2)
	v_lshl_add_u32 v47, v47, 9, v110
	global_load_dwordx4 v[94:97], v47, s[8:9]
	s_waitcnt lgkmcnt(1)
	v_lshl_add_u32 v48, v48, 9, v110
	global_load_dwordx4 v[196:199], v48, s[8:9]
	s_waitcnt lgkmcnt(0)
	v_lshl_add_u32 v49, v49, 9, v110
	global_load_dwordx4 v[200:203], v49, s[8:9]
	ds_read_b128 v[248:251], v112 offset:45312
	ds_read_b128 v[252:255], v112 offset:45376
	s_waitcnt vmcnt(31)
	v_lshlrev_b32_e32 v108, 16, v130
	v_and_b32_e32 v109, 0xffff0000, v130
	v_lshlrev_b32_e32 v246, 16, v131
	v_and_b32_e32 v247, 0xffff0000, v131
	v_lshlrev_b32_e32 v130, 16, v132
	v_and_b32_e32 v131, 0xffff0000, v132
	v_lshlrev_b32_e32 v132, 16, v133
	v_and_b32_e32 v133, 0xffff0000, v133
	s_waitcnt lgkmcnt(1)
	v_pk_fma_f32 v[8:9], v[250:251], v[108:109], v[8:9] op_sel:[1,0,0] op_sel_hi:[1,1,1]
	v_pk_fma_f32 v[32:33], v[248:249], v[108:109], v[32:33] op_sel_hi:[0,1,1]
	v_pk_fma_f32 v[22:23], v[248:249], v[108:109], v[22:23] op_sel:[1,0,0] op_sel_hi:[1,1,1]
	v_pk_fma_f32 v[16:17], v[250:251], v[108:109], v[16:17] op_sel_hi:[0,1,1]
	v_pk_fma_f32 v[4:5], v[250:251], v[246:247], v[4:5] op_sel:[1,0,0] op_sel_hi:[1,1,1]
	v_pk_fma_f32 v[30:31], v[248:249], v[246:247], v[30:31] op_sel_hi:[0,1,1]
	v_pk_fma_f32 v[20:21], v[248:249], v[246:247], v[20:21] op_sel:[1,0,0] op_sel_hi:[1,1,1]
	v_pk_fma_f32 v[12:13], v[250:251], v[246:247], v[12:13] op_sel_hi:[0,1,1]
	v_pk_fma_f32 v[2:3], v[250:251], v[130:131], v[2:3] op_sel:[1,0,0] op_sel_hi:[1,1,1]
	v_pk_fma_f32 v[26:27], v[248:249], v[130:131], v[26:27] op_sel_hi:[0,1,1]
	v_pk_fma_f32 v[18:19], v[248:249], v[130:131], v[18:19] op_sel:[1,0,0] op_sel_hi:[1,1,1]
	v_pk_fma_f32 v[10:11], v[250:251], v[130:131], v[10:11] op_sel_hi:[0,1,1]
	v_pk_fma_f32 v[0:1], v[250:251], v[132:133], v[0:1] op_sel:[1,0,0] op_sel_hi:[1,1,1]
	v_pk_fma_f32 v[24:25], v[248:249], v[132:133], v[24:25] op_sel_hi:[0,1,1]
	v_pk_fma_f32 v[14:15], v[248:249], v[132:133], v[14:15] op_sel:[1,0,0] op_sel_hi:[1,1,1]
	v_pk_fma_f32 v[6:7], v[250:251], v[132:133], v[6:7] op_sel_hi:[0,1,1]
	ds_read_b128 v[248:251], v112 offset:45440
	s_waitcnt vmcnt(30)
	v_lshlrev_b32_e32 v108, 16, v134
	v_and_b32_e32 v109, 0xffff0000, v134
	v_lshlrev_b32_e32 v246, 16, v135
	v_and_b32_e32 v247, 0xffff0000, v135
	v_lshlrev_b32_e32 v134, 16, v136
	v_and_b32_e32 v135, 0xffff0000, v136
	v_lshlrev_b32_e32 v136, 16, v137
	v_and_b32_e32 v137, 0xffff0000, v137
	s_waitcnt lgkmcnt(1)
	v_pk_fma_f32 v[8:9], v[254:255], v[108:109], v[8:9] op_sel:[1,0,0] op_sel_hi:[1,1,1]
	v_pk_fma_f32 v[32:33], v[252:253], v[108:109], v[32:33] op_sel_hi:[0,1,1]
	v_pk_fma_f32 v[22:23], v[252:253], v[108:109], v[22:23] op_sel:[1,0,0] op_sel_hi:[1,1,1]
	v_pk_fma_f32 v[16:17], v[254:255], v[108:109], v[16:17] op_sel_hi:[0,1,1]
	v_pk_fma_f32 v[4:5], v[254:255], v[246:247], v[4:5] op_sel:[1,0,0] op_sel_hi:[1,1,1]
	v_pk_fma_f32 v[30:31], v[252:253], v[246:247], v[30:31] op_sel_hi:[0,1,1]
	v_pk_fma_f32 v[20:21], v[252:253], v[246:247], v[20:21] op_sel:[1,0,0] op_sel_hi:[1,1,1]
	v_pk_fma_f32 v[12:13], v[254:255], v[246:247], v[12:13] op_sel_hi:[0,1,1]
	v_pk_fma_f32 v[2:3], v[254:255], v[134:135], v[2:3] op_sel:[1,0,0] op_sel_hi:[1,1,1]
	v_pk_fma_f32 v[26:27], v[252:253], v[134:135], v[26:27] op_sel_hi:[0,1,1]
	v_pk_fma_f32 v[18:19], v[252:253], v[134:135], v[18:19] op_sel:[1,0,0] op_sel_hi:[1,1,1]
	v_pk_fma_f32 v[10:11], v[254:255], v[134:135], v[10:11] op_sel_hi:[0,1,1]
	v_pk_fma_f32 v[0:1], v[254:255], v[136:137], v[0:1] op_sel:[1,0,0] op_sel_hi:[1,1,1]
	v_pk_fma_f32 v[24:25], v[252:253], v[136:137], v[24:25] op_sel_hi:[0,1,1]
	v_pk_fma_f32 v[14:15], v[252:253], v[136:137], v[14:15] op_sel:[1,0,0] op_sel_hi:[1,1,1]
	v_pk_fma_f32 v[6:7], v[254:255], v[136:137], v[6:7] op_sel_hi:[0,1,1]
	ds_read_b128 v[252:255], v112 offset:45504
	s_waitcnt vmcnt(29)
	v_lshlrev_b32_e32 v108, 16, v138
	v_and_b32_e32 v109, 0xffff0000, v138
	v_lshlrev_b32_e32 v246, 16, v139
	v_and_b32_e32 v247, 0xffff0000, v139
	v_lshlrev_b32_e32 v138, 16, v140
	v_and_b32_e32 v139, 0xffff0000, v140
	v_lshlrev_b32_e32 v140, 16, v141
	v_and_b32_e32 v141, 0xffff0000, v141
	s_waitcnt lgkmcnt(1)
	v_pk_fma_f32 v[8:9], v[250:251], v[108:109], v[8:9] op_sel:[1,0,0] op_sel_hi:[1,1,1]
	v_pk_fma_f32 v[32:33], v[248:249], v[108:109], v[32:33] op_sel_hi:[0,1,1]
	v_pk_fma_f32 v[22:23], v[248:249], v[108:109], v[22:23] op_sel:[1,0,0] op_sel_hi:[1,1,1]
	v_pk_fma_f32 v[16:17], v[250:251], v[108:109], v[16:17] op_sel_hi:[0,1,1]
	v_pk_fma_f32 v[4:5], v[250:251], v[246:247], v[4:5] op_sel:[1,0,0] op_sel_hi:[1,1,1]
	v_pk_fma_f32 v[30:31], v[248:249], v[246:247], v[30:31] op_sel_hi:[0,1,1]
	v_pk_fma_f32 v[20:21], v[248:249], v[246:247], v[20:21] op_sel:[1,0,0] op_sel_hi:[1,1,1]
	v_pk_fma_f32 v[12:13], v[250:251], v[246:247], v[12:13] op_sel_hi:[0,1,1]
	v_pk_fma_f32 v[2:3], v[250:251], v[138:139], v[2:3] op_sel:[1,0,0] op_sel_hi:[1,1,1]
	v_pk_fma_f32 v[26:27], v[248:249], v[138:139], v[26:27] op_sel_hi:[0,1,1]
	v_pk_fma_f32 v[18:19], v[248:249], v[138:139], v[18:19] op_sel:[1,0,0] op_sel_hi:[1,1,1]
	v_pk_fma_f32 v[10:11], v[250:251], v[138:139], v[10:11] op_sel_hi:[0,1,1]
	v_pk_fma_f32 v[0:1], v[250:251], v[140:141], v[0:1] op_sel:[1,0,0] op_sel_hi:[1,1,1]
	v_pk_fma_f32 v[24:25], v[248:249], v[140:141], v[24:25] op_sel_hi:[0,1,1]
	v_pk_fma_f32 v[14:15], v[248:249], v[140:141], v[14:15] op_sel:[1,0,0] op_sel_hi:[1,1,1]
	v_pk_fma_f32 v[6:7], v[250:251], v[140:141], v[6:7] op_sel_hi:[0,1,1]
	ds_read_b128 v[248:251], v112 offset:45568
	s_waitcnt vmcnt(28)
	v_lshlrev_b32_e32 v108, 16, v142
	v_and_b32_e32 v109, 0xffff0000, v142
	v_lshlrev_b32_e32 v246, 16, v143
	v_and_b32_e32 v247, 0xffff0000, v143
	v_lshlrev_b32_e32 v142, 16, v144
	v_and_b32_e32 v143, 0xffff0000, v144
	v_lshlrev_b32_e32 v144, 16, v145
	v_and_b32_e32 v145, 0xffff0000, v145
	s_waitcnt lgkmcnt(1)
	v_pk_fma_f32 v[8:9], v[254:255], v[108:109], v[8:9] op_sel:[1,0,0] op_sel_hi:[1,1,1]
	v_pk_fma_f32 v[32:33], v[252:253], v[108:109], v[32:33] op_sel_hi:[0,1,1]
	v_pk_fma_f32 v[22:23], v[252:253], v[108:109], v[22:23] op_sel:[1,0,0] op_sel_hi:[1,1,1]
	v_pk_fma_f32 v[16:17], v[254:255], v[108:109], v[16:17] op_sel_hi:[0,1,1]
	v_pk_fma_f32 v[4:5], v[254:255], v[246:247], v[4:5] op_sel:[1,0,0] op_sel_hi:[1,1,1]
	v_pk_fma_f32 v[30:31], v[252:253], v[246:247], v[30:31] op_sel_hi:[0,1,1]
	v_pk_fma_f32 v[20:21], v[252:253], v[246:247], v[20:21] op_sel:[1,0,0] op_sel_hi:[1,1,1]
	v_pk_fma_f32 v[12:13], v[254:255], v[246:247], v[12:13] op_sel_hi:[0,1,1]
	v_pk_fma_f32 v[2:3], v[254:255], v[142:143], v[2:3] op_sel:[1,0,0] op_sel_hi:[1,1,1]
	v_pk_fma_f32 v[26:27], v[252:253], v[142:143], v[26:27] op_sel_hi:[0,1,1]
	v_pk_fma_f32 v[18:19], v[252:253], v[142:143], v[18:19] op_sel:[1,0,0] op_sel_hi:[1,1,1]
	v_pk_fma_f32 v[10:11], v[254:255], v[142:143], v[10:11] op_sel_hi:[0,1,1]
	v_pk_fma_f32 v[0:1], v[254:255], v[144:145], v[0:1] op_sel:[1,0,0] op_sel_hi:[1,1,1]
	v_pk_fma_f32 v[24:25], v[252:253], v[144:145], v[24:25] op_sel_hi:[0,1,1]
	v_pk_fma_f32 v[14:15], v[252:253], v[144:145], v[14:15] op_sel:[1,0,0] op_sel_hi:[1,1,1]
	v_pk_fma_f32 v[6:7], v[254:255], v[144:145], v[6:7] op_sel_hi:[0,1,1]
	ds_read_b128 v[252:255], v112 offset:45632
	s_waitcnt vmcnt(27)
	v_lshlrev_b32_e32 v108, 16, v146
	v_and_b32_e32 v109, 0xffff0000, v146
	v_lshlrev_b32_e32 v246, 16, v147
	v_and_b32_e32 v247, 0xffff0000, v147
	v_lshlrev_b32_e32 v146, 16, v148
	v_and_b32_e32 v147, 0xffff0000, v148
	v_lshlrev_b32_e32 v148, 16, v149
	v_and_b32_e32 v149, 0xffff0000, v149
	s_waitcnt lgkmcnt(1)
	v_pk_fma_f32 v[8:9], v[250:251], v[108:109], v[8:9] op_sel:[1,0,0] op_sel_hi:[1,1,1]
	v_pk_fma_f32 v[32:33], v[248:249], v[108:109], v[32:33] op_sel_hi:[0,1,1]
	v_pk_fma_f32 v[22:23], v[248:249], v[108:109], v[22:23] op_sel:[1,0,0] op_sel_hi:[1,1,1]
	v_pk_fma_f32 v[16:17], v[250:251], v[108:109], v[16:17] op_sel_hi:[0,1,1]
	v_pk_fma_f32 v[4:5], v[250:251], v[246:247], v[4:5] op_sel:[1,0,0] op_sel_hi:[1,1,1]
	v_pk_fma_f32 v[30:31], v[248:249], v[246:247], v[30:31] op_sel_hi:[0,1,1]
	v_pk_fma_f32 v[20:21], v[248:249], v[246:247], v[20:21] op_sel:[1,0,0] op_sel_hi:[1,1,1]
	v_pk_fma_f32 v[12:13], v[250:251], v[246:247], v[12:13] op_sel_hi:[0,1,1]
	v_pk_fma_f32 v[2:3], v[250:251], v[146:147], v[2:3] op_sel:[1,0,0] op_sel_hi:[1,1,1]
	v_pk_fma_f32 v[26:27], v[248:249], v[146:147], v[26:27] op_sel_hi:[0,1,1]
	v_pk_fma_f32 v[18:19], v[248:249], v[146:147], v[18:19] op_sel:[1,0,0] op_sel_hi:[1,1,1]
	v_pk_fma_f32 v[10:11], v[250:251], v[146:147], v[10:11] op_sel_hi:[0,1,1]
	v_pk_fma_f32 v[0:1], v[250:251], v[148:149], v[0:1] op_sel:[1,0,0] op_sel_hi:[1,1,1]
	v_pk_fma_f32 v[24:25], v[248:249], v[148:149], v[24:25] op_sel_hi:[0,1,1]
	v_pk_fma_f32 v[14:15], v[248:249], v[148:149], v[14:15] op_sel:[1,0,0] op_sel_hi:[1,1,1]
	v_pk_fma_f32 v[6:7], v[250:251], v[148:149], v[6:7] op_sel_hi:[0,1,1]
	ds_read_b128 v[248:251], v112 offset:45696
	s_waitcnt vmcnt(26)
	v_lshlrev_b32_e32 v108, 16, v150
	v_and_b32_e32 v109, 0xffff0000, v150
	v_lshlrev_b32_e32 v246, 16, v151
	v_and_b32_e32 v247, 0xffff0000, v151
	v_lshlrev_b32_e32 v150, 16, v152
	v_and_b32_e32 v151, 0xffff0000, v152
	v_lshlrev_b32_e32 v152, 16, v153
	v_and_b32_e32 v153, 0xffff0000, v153
	s_waitcnt lgkmcnt(1)
	v_pk_fma_f32 v[8:9], v[254:255], v[108:109], v[8:9] op_sel:[1,0,0] op_sel_hi:[1,1,1]
	v_pk_fma_f32 v[32:33], v[252:253], v[108:109], v[32:33] op_sel_hi:[0,1,1]
	v_pk_fma_f32 v[22:23], v[252:253], v[108:109], v[22:23] op_sel:[1,0,0] op_sel_hi:[1,1,1]
	v_pk_fma_f32 v[16:17], v[254:255], v[108:109], v[16:17] op_sel_hi:[0,1,1]
	v_pk_fma_f32 v[4:5], v[254:255], v[246:247], v[4:5] op_sel:[1,0,0] op_sel_hi:[1,1,1]
	v_pk_fma_f32 v[30:31], v[252:253], v[246:247], v[30:31] op_sel_hi:[0,1,1]
	v_pk_fma_f32 v[20:21], v[252:253], v[246:247], v[20:21] op_sel:[1,0,0] op_sel_hi:[1,1,1]
	v_pk_fma_f32 v[12:13], v[254:255], v[246:247], v[12:13] op_sel_hi:[0,1,1]
	v_pk_fma_f32 v[2:3], v[254:255], v[150:151], v[2:3] op_sel:[1,0,0] op_sel_hi:[1,1,1]
	v_pk_fma_f32 v[26:27], v[252:253], v[150:151], v[26:27] op_sel_hi:[0,1,1]
	v_pk_fma_f32 v[18:19], v[252:253], v[150:151], v[18:19] op_sel:[1,0,0] op_sel_hi:[1,1,1]
	v_pk_fma_f32 v[10:11], v[254:255], v[150:151], v[10:11] op_sel_hi:[0,1,1]
	v_pk_fma_f32 v[0:1], v[254:255], v[152:153], v[0:1] op_sel:[1,0,0] op_sel_hi:[1,1,1]
	v_pk_fma_f32 v[24:25], v[252:253], v[152:153], v[24:25] op_sel_hi:[0,1,1]
	v_pk_fma_f32 v[14:15], v[252:253], v[152:153], v[14:15] op_sel:[1,0,0] op_sel_hi:[1,1,1]
	v_pk_fma_f32 v[6:7], v[254:255], v[152:153], v[6:7] op_sel_hi:[0,1,1]
	ds_read_b128 v[252:255], v112 offset:45760
	s_waitcnt vmcnt(25)
	v_lshlrev_b32_e32 v108, 16, v154
	v_and_b32_e32 v109, 0xffff0000, v154
	v_lshlrev_b32_e32 v246, 16, v155
	v_and_b32_e32 v247, 0xffff0000, v155
	v_lshlrev_b32_e32 v154, 16, v156
	v_and_b32_e32 v155, 0xffff0000, v156
	v_lshlrev_b32_e32 v156, 16, v157
	v_and_b32_e32 v157, 0xffff0000, v157
	s_waitcnt lgkmcnt(1)
	v_pk_fma_f32 v[8:9], v[250:251], v[108:109], v[8:9] op_sel:[1,0,0] op_sel_hi:[1,1,1]
	v_pk_fma_f32 v[32:33], v[248:249], v[108:109], v[32:33] op_sel_hi:[0,1,1]
	v_pk_fma_f32 v[22:23], v[248:249], v[108:109], v[22:23] op_sel:[1,0,0] op_sel_hi:[1,1,1]
	v_pk_fma_f32 v[16:17], v[250:251], v[108:109], v[16:17] op_sel_hi:[0,1,1]
	v_pk_fma_f32 v[4:5], v[250:251], v[246:247], v[4:5] op_sel:[1,0,0] op_sel_hi:[1,1,1]
	v_pk_fma_f32 v[30:31], v[248:249], v[246:247], v[30:31] op_sel_hi:[0,1,1]
	v_pk_fma_f32 v[20:21], v[248:249], v[246:247], v[20:21] op_sel:[1,0,0] op_sel_hi:[1,1,1]
	v_pk_fma_f32 v[12:13], v[250:251], v[246:247], v[12:13] op_sel_hi:[0,1,1]
	v_pk_fma_f32 v[2:3], v[250:251], v[154:155], v[2:3] op_sel:[1,0,0] op_sel_hi:[1,1,1]
	v_pk_fma_f32 v[26:27], v[248:249], v[154:155], v[26:27] op_sel_hi:[0,1,1]
	v_pk_fma_f32 v[18:19], v[248:249], v[154:155], v[18:19] op_sel:[1,0,0] op_sel_hi:[1,1,1]
	v_pk_fma_f32 v[10:11], v[250:251], v[154:155], v[10:11] op_sel_hi:[0,1,1]
	v_pk_fma_f32 v[0:1], v[250:251], v[156:157], v[0:1] op_sel:[1,0,0] op_sel_hi:[1,1,1]
	v_pk_fma_f32 v[24:25], v[248:249], v[156:157], v[24:25] op_sel_hi:[0,1,1]
	v_pk_fma_f32 v[14:15], v[248:249], v[156:157], v[14:15] op_sel:[1,0,0] op_sel_hi:[1,1,1]
	v_pk_fma_f32 v[6:7], v[250:251], v[156:157], v[6:7] op_sel_hi:[0,1,1]
	ds_read_b128 v[248:251], v112 offset:45824
	s_waitcnt vmcnt(24)
	v_lshlrev_b32_e32 v108, 16, v158
	v_and_b32_e32 v109, 0xffff0000, v158
	v_lshlrev_b32_e32 v246, 16, v159
	v_and_b32_e32 v247, 0xffff0000, v159
	v_lshlrev_b32_e32 v158, 16, v160
	v_and_b32_e32 v159, 0xffff0000, v160
	v_lshlrev_b32_e32 v160, 16, v161
	v_and_b32_e32 v161, 0xffff0000, v161
	s_waitcnt lgkmcnt(1)
	v_pk_fma_f32 v[8:9], v[254:255], v[108:109], v[8:9] op_sel:[1,0,0] op_sel_hi:[1,1,1]
	v_pk_fma_f32 v[32:33], v[252:253], v[108:109], v[32:33] op_sel_hi:[0,1,1]
	v_pk_fma_f32 v[22:23], v[252:253], v[108:109], v[22:23] op_sel:[1,0,0] op_sel_hi:[1,1,1]
	v_pk_fma_f32 v[16:17], v[254:255], v[108:109], v[16:17] op_sel_hi:[0,1,1]
	v_pk_fma_f32 v[4:5], v[254:255], v[246:247], v[4:5] op_sel:[1,0,0] op_sel_hi:[1,1,1]
	v_pk_fma_f32 v[30:31], v[252:253], v[246:247], v[30:31] op_sel_hi:[0,1,1]
	v_pk_fma_f32 v[20:21], v[252:253], v[246:247], v[20:21] op_sel:[1,0,0] op_sel_hi:[1,1,1]
	v_pk_fma_f32 v[12:13], v[254:255], v[246:247], v[12:13] op_sel_hi:[0,1,1]
	v_pk_fma_f32 v[2:3], v[254:255], v[158:159], v[2:3] op_sel:[1,0,0] op_sel_hi:[1,1,1]
	v_pk_fma_f32 v[26:27], v[252:253], v[158:159], v[26:27] op_sel_hi:[0,1,1]
	v_pk_fma_f32 v[18:19], v[252:253], v[158:159], v[18:19] op_sel:[1,0,0] op_sel_hi:[1,1,1]
	v_pk_fma_f32 v[10:11], v[254:255], v[158:159], v[10:11] op_sel_hi:[0,1,1]
	v_pk_fma_f32 v[0:1], v[254:255], v[160:161], v[0:1] op_sel:[1,0,0] op_sel_hi:[1,1,1]
	v_pk_fma_f32 v[24:25], v[252:253], v[160:161], v[24:25] op_sel_hi:[0,1,1]
	v_pk_fma_f32 v[14:15], v[252:253], v[160:161], v[14:15] op_sel:[1,0,0] op_sel_hi:[1,1,1]
	v_pk_fma_f32 v[6:7], v[254:255], v[160:161], v[6:7] op_sel_hi:[0,1,1]
	ds_read_b128 v[252:255], v112 offset:45888
	s_waitcnt vmcnt(23)
	v_lshlrev_b32_e32 v108, 16, v162
	v_and_b32_e32 v109, 0xffff0000, v162
	v_lshlrev_b32_e32 v246, 16, v163
	v_and_b32_e32 v247, 0xffff0000, v163
	v_lshlrev_b32_e32 v162, 16, v164
	v_and_b32_e32 v163, 0xffff0000, v164
	v_lshlrev_b32_e32 v164, 16, v165
	v_and_b32_e32 v165, 0xffff0000, v165
	s_waitcnt lgkmcnt(1)
	v_pk_fma_f32 v[8:9], v[250:251], v[108:109], v[8:9] op_sel:[1,0,0] op_sel_hi:[1,1,1]
	v_pk_fma_f32 v[32:33], v[248:249], v[108:109], v[32:33] op_sel_hi:[0,1,1]
	v_pk_fma_f32 v[22:23], v[248:249], v[108:109], v[22:23] op_sel:[1,0,0] op_sel_hi:[1,1,1]
	v_pk_fma_f32 v[16:17], v[250:251], v[108:109], v[16:17] op_sel_hi:[0,1,1]
	v_pk_fma_f32 v[4:5], v[250:251], v[246:247], v[4:5] op_sel:[1,0,0] op_sel_hi:[1,1,1]
	v_pk_fma_f32 v[30:31], v[248:249], v[246:247], v[30:31] op_sel_hi:[0,1,1]
	v_pk_fma_f32 v[20:21], v[248:249], v[246:247], v[20:21] op_sel:[1,0,0] op_sel_hi:[1,1,1]
	v_pk_fma_f32 v[12:13], v[250:251], v[246:247], v[12:13] op_sel_hi:[0,1,1]
	v_pk_fma_f32 v[2:3], v[250:251], v[162:163], v[2:3] op_sel:[1,0,0] op_sel_hi:[1,1,1]
	v_pk_fma_f32 v[26:27], v[248:249], v[162:163], v[26:27] op_sel_hi:[0,1,1]
	v_pk_fma_f32 v[18:19], v[248:249], v[162:163], v[18:19] op_sel:[1,0,0] op_sel_hi:[1,1,1]
	v_pk_fma_f32 v[10:11], v[250:251], v[162:163], v[10:11] op_sel_hi:[0,1,1]
	v_pk_fma_f32 v[0:1], v[250:251], v[164:165], v[0:1] op_sel:[1,0,0] op_sel_hi:[1,1,1]
	v_pk_fma_f32 v[24:25], v[248:249], v[164:165], v[24:25] op_sel_hi:[0,1,1]
	v_pk_fma_f32 v[14:15], v[248:249], v[164:165], v[14:15] op_sel:[1,0,0] op_sel_hi:[1,1,1]
	v_pk_fma_f32 v[6:7], v[250:251], v[164:165], v[6:7] op_sel_hi:[0,1,1]
	ds_read_b128 v[248:251], v112 offset:45952
	s_waitcnt vmcnt(22)
	v_lshlrev_b32_e32 v108, 16, v166
	v_and_b32_e32 v109, 0xffff0000, v166
	v_lshlrev_b32_e32 v246, 16, v167
	v_and_b32_e32 v247, 0xffff0000, v167
	v_lshlrev_b32_e32 v166, 16, v168
	v_and_b32_e32 v167, 0xffff0000, v168
	v_lshlrev_b32_e32 v168, 16, v169
	v_and_b32_e32 v169, 0xffff0000, v169
	s_waitcnt lgkmcnt(1)
	v_pk_fma_f32 v[8:9], v[254:255], v[108:109], v[8:9] op_sel:[1,0,0] op_sel_hi:[1,1,1]
	v_pk_fma_f32 v[32:33], v[252:253], v[108:109], v[32:33] op_sel_hi:[0,1,1]
	v_pk_fma_f32 v[22:23], v[252:253], v[108:109], v[22:23] op_sel:[1,0,0] op_sel_hi:[1,1,1]
	v_pk_fma_f32 v[16:17], v[254:255], v[108:109], v[16:17] op_sel_hi:[0,1,1]
	v_pk_fma_f32 v[4:5], v[254:255], v[246:247], v[4:5] op_sel:[1,0,0] op_sel_hi:[1,1,1]
	v_pk_fma_f32 v[30:31], v[252:253], v[246:247], v[30:31] op_sel_hi:[0,1,1]
	v_pk_fma_f32 v[20:21], v[252:253], v[246:247], v[20:21] op_sel:[1,0,0] op_sel_hi:[1,1,1]
	v_pk_fma_f32 v[12:13], v[254:255], v[246:247], v[12:13] op_sel_hi:[0,1,1]
	v_pk_fma_f32 v[2:3], v[254:255], v[166:167], v[2:3] op_sel:[1,0,0] op_sel_hi:[1,1,1]
	v_pk_fma_f32 v[26:27], v[252:253], v[166:167], v[26:27] op_sel_hi:[0,1,1]
	v_pk_fma_f32 v[18:19], v[252:253], v[166:167], v[18:19] op_sel:[1,0,0] op_sel_hi:[1,1,1]
	v_pk_fma_f32 v[10:11], v[254:255], v[166:167], v[10:11] op_sel_hi:[0,1,1]
	v_pk_fma_f32 v[0:1], v[254:255], v[168:169], v[0:1] op_sel:[1,0,0] op_sel_hi:[1,1,1]
	v_pk_fma_f32 v[24:25], v[252:253], v[168:169], v[24:25] op_sel_hi:[0,1,1]
	v_pk_fma_f32 v[14:15], v[252:253], v[168:169], v[14:15] op_sel:[1,0,0] op_sel_hi:[1,1,1]
	v_pk_fma_f32 v[6:7], v[254:255], v[168:169], v[6:7] op_sel_hi:[0,1,1]
	ds_read_b128 v[252:255], v112 offset:46016
	s_waitcnt vmcnt(21)
	v_lshlrev_b32_e32 v108, 16, v170
	v_and_b32_e32 v109, 0xffff0000, v170
	v_lshlrev_b32_e32 v246, 16, v171
	v_and_b32_e32 v247, 0xffff0000, v171
	v_lshlrev_b32_e32 v170, 16, v172
	v_and_b32_e32 v171, 0xffff0000, v172
	v_lshlrev_b32_e32 v172, 16, v173
	v_and_b32_e32 v173, 0xffff0000, v173
	s_waitcnt lgkmcnt(1)
	v_pk_fma_f32 v[8:9], v[250:251], v[108:109], v[8:9] op_sel:[1,0,0] op_sel_hi:[1,1,1]
	v_pk_fma_f32 v[32:33], v[248:249], v[108:109], v[32:33] op_sel_hi:[0,1,1]
	v_pk_fma_f32 v[22:23], v[248:249], v[108:109], v[22:23] op_sel:[1,0,0] op_sel_hi:[1,1,1]
	v_pk_fma_f32 v[16:17], v[250:251], v[108:109], v[16:17] op_sel_hi:[0,1,1]
	v_pk_fma_f32 v[4:5], v[250:251], v[246:247], v[4:5] op_sel:[1,0,0] op_sel_hi:[1,1,1]
	v_pk_fma_f32 v[30:31], v[248:249], v[246:247], v[30:31] op_sel_hi:[0,1,1]
	v_pk_fma_f32 v[20:21], v[248:249], v[246:247], v[20:21] op_sel:[1,0,0] op_sel_hi:[1,1,1]
	v_pk_fma_f32 v[12:13], v[250:251], v[246:247], v[12:13] op_sel_hi:[0,1,1]
	v_pk_fma_f32 v[2:3], v[250:251], v[170:171], v[2:3] op_sel:[1,0,0] op_sel_hi:[1,1,1]
	v_pk_fma_f32 v[26:27], v[248:249], v[170:171], v[26:27] op_sel_hi:[0,1,1]
	v_pk_fma_f32 v[18:19], v[248:249], v[170:171], v[18:19] op_sel:[1,0,0] op_sel_hi:[1,1,1]
	v_pk_fma_f32 v[10:11], v[250:251], v[170:171], v[10:11] op_sel_hi:[0,1,1]
	v_pk_fma_f32 v[0:1], v[250:251], v[172:173], v[0:1] op_sel:[1,0,0] op_sel_hi:[1,1,1]
	v_pk_fma_f32 v[24:25], v[248:249], v[172:173], v[24:25] op_sel_hi:[0,1,1]
	v_pk_fma_f32 v[14:15], v[248:249], v[172:173], v[14:15] op_sel:[1,0,0] op_sel_hi:[1,1,1]
	v_pk_fma_f32 v[6:7], v[250:251], v[172:173], v[6:7] op_sel_hi:[0,1,1]
	ds_read_b128 v[248:251], v112 offset:46080
	s_waitcnt vmcnt(20)
	v_lshlrev_b32_e32 v108, 16, v174
	v_and_b32_e32 v109, 0xffff0000, v174
	v_lshlrev_b32_e32 v246, 16, v175
	v_and_b32_e32 v247, 0xffff0000, v175
	v_lshlrev_b32_e32 v174, 16, v176
	v_and_b32_e32 v175, 0xffff0000, v176
	v_lshlrev_b32_e32 v176, 16, v177
	v_and_b32_e32 v177, 0xffff0000, v177
	s_waitcnt lgkmcnt(1)
	v_pk_fma_f32 v[8:9], v[254:255], v[108:109], v[8:9] op_sel:[1,0,0] op_sel_hi:[1,1,1]
	v_pk_fma_f32 v[32:33], v[252:253], v[108:109], v[32:33] op_sel_hi:[0,1,1]
	v_pk_fma_f32 v[22:23], v[252:253], v[108:109], v[22:23] op_sel:[1,0,0] op_sel_hi:[1,1,1]
	v_pk_fma_f32 v[16:17], v[254:255], v[108:109], v[16:17] op_sel_hi:[0,1,1]
	v_pk_fma_f32 v[4:5], v[254:255], v[246:247], v[4:5] op_sel:[1,0,0] op_sel_hi:[1,1,1]
	v_pk_fma_f32 v[30:31], v[252:253], v[246:247], v[30:31] op_sel_hi:[0,1,1]
	v_pk_fma_f32 v[20:21], v[252:253], v[246:247], v[20:21] op_sel:[1,0,0] op_sel_hi:[1,1,1]
	v_pk_fma_f32 v[12:13], v[254:255], v[246:247], v[12:13] op_sel_hi:[0,1,1]
	v_pk_fma_f32 v[2:3], v[254:255], v[174:175], v[2:3] op_sel:[1,0,0] op_sel_hi:[1,1,1]
	v_pk_fma_f32 v[26:27], v[252:253], v[174:175], v[26:27] op_sel_hi:[0,1,1]
	v_pk_fma_f32 v[18:19], v[252:253], v[174:175], v[18:19] op_sel:[1,0,0] op_sel_hi:[1,1,1]
	v_pk_fma_f32 v[10:11], v[254:255], v[174:175], v[10:11] op_sel_hi:[0,1,1]
	v_pk_fma_f32 v[0:1], v[254:255], v[176:177], v[0:1] op_sel:[1,0,0] op_sel_hi:[1,1,1]
	v_pk_fma_f32 v[24:25], v[252:253], v[176:177], v[24:25] op_sel_hi:[0,1,1]
	v_pk_fma_f32 v[14:15], v[252:253], v[176:177], v[14:15] op_sel:[1,0,0] op_sel_hi:[1,1,1]
	v_pk_fma_f32 v[6:7], v[254:255], v[176:177], v[6:7] op_sel_hi:[0,1,1]
	ds_read_b128 v[252:255], v112 offset:46144
	s_waitcnt vmcnt(19)
	v_lshlrev_b32_e32 v108, 16, v178
	v_and_b32_e32 v109, 0xffff0000, v178
	v_lshlrev_b32_e32 v246, 16, v179
	v_and_b32_e32 v247, 0xffff0000, v179
	v_lshlrev_b32_e32 v178, 16, v180
	v_and_b32_e32 v179, 0xffff0000, v180
	v_lshlrev_b32_e32 v180, 16, v181
	v_and_b32_e32 v181, 0xffff0000, v181
	s_waitcnt lgkmcnt(1)
	v_pk_fma_f32 v[8:9], v[250:251], v[108:109], v[8:9] op_sel:[1,0,0] op_sel_hi:[1,1,1]
	v_pk_fma_f32 v[32:33], v[248:249], v[108:109], v[32:33] op_sel_hi:[0,1,1]
	v_pk_fma_f32 v[22:23], v[248:249], v[108:109], v[22:23] op_sel:[1,0,0] op_sel_hi:[1,1,1]
	v_pk_fma_f32 v[16:17], v[250:251], v[108:109], v[16:17] op_sel_hi:[0,1,1]
	v_pk_fma_f32 v[4:5], v[250:251], v[246:247], v[4:5] op_sel:[1,0,0] op_sel_hi:[1,1,1]
	v_pk_fma_f32 v[30:31], v[248:249], v[246:247], v[30:31] op_sel_hi:[0,1,1]
	v_pk_fma_f32 v[20:21], v[248:249], v[246:247], v[20:21] op_sel:[1,0,0] op_sel_hi:[1,1,1]
	v_pk_fma_f32 v[12:13], v[250:251], v[246:247], v[12:13] op_sel_hi:[0,1,1]
	v_pk_fma_f32 v[2:3], v[250:251], v[178:179], v[2:3] op_sel:[1,0,0] op_sel_hi:[1,1,1]
	v_pk_fma_f32 v[26:27], v[248:249], v[178:179], v[26:27] op_sel_hi:[0,1,1]
	v_pk_fma_f32 v[18:19], v[248:249], v[178:179], v[18:19] op_sel:[1,0,0] op_sel_hi:[1,1,1]
	v_pk_fma_f32 v[10:11], v[250:251], v[178:179], v[10:11] op_sel_hi:[0,1,1]
	v_pk_fma_f32 v[0:1], v[250:251], v[180:181], v[0:1] op_sel:[1,0,0] op_sel_hi:[1,1,1]
	v_pk_fma_f32 v[24:25], v[248:249], v[180:181], v[24:25] op_sel_hi:[0,1,1]
	v_pk_fma_f32 v[14:15], v[248:249], v[180:181], v[14:15] op_sel:[1,0,0] op_sel_hi:[1,1,1]
	v_pk_fma_f32 v[6:7], v[250:251], v[180:181], v[6:7] op_sel_hi:[0,1,1]
	ds_read_b128 v[248:251], v112 offset:46208
	s_waitcnt vmcnt(18)
	v_lshlrev_b32_e32 v108, 16, v182
	v_and_b32_e32 v109, 0xffff0000, v182
	v_lshlrev_b32_e32 v246, 16, v183
	v_and_b32_e32 v247, 0xffff0000, v183
	v_lshlrev_b32_e32 v182, 16, v184
	v_and_b32_e32 v183, 0xffff0000, v184
	v_lshlrev_b32_e32 v184, 16, v185
	v_and_b32_e32 v185, 0xffff0000, v185
	s_waitcnt lgkmcnt(1)
	v_pk_fma_f32 v[8:9], v[254:255], v[108:109], v[8:9] op_sel:[1,0,0] op_sel_hi:[1,1,1]
	v_pk_fma_f32 v[32:33], v[252:253], v[108:109], v[32:33] op_sel_hi:[0,1,1]
	v_pk_fma_f32 v[22:23], v[252:253], v[108:109], v[22:23] op_sel:[1,0,0] op_sel_hi:[1,1,1]
	v_pk_fma_f32 v[16:17], v[254:255], v[108:109], v[16:17] op_sel_hi:[0,1,1]
	v_pk_fma_f32 v[4:5], v[254:255], v[246:247], v[4:5] op_sel:[1,0,0] op_sel_hi:[1,1,1]
	v_pk_fma_f32 v[30:31], v[252:253], v[246:247], v[30:31] op_sel_hi:[0,1,1]
	v_pk_fma_f32 v[20:21], v[252:253], v[246:247], v[20:21] op_sel:[1,0,0] op_sel_hi:[1,1,1]
	v_pk_fma_f32 v[12:13], v[254:255], v[246:247], v[12:13] op_sel_hi:[0,1,1]
	v_pk_fma_f32 v[2:3], v[254:255], v[182:183], v[2:3] op_sel:[1,0,0] op_sel_hi:[1,1,1]
	v_pk_fma_f32 v[26:27], v[252:253], v[182:183], v[26:27] op_sel_hi:[0,1,1]
	v_pk_fma_f32 v[18:19], v[252:253], v[182:183], v[18:19] op_sel:[1,0,0] op_sel_hi:[1,1,1]
	v_pk_fma_f32 v[10:11], v[254:255], v[182:183], v[10:11] op_sel_hi:[0,1,1]
	v_pk_fma_f32 v[0:1], v[254:255], v[184:185], v[0:1] op_sel:[1,0,0] op_sel_hi:[1,1,1]
	v_pk_fma_f32 v[24:25], v[252:253], v[184:185], v[24:25] op_sel_hi:[0,1,1]
	v_pk_fma_f32 v[14:15], v[252:253], v[184:185], v[14:15] op_sel:[1,0,0] op_sel_hi:[1,1,1]
	v_pk_fma_f32 v[6:7], v[254:255], v[184:185], v[6:7] op_sel_hi:[0,1,1]
	ds_read_b128 v[252:255], v112 offset:46272
	s_waitcnt vmcnt(17)
	v_lshlrev_b32_e32 v108, 16, v186
	v_and_b32_e32 v109, 0xffff0000, v186
	v_lshlrev_b32_e32 v246, 16, v187
	v_and_b32_e32 v247, 0xffff0000, v187
	v_lshlrev_b32_e32 v186, 16, v188
	v_and_b32_e32 v187, 0xffff0000, v188
	v_lshlrev_b32_e32 v188, 16, v189
	v_and_b32_e32 v189, 0xffff0000, v189
	s_waitcnt lgkmcnt(1)
	v_pk_fma_f32 v[8:9], v[250:251], v[108:109], v[8:9] op_sel:[1,0,0] op_sel_hi:[1,1,1]
	v_pk_fma_f32 v[32:33], v[248:249], v[108:109], v[32:33] op_sel_hi:[0,1,1]
	v_pk_fma_f32 v[22:23], v[248:249], v[108:109], v[22:23] op_sel:[1,0,0] op_sel_hi:[1,1,1]
	v_pk_fma_f32 v[16:17], v[250:251], v[108:109], v[16:17] op_sel_hi:[0,1,1]
	v_pk_fma_f32 v[4:5], v[250:251], v[246:247], v[4:5] op_sel:[1,0,0] op_sel_hi:[1,1,1]
	v_pk_fma_f32 v[30:31], v[248:249], v[246:247], v[30:31] op_sel_hi:[0,1,1]
	v_pk_fma_f32 v[20:21], v[248:249], v[246:247], v[20:21] op_sel:[1,0,0] op_sel_hi:[1,1,1]
	v_pk_fma_f32 v[12:13], v[250:251], v[246:247], v[12:13] op_sel_hi:[0,1,1]
	v_pk_fma_f32 v[2:3], v[250:251], v[186:187], v[2:3] op_sel:[1,0,0] op_sel_hi:[1,1,1]
	v_pk_fma_f32 v[26:27], v[248:249], v[186:187], v[26:27] op_sel_hi:[0,1,1]
	v_pk_fma_f32 v[18:19], v[248:249], v[186:187], v[18:19] op_sel:[1,0,0] op_sel_hi:[1,1,1]
	v_pk_fma_f32 v[10:11], v[250:251], v[186:187], v[10:11] op_sel_hi:[0,1,1]
	v_pk_fma_f32 v[0:1], v[250:251], v[188:189], v[0:1] op_sel:[1,0,0] op_sel_hi:[1,1,1]
	v_pk_fma_f32 v[24:25], v[248:249], v[188:189], v[24:25] op_sel_hi:[0,1,1]
	v_pk_fma_f32 v[14:15], v[248:249], v[188:189], v[14:15] op_sel:[1,0,0] op_sel_hi:[1,1,1]
	v_pk_fma_f32 v[6:7], v[250:251], v[188:189], v[6:7] op_sel_hi:[0,1,1]
	s_waitcnt vmcnt(16)
	v_lshlrev_b32_e32 v108, 16, v190
	v_and_b32_e32 v109, 0xffff0000, v190
	v_lshlrev_b32_e32 v246, 16, v191
	v_and_b32_e32 v247, 0xffff0000, v191
	v_lshlrev_b32_e32 v190, 16, v192
	v_and_b32_e32 v191, 0xffff0000, v192
	v_lshlrev_b32_e32 v192, 16, v193
	v_and_b32_e32 v193, 0xffff0000, v193
	s_waitcnt lgkmcnt(0)
	v_pk_fma_f32 v[8:9], v[254:255], v[108:109], v[8:9] op_sel:[1,0,0] op_sel_hi:[1,1,1]
	v_pk_fma_f32 v[32:33], v[252:253], v[108:109], v[32:33] op_sel_hi:[0,1,1]
	v_pk_fma_f32 v[22:23], v[252:253], v[108:109], v[22:23] op_sel:[1,0,0] op_sel_hi:[1,1,1]
	v_pk_fma_f32 v[16:17], v[254:255], v[108:109], v[16:17] op_sel_hi:[0,1,1]
	v_pk_fma_f32 v[4:5], v[254:255], v[246:247], v[4:5] op_sel:[1,0,0] op_sel_hi:[1,1,1]
	v_pk_fma_f32 v[30:31], v[252:253], v[246:247], v[30:31] op_sel_hi:[0,1,1]
	v_pk_fma_f32 v[20:21], v[252:253], v[246:247], v[20:21] op_sel:[1,0,0] op_sel_hi:[1,1,1]
	v_pk_fma_f32 v[12:13], v[254:255], v[246:247], v[12:13] op_sel_hi:[0,1,1]
	v_pk_fma_f32 v[2:3], v[254:255], v[190:191], v[2:3] op_sel:[1,0,0] op_sel_hi:[1,1,1]
	v_pk_fma_f32 v[26:27], v[252:253], v[190:191], v[26:27] op_sel_hi:[0,1,1]
	v_pk_fma_f32 v[18:19], v[252:253], v[190:191], v[18:19] op_sel:[1,0,0] op_sel_hi:[1,1,1]
	v_pk_fma_f32 v[10:11], v[254:255], v[190:191], v[10:11] op_sel_hi:[0,1,1]
	v_pk_fma_f32 v[0:1], v[254:255], v[192:193], v[0:1] op_sel:[1,0,0] op_sel_hi:[1,1,1]
	v_pk_fma_f32 v[24:25], v[252:253], v[192:193], v[24:25] op_sel_hi:[0,1,1]
	v_pk_fma_f32 v[14:15], v[252:253], v[192:193], v[14:15] op_sel:[1,0,0] op_sel_hi:[1,1,1]
	v_pk_fma_f32 v[6:7], v[254:255], v[192:193], v[6:7] op_sel_hi:[0,1,1]
	ds_read_b128 v[248:251], v112 offset:46336
	ds_read_b128 v[252:255], v112 offset:46400
	s_waitcnt vmcnt(15)
	v_lshlrev_b32_e32 v108, 16, v210
	v_and_b32_e32 v109, 0xffff0000, v210
	v_lshlrev_b32_e32 v246, 16, v211
	v_and_b32_e32 v247, 0xffff0000, v211
	v_lshlrev_b32_e32 v210, 16, v212
	v_and_b32_e32 v211, 0xffff0000, v212
	v_lshlrev_b32_e32 v212, 16, v213
	v_and_b32_e32 v213, 0xffff0000, v213
	s_waitcnt lgkmcnt(1)
	v_pk_fma_f32 v[8:9], v[250:251], v[108:109], v[8:9] op_sel:[1,0,0] op_sel_hi:[1,1,1]
	v_pk_fma_f32 v[32:33], v[248:249], v[108:109], v[32:33] op_sel_hi:[0,1,1]
	v_pk_fma_f32 v[22:23], v[248:249], v[108:109], v[22:23] op_sel:[1,0,0] op_sel_hi:[1,1,1]
	v_pk_fma_f32 v[16:17], v[250:251], v[108:109], v[16:17] op_sel_hi:[0,1,1]
	v_pk_fma_f32 v[4:5], v[250:251], v[246:247], v[4:5] op_sel:[1,0,0] op_sel_hi:[1,1,1]
	v_pk_fma_f32 v[30:31], v[248:249], v[246:247], v[30:31] op_sel_hi:[0,1,1]
	v_pk_fma_f32 v[20:21], v[248:249], v[246:247], v[20:21] op_sel:[1,0,0] op_sel_hi:[1,1,1]
	v_pk_fma_f32 v[12:13], v[250:251], v[246:247], v[12:13] op_sel_hi:[0,1,1]
	v_pk_fma_f32 v[2:3], v[250:251], v[210:211], v[2:3] op_sel:[1,0,0] op_sel_hi:[1,1,1]
	v_pk_fma_f32 v[26:27], v[248:249], v[210:211], v[26:27] op_sel_hi:[0,1,1]
	v_pk_fma_f32 v[18:19], v[248:249], v[210:211], v[18:19] op_sel:[1,0,0] op_sel_hi:[1,1,1]
	v_pk_fma_f32 v[10:11], v[250:251], v[210:211], v[10:11] op_sel_hi:[0,1,1]
	v_pk_fma_f32 v[0:1], v[250:251], v[212:213], v[0:1] op_sel:[1,0,0] op_sel_hi:[1,1,1]
	v_pk_fma_f32 v[24:25], v[248:249], v[212:213], v[24:25] op_sel_hi:[0,1,1]
	v_pk_fma_f32 v[14:15], v[248:249], v[212:213], v[14:15] op_sel:[1,0,0] op_sel_hi:[1,1,1]
	v_pk_fma_f32 v[6:7], v[250:251], v[212:213], v[6:7] op_sel_hi:[0,1,1]
	ds_read_b128 v[248:251], v112 offset:46464
	s_waitcnt vmcnt(14)
	v_lshlrev_b32_e32 v108, 16, v214
	v_and_b32_e32 v109, 0xffff0000, v214
	v_lshlrev_b32_e32 v246, 16, v215
	v_and_b32_e32 v247, 0xffff0000, v215
	v_lshlrev_b32_e32 v214, 16, v216
	v_and_b32_e32 v215, 0xffff0000, v216
	v_lshlrev_b32_e32 v216, 16, v217
	v_and_b32_e32 v217, 0xffff0000, v217
	s_waitcnt lgkmcnt(1)
	v_pk_fma_f32 v[8:9], v[254:255], v[108:109], v[8:9] op_sel:[1,0,0] op_sel_hi:[1,1,1]
	v_pk_fma_f32 v[32:33], v[252:253], v[108:109], v[32:33] op_sel_hi:[0,1,1]
	v_pk_fma_f32 v[22:23], v[252:253], v[108:109], v[22:23] op_sel:[1,0,0] op_sel_hi:[1,1,1]
	v_pk_fma_f32 v[16:17], v[254:255], v[108:109], v[16:17] op_sel_hi:[0,1,1]
	v_pk_fma_f32 v[4:5], v[254:255], v[246:247], v[4:5] op_sel:[1,0,0] op_sel_hi:[1,1,1]
	v_pk_fma_f32 v[30:31], v[252:253], v[246:247], v[30:31] op_sel_hi:[0,1,1]
	v_pk_fma_f32 v[20:21], v[252:253], v[246:247], v[20:21] op_sel:[1,0,0] op_sel_hi:[1,1,1]
	v_pk_fma_f32 v[12:13], v[254:255], v[246:247], v[12:13] op_sel_hi:[0,1,1]
	v_pk_fma_f32 v[2:3], v[254:255], v[214:215], v[2:3] op_sel:[1,0,0] op_sel_hi:[1,1,1]
	v_pk_fma_f32 v[26:27], v[252:253], v[214:215], v[26:27] op_sel_hi:[0,1,1]
	v_pk_fma_f32 v[18:19], v[252:253], v[214:215], v[18:19] op_sel:[1,0,0] op_sel_hi:[1,1,1]
	v_pk_fma_f32 v[10:11], v[254:255], v[214:215], v[10:11] op_sel_hi:[0,1,1]
	v_pk_fma_f32 v[0:1], v[254:255], v[216:217], v[0:1] op_sel:[1,0,0] op_sel_hi:[1,1,1]
	v_pk_fma_f32 v[24:25], v[252:253], v[216:217], v[24:25] op_sel_hi:[0,1,1]
	v_pk_fma_f32 v[14:15], v[252:253], v[216:217], v[14:15] op_sel:[1,0,0] op_sel_hi:[1,1,1]
	v_pk_fma_f32 v[6:7], v[254:255], v[216:217], v[6:7] op_sel_hi:[0,1,1]
	ds_read_b128 v[252:255], v112 offset:46528
	s_waitcnt vmcnt(13)
	v_lshlrev_b32_e32 v108, 16, v218
	v_and_b32_e32 v109, 0xffff0000, v218
	v_lshlrev_b32_e32 v246, 16, v219
	v_and_b32_e32 v247, 0xffff0000, v219
	v_lshlrev_b32_e32 v218, 16, v220
	v_and_b32_e32 v219, 0xffff0000, v220
	v_lshlrev_b32_e32 v220, 16, v221
	v_and_b32_e32 v221, 0xffff0000, v221
	s_waitcnt lgkmcnt(1)
	v_pk_fma_f32 v[8:9], v[250:251], v[108:109], v[8:9] op_sel:[1,0,0] op_sel_hi:[1,1,1]
	v_pk_fma_f32 v[32:33], v[248:249], v[108:109], v[32:33] op_sel_hi:[0,1,1]
	v_pk_fma_f32 v[22:23], v[248:249], v[108:109], v[22:23] op_sel:[1,0,0] op_sel_hi:[1,1,1]
	v_pk_fma_f32 v[16:17], v[250:251], v[108:109], v[16:17] op_sel_hi:[0,1,1]
	v_pk_fma_f32 v[4:5], v[250:251], v[246:247], v[4:5] op_sel:[1,0,0] op_sel_hi:[1,1,1]
	v_pk_fma_f32 v[30:31], v[248:249], v[246:247], v[30:31] op_sel_hi:[0,1,1]
	v_pk_fma_f32 v[20:21], v[248:249], v[246:247], v[20:21] op_sel:[1,0,0] op_sel_hi:[1,1,1]
	v_pk_fma_f32 v[12:13], v[250:251], v[246:247], v[12:13] op_sel_hi:[0,1,1]
	v_pk_fma_f32 v[2:3], v[250:251], v[218:219], v[2:3] op_sel:[1,0,0] op_sel_hi:[1,1,1]
	v_pk_fma_f32 v[26:27], v[248:249], v[218:219], v[26:27] op_sel_hi:[0,1,1]
	v_pk_fma_f32 v[18:19], v[248:249], v[218:219], v[18:19] op_sel:[1,0,0] op_sel_hi:[1,1,1]
	v_pk_fma_f32 v[10:11], v[250:251], v[218:219], v[10:11] op_sel_hi:[0,1,1]
	v_pk_fma_f32 v[0:1], v[250:251], v[220:221], v[0:1] op_sel:[1,0,0] op_sel_hi:[1,1,1]
	v_pk_fma_f32 v[24:25], v[248:249], v[220:221], v[24:25] op_sel_hi:[0,1,1]
	v_pk_fma_f32 v[14:15], v[248:249], v[220:221], v[14:15] op_sel:[1,0,0] op_sel_hi:[1,1,1]
	v_pk_fma_f32 v[6:7], v[250:251], v[220:221], v[6:7] op_sel_hi:[0,1,1]
	ds_read_b128 v[248:251], v112 offset:46592
	s_waitcnt vmcnt(12)
	v_lshlrev_b32_e32 v108, 16, v222
	v_and_b32_e32 v109, 0xffff0000, v222
	v_lshlrev_b32_e32 v246, 16, v223
	v_and_b32_e32 v247, 0xffff0000, v223
	v_lshlrev_b32_e32 v222, 16, v224
	v_and_b32_e32 v223, 0xffff0000, v224
	v_lshlrev_b32_e32 v224, 16, v225
	v_and_b32_e32 v225, 0xffff0000, v225
	s_waitcnt lgkmcnt(1)
	v_pk_fma_f32 v[8:9], v[254:255], v[108:109], v[8:9] op_sel:[1,0,0] op_sel_hi:[1,1,1]
	v_pk_fma_f32 v[32:33], v[252:253], v[108:109], v[32:33] op_sel_hi:[0,1,1]
	v_pk_fma_f32 v[22:23], v[252:253], v[108:109], v[22:23] op_sel:[1,0,0] op_sel_hi:[1,1,1]
	v_pk_fma_f32 v[16:17], v[254:255], v[108:109], v[16:17] op_sel_hi:[0,1,1]
	v_pk_fma_f32 v[4:5], v[254:255], v[246:247], v[4:5] op_sel:[1,0,0] op_sel_hi:[1,1,1]
	v_pk_fma_f32 v[30:31], v[252:253], v[246:247], v[30:31] op_sel_hi:[0,1,1]
	v_pk_fma_f32 v[20:21], v[252:253], v[246:247], v[20:21] op_sel:[1,0,0] op_sel_hi:[1,1,1]
	v_pk_fma_f32 v[12:13], v[254:255], v[246:247], v[12:13] op_sel_hi:[0,1,1]
	v_pk_fma_f32 v[2:3], v[254:255], v[222:223], v[2:3] op_sel:[1,0,0] op_sel_hi:[1,1,1]
	v_pk_fma_f32 v[26:27], v[252:253], v[222:223], v[26:27] op_sel_hi:[0,1,1]
	v_pk_fma_f32 v[18:19], v[252:253], v[222:223], v[18:19] op_sel:[1,0,0] op_sel_hi:[1,1,1]
	v_pk_fma_f32 v[10:11], v[254:255], v[222:223], v[10:11] op_sel_hi:[0,1,1]
	v_pk_fma_f32 v[0:1], v[254:255], v[224:225], v[0:1] op_sel:[1,0,0] op_sel_hi:[1,1,1]
	v_pk_fma_f32 v[24:25], v[252:253], v[224:225], v[24:25] op_sel_hi:[0,1,1]
	v_pk_fma_f32 v[14:15], v[252:253], v[224:225], v[14:15] op_sel:[1,0,0] op_sel_hi:[1,1,1]
	v_pk_fma_f32 v[6:7], v[254:255], v[224:225], v[6:7] op_sel_hi:[0,1,1]
	ds_read_b128 v[252:255], v112 offset:46656
	s_waitcnt vmcnt(11)
	v_lshlrev_b32_e32 v108, 16, v226
	v_and_b32_e32 v109, 0xffff0000, v226
	v_lshlrev_b32_e32 v246, 16, v227
	v_and_b32_e32 v247, 0xffff0000, v227
	v_lshlrev_b32_e32 v226, 16, v228
	v_and_b32_e32 v227, 0xffff0000, v228
	v_lshlrev_b32_e32 v228, 16, v229
	v_and_b32_e32 v229, 0xffff0000, v229
	s_waitcnt lgkmcnt(1)
	v_pk_fma_f32 v[8:9], v[250:251], v[108:109], v[8:9] op_sel:[1,0,0] op_sel_hi:[1,1,1]
	v_pk_fma_f32 v[32:33], v[248:249], v[108:109], v[32:33] op_sel_hi:[0,1,1]
	v_pk_fma_f32 v[22:23], v[248:249], v[108:109], v[22:23] op_sel:[1,0,0] op_sel_hi:[1,1,1]
	v_pk_fma_f32 v[16:17], v[250:251], v[108:109], v[16:17] op_sel_hi:[0,1,1]
	v_pk_fma_f32 v[4:5], v[250:251], v[246:247], v[4:5] op_sel:[1,0,0] op_sel_hi:[1,1,1]
	v_pk_fma_f32 v[30:31], v[248:249], v[246:247], v[30:31] op_sel_hi:[0,1,1]
	v_pk_fma_f32 v[20:21], v[248:249], v[246:247], v[20:21] op_sel:[1,0,0] op_sel_hi:[1,1,1]
	v_pk_fma_f32 v[12:13], v[250:251], v[246:247], v[12:13] op_sel_hi:[0,1,1]
	v_pk_fma_f32 v[2:3], v[250:251], v[226:227], v[2:3] op_sel:[1,0,0] op_sel_hi:[1,1,1]
	v_pk_fma_f32 v[26:27], v[248:249], v[226:227], v[26:27] op_sel_hi:[0,1,1]
	v_pk_fma_f32 v[18:19], v[248:249], v[226:227], v[18:19] op_sel:[1,0,0] op_sel_hi:[1,1,1]
	v_pk_fma_f32 v[10:11], v[250:251], v[226:227], v[10:11] op_sel_hi:[0,1,1]
	v_pk_fma_f32 v[0:1], v[250:251], v[228:229], v[0:1] op_sel:[1,0,0] op_sel_hi:[1,1,1]
	v_pk_fma_f32 v[24:25], v[248:249], v[228:229], v[24:25] op_sel_hi:[0,1,1]
	v_pk_fma_f32 v[14:15], v[248:249], v[228:229], v[14:15] op_sel:[1,0,0] op_sel_hi:[1,1,1]
	v_pk_fma_f32 v[6:7], v[250:251], v[228:229], v[6:7] op_sel_hi:[0,1,1]
	ds_read_b128 v[248:251], v112 offset:46720
	s_waitcnt vmcnt(10)
	v_lshlrev_b32_e32 v108, 16, v230
	v_and_b32_e32 v109, 0xffff0000, v230
	v_lshlrev_b32_e32 v246, 16, v231
	v_and_b32_e32 v247, 0xffff0000, v231
	v_lshlrev_b32_e32 v230, 16, v232
	v_and_b32_e32 v231, 0xffff0000, v232
	v_lshlrev_b32_e32 v232, 16, v233
	v_and_b32_e32 v233, 0xffff0000, v233
	s_waitcnt lgkmcnt(1)
	v_pk_fma_f32 v[8:9], v[254:255], v[108:109], v[8:9] op_sel:[1,0,0] op_sel_hi:[1,1,1]
	v_pk_fma_f32 v[32:33], v[252:253], v[108:109], v[32:33] op_sel_hi:[0,1,1]
	v_pk_fma_f32 v[22:23], v[252:253], v[108:109], v[22:23] op_sel:[1,0,0] op_sel_hi:[1,1,1]
	v_pk_fma_f32 v[16:17], v[254:255], v[108:109], v[16:17] op_sel_hi:[0,1,1]
	v_pk_fma_f32 v[4:5], v[254:255], v[246:247], v[4:5] op_sel:[1,0,0] op_sel_hi:[1,1,1]
	v_pk_fma_f32 v[30:31], v[252:253], v[246:247], v[30:31] op_sel_hi:[0,1,1]
	v_pk_fma_f32 v[20:21], v[252:253], v[246:247], v[20:21] op_sel:[1,0,0] op_sel_hi:[1,1,1]
	v_pk_fma_f32 v[12:13], v[254:255], v[246:247], v[12:13] op_sel_hi:[0,1,1]
	v_pk_fma_f32 v[2:3], v[254:255], v[230:231], v[2:3] op_sel:[1,0,0] op_sel_hi:[1,1,1]
	v_pk_fma_f32 v[26:27], v[252:253], v[230:231], v[26:27] op_sel_hi:[0,1,1]
	v_pk_fma_f32 v[18:19], v[252:253], v[230:231], v[18:19] op_sel:[1,0,0] op_sel_hi:[1,1,1]
	v_pk_fma_f32 v[10:11], v[254:255], v[230:231], v[10:11] op_sel_hi:[0,1,1]
	v_pk_fma_f32 v[0:1], v[254:255], v[232:233], v[0:1] op_sel:[1,0,0] op_sel_hi:[1,1,1]
	v_pk_fma_f32 v[24:25], v[252:253], v[232:233], v[24:25] op_sel_hi:[0,1,1]
	v_pk_fma_f32 v[14:15], v[252:253], v[232:233], v[14:15] op_sel:[1,0,0] op_sel_hi:[1,1,1]
	v_pk_fma_f32 v[6:7], v[254:255], v[232:233], v[6:7] op_sel_hi:[0,1,1]
	ds_read_b128 v[252:255], v112 offset:46784
	s_waitcnt vmcnt(9)
	v_lshlrev_b32_e32 v108, 16, v234
	v_and_b32_e32 v109, 0xffff0000, v234
	v_lshlrev_b32_e32 v246, 16, v235
	v_and_b32_e32 v247, 0xffff0000, v235
	v_lshlrev_b32_e32 v234, 16, v236
	v_and_b32_e32 v235, 0xffff0000, v236
	v_lshlrev_b32_e32 v236, 16, v237
	v_and_b32_e32 v237, 0xffff0000, v237
	s_waitcnt lgkmcnt(1)
	v_pk_fma_f32 v[8:9], v[250:251], v[108:109], v[8:9] op_sel:[1,0,0] op_sel_hi:[1,1,1]
	v_pk_fma_f32 v[32:33], v[248:249], v[108:109], v[32:33] op_sel_hi:[0,1,1]
	v_pk_fma_f32 v[22:23], v[248:249], v[108:109], v[22:23] op_sel:[1,0,0] op_sel_hi:[1,1,1]
	v_pk_fma_f32 v[16:17], v[250:251], v[108:109], v[16:17] op_sel_hi:[0,1,1]
	v_pk_fma_f32 v[4:5], v[250:251], v[246:247], v[4:5] op_sel:[1,0,0] op_sel_hi:[1,1,1]
	v_pk_fma_f32 v[30:31], v[248:249], v[246:247], v[30:31] op_sel_hi:[0,1,1]
	v_pk_fma_f32 v[20:21], v[248:249], v[246:247], v[20:21] op_sel:[1,0,0] op_sel_hi:[1,1,1]
	v_pk_fma_f32 v[12:13], v[250:251], v[246:247], v[12:13] op_sel_hi:[0,1,1]
	v_pk_fma_f32 v[2:3], v[250:251], v[234:235], v[2:3] op_sel:[1,0,0] op_sel_hi:[1,1,1]
	v_pk_fma_f32 v[26:27], v[248:249], v[234:235], v[26:27] op_sel_hi:[0,1,1]
	v_pk_fma_f32 v[18:19], v[248:249], v[234:235], v[18:19] op_sel:[1,0,0] op_sel_hi:[1,1,1]
	v_pk_fma_f32 v[10:11], v[250:251], v[234:235], v[10:11] op_sel_hi:[0,1,1]
	v_pk_fma_f32 v[0:1], v[250:251], v[236:237], v[0:1] op_sel:[1,0,0] op_sel_hi:[1,1,1]
	v_pk_fma_f32 v[24:25], v[248:249], v[236:237], v[24:25] op_sel_hi:[0,1,1]
	v_pk_fma_f32 v[14:15], v[248:249], v[236:237], v[14:15] op_sel:[1,0,0] op_sel_hi:[1,1,1]
	v_pk_fma_f32 v[6:7], v[250:251], v[236:237], v[6:7] op_sel_hi:[0,1,1]
	ds_read_b128 v[248:251], v112 offset:46848
	s_waitcnt vmcnt(8)
	v_lshlrev_b32_e32 v108, 16, v238
	v_and_b32_e32 v109, 0xffff0000, v238
	v_lshlrev_b32_e32 v246, 16, v239
	v_and_b32_e32 v247, 0xffff0000, v239
	v_lshlrev_b32_e32 v238, 16, v240
	v_and_b32_e32 v239, 0xffff0000, v240
	v_lshlrev_b32_e32 v240, 16, v241
	v_and_b32_e32 v241, 0xffff0000, v241
	s_waitcnt lgkmcnt(1)
	v_pk_fma_f32 v[8:9], v[254:255], v[108:109], v[8:9] op_sel:[1,0,0] op_sel_hi:[1,1,1]
	v_pk_fma_f32 v[32:33], v[252:253], v[108:109], v[32:33] op_sel_hi:[0,1,1]
	v_pk_fma_f32 v[22:23], v[252:253], v[108:109], v[22:23] op_sel:[1,0,0] op_sel_hi:[1,1,1]
	v_pk_fma_f32 v[16:17], v[254:255], v[108:109], v[16:17] op_sel_hi:[0,1,1]
	v_pk_fma_f32 v[4:5], v[254:255], v[246:247], v[4:5] op_sel:[1,0,0] op_sel_hi:[1,1,1]
	v_pk_fma_f32 v[30:31], v[252:253], v[246:247], v[30:31] op_sel_hi:[0,1,1]
	v_pk_fma_f32 v[20:21], v[252:253], v[246:247], v[20:21] op_sel:[1,0,0] op_sel_hi:[1,1,1]
	v_pk_fma_f32 v[12:13], v[254:255], v[246:247], v[12:13] op_sel_hi:[0,1,1]
	v_pk_fma_f32 v[2:3], v[254:255], v[238:239], v[2:3] op_sel:[1,0,0] op_sel_hi:[1,1,1]
	v_pk_fma_f32 v[26:27], v[252:253], v[238:239], v[26:27] op_sel_hi:[0,1,1]
	v_pk_fma_f32 v[18:19], v[252:253], v[238:239], v[18:19] op_sel:[1,0,0] op_sel_hi:[1,1,1]
	v_pk_fma_f32 v[10:11], v[254:255], v[238:239], v[10:11] op_sel_hi:[0,1,1]
	v_pk_fma_f32 v[0:1], v[254:255], v[240:241], v[0:1] op_sel:[1,0,0] op_sel_hi:[1,1,1]
	v_pk_fma_f32 v[24:25], v[252:253], v[240:241], v[24:25] op_sel_hi:[0,1,1]
	v_pk_fma_f32 v[14:15], v[252:253], v[240:241], v[14:15] op_sel:[1,0,0] op_sel_hi:[1,1,1]
	v_pk_fma_f32 v[6:7], v[254:255], v[240:241], v[6:7] op_sel_hi:[0,1,1]
	ds_read_b128 v[252:255], v112 offset:46912
	s_waitcnt vmcnt(7)
	v_lshlrev_b32_e32 v108, 16, v70
	v_and_b32_e32 v109, 0xffff0000, v70
	v_lshlrev_b32_e32 v246, 16, v71
	v_and_b32_e32 v247, 0xffff0000, v71
	v_lshlrev_b32_e32 v70, 16, v72
	v_and_b32_e32 v71, 0xffff0000, v72
	v_lshlrev_b32_e32 v72, 16, v73
	v_and_b32_e32 v73, 0xffff0000, v73
	s_waitcnt lgkmcnt(1)
	v_pk_fma_f32 v[8:9], v[250:251], v[108:109], v[8:9] op_sel:[1,0,0] op_sel_hi:[1,1,1]
	v_pk_fma_f32 v[32:33], v[248:249], v[108:109], v[32:33] op_sel_hi:[0,1,1]
	v_pk_fma_f32 v[22:23], v[248:249], v[108:109], v[22:23] op_sel:[1,0,0] op_sel_hi:[1,1,1]
	v_pk_fma_f32 v[16:17], v[250:251], v[108:109], v[16:17] op_sel_hi:[0,1,1]
	v_pk_fma_f32 v[4:5], v[250:251], v[246:247], v[4:5] op_sel:[1,0,0] op_sel_hi:[1,1,1]
	v_pk_fma_f32 v[30:31], v[248:249], v[246:247], v[30:31] op_sel_hi:[0,1,1]
	v_pk_fma_f32 v[20:21], v[248:249], v[246:247], v[20:21] op_sel:[1,0,0] op_sel_hi:[1,1,1]
	v_pk_fma_f32 v[12:13], v[250:251], v[246:247], v[12:13] op_sel_hi:[0,1,1]
	v_pk_fma_f32 v[2:3], v[250:251], v[70:71], v[2:3] op_sel:[1,0,0] op_sel_hi:[1,1,1]
	v_pk_fma_f32 v[26:27], v[248:249], v[70:71], v[26:27] op_sel_hi:[0,1,1]
	v_pk_fma_f32 v[18:19], v[248:249], v[70:71], v[18:19] op_sel:[1,0,0] op_sel_hi:[1,1,1]
	v_pk_fma_f32 v[10:11], v[250:251], v[70:71], v[10:11] op_sel_hi:[0,1,1]
	v_pk_fma_f32 v[0:1], v[250:251], v[72:73], v[0:1] op_sel:[1,0,0] op_sel_hi:[1,1,1]
	v_pk_fma_f32 v[24:25], v[248:249], v[72:73], v[24:25] op_sel_hi:[0,1,1]
	v_pk_fma_f32 v[14:15], v[248:249], v[72:73], v[14:15] op_sel:[1,0,0] op_sel_hi:[1,1,1]
	v_pk_fma_f32 v[6:7], v[250:251], v[72:73], v[6:7] op_sel_hi:[0,1,1]
	ds_read_b128 v[248:251], v112 offset:46976
	s_waitcnt vmcnt(6)
	v_lshlrev_b32_e32 v108, 16, v74
	v_and_b32_e32 v109, 0xffff0000, v74
	v_lshlrev_b32_e32 v246, 16, v75
	v_and_b32_e32 v247, 0xffff0000, v75
	v_lshlrev_b32_e32 v74, 16, v76
	v_and_b32_e32 v75, 0xffff0000, v76
	v_lshlrev_b32_e32 v76, 16, v77
	v_and_b32_e32 v77, 0xffff0000, v77
	s_waitcnt lgkmcnt(1)
	v_pk_fma_f32 v[8:9], v[254:255], v[108:109], v[8:9] op_sel:[1,0,0] op_sel_hi:[1,1,1]
	v_pk_fma_f32 v[32:33], v[252:253], v[108:109], v[32:33] op_sel_hi:[0,1,1]
	v_pk_fma_f32 v[22:23], v[252:253], v[108:109], v[22:23] op_sel:[1,0,0] op_sel_hi:[1,1,1]
	v_pk_fma_f32 v[16:17], v[254:255], v[108:109], v[16:17] op_sel_hi:[0,1,1]
	v_pk_fma_f32 v[4:5], v[254:255], v[246:247], v[4:5] op_sel:[1,0,0] op_sel_hi:[1,1,1]
	v_pk_fma_f32 v[30:31], v[252:253], v[246:247], v[30:31] op_sel_hi:[0,1,1]
	v_pk_fma_f32 v[20:21], v[252:253], v[246:247], v[20:21] op_sel:[1,0,0] op_sel_hi:[1,1,1]
	v_pk_fma_f32 v[12:13], v[254:255], v[246:247], v[12:13] op_sel_hi:[0,1,1]
	v_pk_fma_f32 v[2:3], v[254:255], v[74:75], v[2:3] op_sel:[1,0,0] op_sel_hi:[1,1,1]
	v_pk_fma_f32 v[26:27], v[252:253], v[74:75], v[26:27] op_sel_hi:[0,1,1]
	v_pk_fma_f32 v[18:19], v[252:253], v[74:75], v[18:19] op_sel:[1,0,0] op_sel_hi:[1,1,1]
	v_pk_fma_f32 v[10:11], v[254:255], v[74:75], v[10:11] op_sel_hi:[0,1,1]
	v_pk_fma_f32 v[0:1], v[254:255], v[76:77], v[0:1] op_sel:[1,0,0] op_sel_hi:[1,1,1]
	v_pk_fma_f32 v[24:25], v[252:253], v[76:77], v[24:25] op_sel_hi:[0,1,1]
	v_pk_fma_f32 v[14:15], v[252:253], v[76:77], v[14:15] op_sel:[1,0,0] op_sel_hi:[1,1,1]
	v_pk_fma_f32 v[6:7], v[254:255], v[76:77], v[6:7] op_sel_hi:[0,1,1]
	ds_read_b128 v[252:255], v112 offset:47040
	s_waitcnt vmcnt(5)
	v_lshlrev_b32_e32 v108, 16, v78
	v_and_b32_e32 v109, 0xffff0000, v78
	v_lshlrev_b32_e32 v246, 16, v79
	v_and_b32_e32 v247, 0xffff0000, v79
	v_lshlrev_b32_e32 v78, 16, v80
	v_and_b32_e32 v79, 0xffff0000, v80
	v_lshlrev_b32_e32 v80, 16, v81
	v_and_b32_e32 v81, 0xffff0000, v81
	s_waitcnt lgkmcnt(1)
	v_pk_fma_f32 v[8:9], v[250:251], v[108:109], v[8:9] op_sel:[1,0,0] op_sel_hi:[1,1,1]
	v_pk_fma_f32 v[32:33], v[248:249], v[108:109], v[32:33] op_sel_hi:[0,1,1]
	v_pk_fma_f32 v[22:23], v[248:249], v[108:109], v[22:23] op_sel:[1,0,0] op_sel_hi:[1,1,1]
	v_pk_fma_f32 v[16:17], v[250:251], v[108:109], v[16:17] op_sel_hi:[0,1,1]
	v_pk_fma_f32 v[4:5], v[250:251], v[246:247], v[4:5] op_sel:[1,0,0] op_sel_hi:[1,1,1]
	v_pk_fma_f32 v[30:31], v[248:249], v[246:247], v[30:31] op_sel_hi:[0,1,1]
	v_pk_fma_f32 v[20:21], v[248:249], v[246:247], v[20:21] op_sel:[1,0,0] op_sel_hi:[1,1,1]
	v_pk_fma_f32 v[12:13], v[250:251], v[246:247], v[12:13] op_sel_hi:[0,1,1]
	v_pk_fma_f32 v[2:3], v[250:251], v[78:79], v[2:3] op_sel:[1,0,0] op_sel_hi:[1,1,1]
	v_pk_fma_f32 v[26:27], v[248:249], v[78:79], v[26:27] op_sel_hi:[0,1,1]
	v_pk_fma_f32 v[18:19], v[248:249], v[78:79], v[18:19] op_sel:[1,0,0] op_sel_hi:[1,1,1]
	v_pk_fma_f32 v[10:11], v[250:251], v[78:79], v[10:11] op_sel_hi:[0,1,1]
	v_pk_fma_f32 v[0:1], v[250:251], v[80:81], v[0:1] op_sel:[1,0,0] op_sel_hi:[1,1,1]
	v_pk_fma_f32 v[24:25], v[248:249], v[80:81], v[24:25] op_sel_hi:[0,1,1]
	v_pk_fma_f32 v[14:15], v[248:249], v[80:81], v[14:15] op_sel:[1,0,0] op_sel_hi:[1,1,1]
	v_pk_fma_f32 v[6:7], v[250:251], v[80:81], v[6:7] op_sel_hi:[0,1,1]
	ds_read_b128 v[248:251], v112 offset:47104
	s_waitcnt vmcnt(4)
	v_lshlrev_b32_e32 v108, 16, v82
	v_and_b32_e32 v109, 0xffff0000, v82
	v_lshlrev_b32_e32 v246, 16, v83
	v_and_b32_e32 v247, 0xffff0000, v83
	v_lshlrev_b32_e32 v82, 16, v84
	v_and_b32_e32 v83, 0xffff0000, v84
	v_lshlrev_b32_e32 v84, 16, v85
	v_and_b32_e32 v85, 0xffff0000, v85
	s_waitcnt lgkmcnt(1)
	v_pk_fma_f32 v[8:9], v[254:255], v[108:109], v[8:9] op_sel:[1,0,0] op_sel_hi:[1,1,1]
	v_pk_fma_f32 v[32:33], v[252:253], v[108:109], v[32:33] op_sel_hi:[0,1,1]
	v_pk_fma_f32 v[22:23], v[252:253], v[108:109], v[22:23] op_sel:[1,0,0] op_sel_hi:[1,1,1]
	v_pk_fma_f32 v[16:17], v[254:255], v[108:109], v[16:17] op_sel_hi:[0,1,1]
	v_pk_fma_f32 v[4:5], v[254:255], v[246:247], v[4:5] op_sel:[1,0,0] op_sel_hi:[1,1,1]
	v_pk_fma_f32 v[30:31], v[252:253], v[246:247], v[30:31] op_sel_hi:[0,1,1]
	v_pk_fma_f32 v[20:21], v[252:253], v[246:247], v[20:21] op_sel:[1,0,0] op_sel_hi:[1,1,1]
	v_pk_fma_f32 v[12:13], v[254:255], v[246:247], v[12:13] op_sel_hi:[0,1,1]
	v_pk_fma_f32 v[2:3], v[254:255], v[82:83], v[2:3] op_sel:[1,0,0] op_sel_hi:[1,1,1]
	v_pk_fma_f32 v[26:27], v[252:253], v[82:83], v[26:27] op_sel_hi:[0,1,1]
	v_pk_fma_f32 v[18:19], v[252:253], v[82:83], v[18:19] op_sel:[1,0,0] op_sel_hi:[1,1,1]
	v_pk_fma_f32 v[10:11], v[254:255], v[82:83], v[10:11] op_sel_hi:[0,1,1]
	v_pk_fma_f32 v[0:1], v[254:255], v[84:85], v[0:1] op_sel:[1,0,0] op_sel_hi:[1,1,1]
	v_pk_fma_f32 v[24:25], v[252:253], v[84:85], v[24:25] op_sel_hi:[0,1,1]
	v_pk_fma_f32 v[14:15], v[252:253], v[84:85], v[14:15] op_sel:[1,0,0] op_sel_hi:[1,1,1]
	v_pk_fma_f32 v[6:7], v[254:255], v[84:85], v[6:7] op_sel_hi:[0,1,1]
	ds_read_b128 v[252:255], v112 offset:47168
	s_waitcnt vmcnt(3)
	v_lshlrev_b32_e32 v108, 16, v90
	v_and_b32_e32 v109, 0xffff0000, v90
	v_lshlrev_b32_e32 v246, 16, v91
	v_and_b32_e32 v247, 0xffff0000, v91
	v_lshlrev_b32_e32 v90, 16, v92
	v_and_b32_e32 v91, 0xffff0000, v92
	v_lshlrev_b32_e32 v92, 16, v93
	v_and_b32_e32 v93, 0xffff0000, v93
	s_waitcnt lgkmcnt(1)
	v_pk_fma_f32 v[8:9], v[250:251], v[108:109], v[8:9] op_sel:[1,0,0] op_sel_hi:[1,1,1]
	v_pk_fma_f32 v[32:33], v[248:249], v[108:109], v[32:33] op_sel_hi:[0,1,1]
	v_pk_fma_f32 v[22:23], v[248:249], v[108:109], v[22:23] op_sel:[1,0,0] op_sel_hi:[1,1,1]
	v_pk_fma_f32 v[16:17], v[250:251], v[108:109], v[16:17] op_sel_hi:[0,1,1]
	v_pk_fma_f32 v[4:5], v[250:251], v[246:247], v[4:5] op_sel:[1,0,0] op_sel_hi:[1,1,1]
	v_pk_fma_f32 v[30:31], v[248:249], v[246:247], v[30:31] op_sel_hi:[0,1,1]
	v_pk_fma_f32 v[20:21], v[248:249], v[246:247], v[20:21] op_sel:[1,0,0] op_sel_hi:[1,1,1]
	v_pk_fma_f32 v[12:13], v[250:251], v[246:247], v[12:13] op_sel_hi:[0,1,1]
	v_pk_fma_f32 v[2:3], v[250:251], v[90:91], v[2:3] op_sel:[1,0,0] op_sel_hi:[1,1,1]
	v_pk_fma_f32 v[26:27], v[248:249], v[90:91], v[26:27] op_sel_hi:[0,1,1]
	v_pk_fma_f32 v[18:19], v[248:249], v[90:91], v[18:19] op_sel:[1,0,0] op_sel_hi:[1,1,1]
	v_pk_fma_f32 v[10:11], v[250:251], v[90:91], v[10:11] op_sel_hi:[0,1,1]
	v_pk_fma_f32 v[0:1], v[250:251], v[92:93], v[0:1] op_sel:[1,0,0] op_sel_hi:[1,1,1]
	v_pk_fma_f32 v[24:25], v[248:249], v[92:93], v[24:25] op_sel_hi:[0,1,1]
	v_pk_fma_f32 v[14:15], v[248:249], v[92:93], v[14:15] op_sel:[1,0,0] op_sel_hi:[1,1,1]
	v_pk_fma_f32 v[6:7], v[250:251], v[92:93], v[6:7] op_sel_hi:[0,1,1]
	ds_read_b128 v[248:251], v112 offset:47232
	s_waitcnt vmcnt(2)
	v_lshlrev_b32_e32 v108, 16, v94
	v_and_b32_e32 v109, 0xffff0000, v94
	v_lshlrev_b32_e32 v246, 16, v95
	v_and_b32_e32 v247, 0xffff0000, v95
	v_lshlrev_b32_e32 v94, 16, v96
	v_and_b32_e32 v95, 0xffff0000, v96
	v_lshlrev_b32_e32 v96, 16, v97
	v_and_b32_e32 v97, 0xffff0000, v97
	s_waitcnt lgkmcnt(1)
	v_pk_fma_f32 v[8:9], v[254:255], v[108:109], v[8:9] op_sel:[1,0,0] op_sel_hi:[1,1,1]
	v_pk_fma_f32 v[32:33], v[252:253], v[108:109], v[32:33] op_sel_hi:[0,1,1]
	v_pk_fma_f32 v[22:23], v[252:253], v[108:109], v[22:23] op_sel:[1,0,0] op_sel_hi:[1,1,1]
	v_pk_fma_f32 v[16:17], v[254:255], v[108:109], v[16:17] op_sel_hi:[0,1,1]
	v_pk_fma_f32 v[4:5], v[254:255], v[246:247], v[4:5] op_sel:[1,0,0] op_sel_hi:[1,1,1]
	v_pk_fma_f32 v[30:31], v[252:253], v[246:247], v[30:31] op_sel_hi:[0,1,1]
	v_pk_fma_f32 v[20:21], v[252:253], v[246:247], v[20:21] op_sel:[1,0,0] op_sel_hi:[1,1,1]
	v_pk_fma_f32 v[12:13], v[254:255], v[246:247], v[12:13] op_sel_hi:[0,1,1]
	v_pk_fma_f32 v[2:3], v[254:255], v[94:95], v[2:3] op_sel:[1,0,0] op_sel_hi:[1,1,1]
	v_pk_fma_f32 v[26:27], v[252:253], v[94:95], v[26:27] op_sel_hi:[0,1,1]
	v_pk_fma_f32 v[18:19], v[252:253], v[94:95], v[18:19] op_sel:[1,0,0] op_sel_hi:[1,1,1]
	v_pk_fma_f32 v[10:11], v[254:255], v[94:95], v[10:11] op_sel_hi:[0,1,1]
	v_pk_fma_f32 v[0:1], v[254:255], v[96:97], v[0:1] op_sel:[1,0,0] op_sel_hi:[1,1,1]
	v_pk_fma_f32 v[24:25], v[252:253], v[96:97], v[24:25] op_sel_hi:[0,1,1]
	v_pk_fma_f32 v[14:15], v[252:253], v[96:97], v[14:15] op_sel:[1,0,0] op_sel_hi:[1,1,1]
	v_pk_fma_f32 v[6:7], v[254:255], v[96:97], v[6:7] op_sel_hi:[0,1,1]
	ds_read_b128 v[252:255], v112 offset:47296
	s_waitcnt vmcnt(1)
	v_lshlrev_b32_e32 v108, 16, v196
	v_and_b32_e32 v109, 0xffff0000, v196
	v_lshlrev_b32_e32 v246, 16, v197
	v_and_b32_e32 v247, 0xffff0000, v197
	v_lshlrev_b32_e32 v196, 16, v198
	v_and_b32_e32 v197, 0xffff0000, v198
	v_lshlrev_b32_e32 v198, 16, v199
	v_and_b32_e32 v199, 0xffff0000, v199
	s_waitcnt lgkmcnt(1)
	v_pk_fma_f32 v[8:9], v[250:251], v[108:109], v[8:9] op_sel:[1,0,0] op_sel_hi:[1,1,1]
	v_pk_fma_f32 v[32:33], v[248:249], v[108:109], v[32:33] op_sel_hi:[0,1,1]
	v_pk_fma_f32 v[22:23], v[248:249], v[108:109], v[22:23] op_sel:[1,0,0] op_sel_hi:[1,1,1]
	v_pk_fma_f32 v[16:17], v[250:251], v[108:109], v[16:17] op_sel_hi:[0,1,1]
	v_pk_fma_f32 v[4:5], v[250:251], v[246:247], v[4:5] op_sel:[1,0,0] op_sel_hi:[1,1,1]
	v_pk_fma_f32 v[30:31], v[248:249], v[246:247], v[30:31] op_sel_hi:[0,1,1]
	v_pk_fma_f32 v[20:21], v[248:249], v[246:247], v[20:21] op_sel:[1,0,0] op_sel_hi:[1,1,1]
	v_pk_fma_f32 v[12:13], v[250:251], v[246:247], v[12:13] op_sel_hi:[0,1,1]
	v_pk_fma_f32 v[2:3], v[250:251], v[196:197], v[2:3] op_sel:[1,0,0] op_sel_hi:[1,1,1]
	v_pk_fma_f32 v[26:27], v[248:249], v[196:197], v[26:27] op_sel_hi:[0,1,1]
	v_pk_fma_f32 v[18:19], v[248:249], v[196:197], v[18:19] op_sel:[1,0,0] op_sel_hi:[1,1,1]
	v_pk_fma_f32 v[10:11], v[250:251], v[196:197], v[10:11] op_sel_hi:[0,1,1]
	v_pk_fma_f32 v[0:1], v[250:251], v[198:199], v[0:1] op_sel:[1,0,0] op_sel_hi:[1,1,1]
	v_pk_fma_f32 v[24:25], v[248:249], v[198:199], v[24:25] op_sel_hi:[0,1,1]
	v_pk_fma_f32 v[14:15], v[248:249], v[198:199], v[14:15] op_sel:[1,0,0] op_sel_hi:[1,1,1]
	v_pk_fma_f32 v[6:7], v[250:251], v[198:199], v[6:7] op_sel_hi:[0,1,1]
	s_waitcnt vmcnt(0)
	v_lshlrev_b32_e32 v108, 16, v200
	v_and_b32_e32 v109, 0xffff0000, v200
	v_lshlrev_b32_e32 v246, 16, v201
	v_and_b32_e32 v247, 0xffff0000, v201
	v_lshlrev_b32_e32 v200, 16, v202
	v_and_b32_e32 v201, 0xffff0000, v202
	v_lshlrev_b32_e32 v202, 16, v203
	v_and_b32_e32 v203, 0xffff0000, v203
	s_waitcnt lgkmcnt(0)
	v_pk_fma_f32 v[8:9], v[254:255], v[108:109], v[8:9] op_sel:[1,0,0] op_sel_hi:[1,1,1]
	v_pk_fma_f32 v[32:33], v[252:253], v[108:109], v[32:33] op_sel_hi:[0,1,1]
	v_pk_fma_f32 v[22:23], v[252:253], v[108:109], v[22:23] op_sel:[1,0,0] op_sel_hi:[1,1,1]
	v_pk_fma_f32 v[16:17], v[254:255], v[108:109], v[16:17] op_sel_hi:[0,1,1]
	v_pk_fma_f32 v[4:5], v[254:255], v[246:247], v[4:5] op_sel:[1,0,0] op_sel_hi:[1,1,1]
	v_pk_fma_f32 v[30:31], v[252:253], v[246:247], v[30:31] op_sel_hi:[0,1,1]
	v_pk_fma_f32 v[20:21], v[252:253], v[246:247], v[20:21] op_sel:[1,0,0] op_sel_hi:[1,1,1]
	v_pk_fma_f32 v[12:13], v[254:255], v[246:247], v[12:13] op_sel_hi:[0,1,1]
	v_pk_fma_f32 v[2:3], v[254:255], v[200:201], v[2:3] op_sel:[1,0,0] op_sel_hi:[1,1,1]
	v_pk_fma_f32 v[26:27], v[252:253], v[200:201], v[26:27] op_sel_hi:[0,1,1]
	v_pk_fma_f32 v[18:19], v[252:253], v[200:201], v[18:19] op_sel:[1,0,0] op_sel_hi:[1,1,1]
	v_pk_fma_f32 v[10:11], v[254:255], v[200:201], v[10:11] op_sel_hi:[0,1,1]
	v_pk_fma_f32 v[0:1], v[254:255], v[202:203], v[0:1] op_sel:[1,0,0] op_sel_hi:[1,1,1]
	v_pk_fma_f32 v[24:25], v[252:253], v[202:203], v[24:25] op_sel_hi:[0,1,1]
	v_pk_fma_f32 v[14:15], v[252:253], v[202:203], v[14:15] op_sel:[1,0,0] op_sel_hi:[1,1,1]
	v_pk_fma_f32 v[6:7], v[254:255], v[202:203], v[6:7] op_sel_hi:[0,1,1]
	s_branch .LBB0_1536
